# GEMM hot loops without the per-phase s_setprio flips and without the compiler's duplicate lgkmcnt(0)
# speedup vs baseline: 1.0082x; 1.0005x over previous
; #define PG8_STAGE(bufoff, gbase, voff) do { _Pragma("unroll") for (int _i = 0; _i < 2; ++_i) \
;         __builtin_amdgcn_global_load_lds((const unsigned*)((const char*)(gbase) + (voff)[_i]), (PG8_LAS unsigned*)(lds + (bufoff) + ldsw + _i * 8192), 16, 0, 0); } while (0)
; #define PG8_LDA(dst, b, h) do { _Pragma("unroll") for (int m = 0; m < 4; ++m) _Pragma("unroll") for (int k = 0; k < 2; ++k) dst[m][k] = *(const PG8_LAS bf16x8*)(lds + PG8_SA(b, h) + aoff + m * 2048 + k * 1024); } while (0)
; #define PG8_LDB(dst, b, h) do { _Pragma("unroll") for (int n = 0; n < 2; ++n) _Pragma("unroll") for (int k = 0; k < 2; ++k) dst[n][k] = *(const PG8_LAS bf16x8*)(lds + PG8_SB(b, h) + boff + n * 2048 + k * 1024); } while (0)
; #define PG8_MMA(ai, bj, At, Bt) do { __builtin_amdgcn_s_setprio(1); _Pragma("unroll") for (int m = 0; m < 4; ++m) _Pragma("unroll") for (int n = 0; n < 2; ++n) _Pragma("unroll") for (int k = 0; k < 2; ++k) \
;         acc[ai][bj][m][n] = __builtin_amdgcn_mfma_f32_16x16x32_bf16(Bt[n][k], At[m][k], acc[ai][bj][m][n], 0, 0, 0); __builtin_amdgcn_s_setprio(0); } while (0)
; #define PG8_WAIT_L(n) asm volatile("s_waitcnt lgkmcnt(" #n ")" ::: "memory")
; #define PG8_BAR __builtin_amdgcn_s_barrier()
; #define PG8_SCHED __builtin_amdgcn_sched_barrier(0)
; template <class Epi, class Sched>
; __device__ __forceinline__ void gemm_phase(PG8_LAS unsigned char* lds, const Gemm g, const Sched& S, const Epi& E) {
;     ...
;         for (int t = 0; t < nt; t += 2) {
;             const bool last = (t == nt - 2);
;             const char* a1 = cA + (size_t)(t + 1) * kstep;
;             const char* a2 = last ? nA : cA + (size_t)(t + 2) * kstep; const char* b2 = last ? nB : cB + (size_t)(t + 2) * kstep;
;             const char* a3 = a2 + kstep; const char* b3 = b2 + kstep;
;             if (last && has_next) S.a_ready(nxt);
;             PG8_LDB(B0, 0, 0); PG8_SCHED; PG8_LDA(At, 0, 0); PG8_STAGE(PG8_SA(1, 1), a1 + hstep, voffA);
;             PG8_WAIT_L(8); PG8_BAR; PG8_WAIT_L(0); PG8_MMA(0, 0, At, B0); PG8_BAR; PG8_SCHED;
;             PG8_LDB(B1, 0, 1); PG8_STAGE(PG8_SB(0, 0), b2, voffB);
;             PG8_BAR; PG8_WAIT_L(0); PG8_MMA(0, 1, At, B1); PG8_BAR;
;             PG8_LDA(At, 0, 1); PG8_STAGE(PG8_SA(0, 0), a2, voffA);
;             PG8_BAR; PG8_WAIT_L(0); PG8_MMA(1, 0, At, B0); PG8_BAR; PG8_SCHED;
.LBB0_114:
	s_add_u32 s20, s18, 0xfffc0080
	s_addc_u32 s21, s19, -1
	s_add_i32 s60, s46, 0x100
	v_add_u32_e32 v166, s60, v155
	ds_read_b128 v[150:153], v166
	ds_read_b128 v[158:161], v166 offset:1024
	ds_read_b128 v[162:165], v166 offset:2048
	ds_read_b128 v[166:169], v166 offset:3072
	s_cmp_eq_u32 s59, 12
	s_cselect_b32 s23, s1, s21
	s_cselect_b32 s22, s9, s20
	s_cselect_b32 s21, s7, s41
	s_cselect_b32 s20, s17, s40
	v_lshl_add_u64 v[186:187], s[18:19], 0, v[134:135]
	s_add_i32 m0, s31, 0xc000
	ds_read_b128 v[170:173], v157
	ds_read_b128 v[174:177], v157 offset:1024
	ds_read_b128 v[178:181], v157 offset:2048
	ds_read_b128 v[182:185], v157 offset:3072
	ds_read_b128 v[210:213], v157 offset:4096
	ds_read_b128 v[214:217], v157 offset:5120
	ds_read_b128 v[218:221], v157 offset:6144
	ds_read_b128 v[222:225], v157 offset:7168
	global_load_lds_dwordx4 v[186:187], off
	v_lshl_add_u64 v[186:187], s[18:19], 0, v[148:149]
	s_add_i32 m0, s31, 0xe000
	s_nop 0
	global_load_lds_dwordx4 v[186:187], off
	s_waitcnt lgkmcnt(8)
	s_barrier
	s_waitcnt lgkmcnt(0)
	v_mfma_f32_16x16x32_bf16 v[124:127], v[150:153], v[170:173], v[124:127]
	v_mfma_f32_16x16x32_bf16 v[120:123], v[162:165], v[170:173], v[120:123]
	v_mfma_f32_16x16x32_bf16 v[112:115], v[150:153], v[178:181], v[112:115]
	v_mfma_f32_16x16x32_bf16 v[104:107], v[162:165], v[178:181], v[104:107]
	v_mfma_f32_16x16x32_bf16 v[96:99], v[150:153], v[210:213], v[96:99]
	v_mfma_f32_16x16x32_bf16 v[88:91], v[162:165], v[210:213], v[88:91]
	v_mfma_f32_16x16x32_bf16 v[80:83], v[150:153], v[218:221], v[80:83]
	v_mfma_f32_16x16x32_bf16 v[72:75], v[162:165], v[218:221], v[72:75]
	v_mfma_f32_16x16x32_bf16 v[124:127], v[158:161], v[174:177], v[124:127]
	v_mfma_f32_16x16x32_bf16 v[120:123], v[166:169], v[174:177], v[120:123]
	v_mfma_f32_16x16x32_bf16 v[112:115], v[158:161], v[182:185], v[112:115]
	v_mfma_f32_16x16x32_bf16 v[104:107], v[166:169], v[182:185], v[104:107]
	v_mfma_f32_16x16x32_bf16 v[96:99], v[158:161], v[214:217], v[96:99]
	v_mfma_f32_16x16x32_bf16 v[88:91], v[166:169], v[214:217], v[88:91]
	v_mfma_f32_16x16x32_bf16 v[80:83], v[158:161], v[222:225], v[80:83]
	v_mfma_f32_16x16x32_bf16 v[72:75], v[166:169], v[222:225], v[72:75]
	s_barrier
	s_add_i32 s62, s48, 0x100
	v_add_u32_e32 v186, s62, v155
	s_add_i32 s60, s60, s30
	ds_read_b128 v[226:229], v186
	ds_read_b128 v[230:233], v186 offset:1024
	ds_read_b128 v[234:237], v186 offset:2048
	ds_read_b128 v[238:241], v186 offset:3072
	v_lshl_add_u64 v[186:187], s[20:21], 0, v[138:139]
	s_mov_b32 m0, s60
	v_lshl_add_u64 v[242:243], s[20:21], 0, v[132:133]
	global_load_lds_dwordx4 v[186:187], off
	s_add_i32 m0, s60, 0x2000
	s_nop 0
	global_load_lds_dwordx4 v[242:243], off
	s_barrier
	s_waitcnt lgkmcnt(0)
	v_mfma_f32_16x16x32_bf16 v[116:119], v[226:229], v[170:173], v[116:119]
	v_mfma_f32_16x16x32_bf16 v[108:111], v[234:237], v[170:173], v[108:111]
	v_mfma_f32_16x16x32_bf16 v[100:103], v[226:229], v[178:181], v[100:103]
	v_mfma_f32_16x16x32_bf16 v[92:95], v[234:237], v[178:181], v[92:95]
	v_mfma_f32_16x16x32_bf16 v[84:87], v[226:229], v[210:213], v[84:87]
	v_mfma_f32_16x16x32_bf16 v[76:79], v[234:237], v[210:213], v[76:79]
	v_mfma_f32_16x16x32_bf16 v[68:71], v[226:229], v[218:221], v[68:71]
	v_mfma_f32_16x16x32_bf16 v[64:67], v[234:237], v[218:221], v[64:67]
	v_mfma_f32_16x16x32_bf16 v[116:119], v[230:233], v[174:177], v[116:119]
	v_mfma_f32_16x16x32_bf16 v[108:111], v[238:241], v[174:177], v[108:111]
	v_mfma_f32_16x16x32_bf16 v[100:103], v[230:233], v[182:185], v[100:103]
	v_mfma_f32_16x16x32_bf16 v[92:95], v[238:241], v[182:185], v[92:95]
	v_mfma_f32_16x16x32_bf16 v[84:87], v[230:233], v[214:217], v[84:87]
	v_mfma_f32_16x16x32_bf16 v[76:79], v[238:241], v[214:217], v[76:79]
	v_mfma_f32_16x16x32_bf16 v[68:71], v[230:233], v[222:225], v[68:71]
	v_mfma_f32_16x16x32_bf16 v[64:67], v[238:241], v[222:225], v[64:67]
	s_mov_b32 m0, s31
	v_lshl_add_u64 v[244:245], s[22:23], 0, v[128:129]
	s_barrier
	ds_read_b128 v[170:173], v157 offset:16384
	ds_read_b128 v[174:177], v157 offset:17408
	ds_read_b128 v[178:181], v157 offset:18432
	ds_read_b128 v[182:185], v157 offset:19456
	ds_read_b128 v[210:213], v157 offset:20480
	ds_read_b128 v[214:217], v157 offset:21504
	ds_read_b128 v[218:221], v157 offset:22528
	ds_read_b128 v[222:225], v157 offset:23552
	global_load_lds_dwordx4 v[244:245], off
	v_lshl_add_u64 v[246:247], s[22:23], 0, v[130:131]
	s_mov_b32 m0, s33
	s_nop 0
	global_load_lds_dwordx4 v[246:247], off
	s_barrier
	s_waitcnt lgkmcnt(0)
	v_mfma_f32_16x16x32_bf16 v[60:63], v[150:153], v[170:173], v[60:63]
	v_mfma_f32_16x16x32_bf16 v[56:59], v[162:165], v[170:173], v[56:59]
	v_mfma_f32_16x16x32_bf16 v[48:51], v[150:153], v[178:181], v[48:51]
	v_mfma_f32_16x16x32_bf16 v[40:43], v[162:165], v[178:181], v[40:43]
	v_mfma_f32_16x16x32_bf16 v[32:35], v[150:153], v[210:213], v[32:35]
	v_mfma_f32_16x16x32_bf16 v[24:27], v[162:165], v[210:213], v[24:27]
	v_mfma_f32_16x16x32_bf16 v[16:19], v[150:153], v[218:221], v[16:19]
	v_mfma_f32_16x16x32_bf16 v[8:11], v[162:165], v[218:221], v[8:11]
	v_mfma_f32_16x16x32_bf16 v[60:63], v[158:161], v[174:177], v[60:63]
	v_mfma_f32_16x16x32_bf16 v[56:59], v[166:169], v[174:177], v[56:59]
	v_mfma_f32_16x16x32_bf16 v[48:51], v[158:161], v[182:185], v[48:51]
	v_mfma_f32_16x16x32_bf16 v[40:43], v[166:169], v[182:185], v[40:43]
	v_mfma_f32_16x16x32_bf16 v[32:35], v[158:161], v[214:217], v[32:35]
	v_mfma_f32_16x16x32_bf16 v[24:27], v[166:169], v[214:217], v[24:27]
	v_mfma_f32_16x16x32_bf16 v[16:19], v[158:161], v[222:225], v[16:19]
	v_mfma_f32_16x16x32_bf16 v[8:11], v[166:169], v[222:225], v[8:11]
	s_barrier
; #define PG8_STAGE(bufoff, gbase, voff) do { _Pragma("unroll") for (int _i = 0; _i < 2; ++_i) \
;         __builtin_amdgcn_global_load_lds((const unsigned*)((const char*)(gbase) + (voff)[_i]), (PG8_LAS unsigned*)(lds + (bufoff) + ldsw + _i * 8192), 16, 0, 0); } while (0)
; #define PG8_LDA(dst, b, h) do { _Pragma("unroll") for (int m = 0; m < 4; ++m) _Pragma("unroll") for (int k = 0; k < 2; ++k) dst[m][k] = *(const PG8_LAS bf16x8*)(lds + PG8_SA(b, h) + aoff + m * 2048 + k * 1024); } while (0)
; #define PG8_LDB(dst, b, h) do { _Pragma("unroll") for (int n = 0; n < 2; ++n) _Pragma("unroll") for (int k = 0; k < 2; ++k) dst[n][k] = *(const PG8_LAS bf16x8*)(lds + PG8_SB(b, h) + boff + n * 2048 + k * 1024); } while (0)
; #define PG8_MMA(ai, bj, At, Bt) do { __builtin_amdgcn_s_setprio(1); _Pragma("unroll") for (int m = 0; m < 4; ++m) _Pragma("unroll") for (int n = 0; n < 2; ++n) _Pragma("unroll") for (int k = 0; k < 2; ++k) \
;         acc[ai][bj][m][n] = __builtin_amdgcn_mfma_f32_16x16x32_bf16(Bt[n][k], At[m][k], acc[ai][bj][m][n], 0, 0, 0); __builtin_amdgcn_s_setprio(0); } while (0)
; #define PG8_WAIT_V(n) asm volatile("s_waitcnt vmcnt(" #n ")" ::: "memory")
; #define PG8_WAIT_L(n) asm volatile("s_waitcnt lgkmcnt(" #n ")" ::: "memory")
; #define PG8_BAR __builtin_amdgcn_s_barrier()
; #define PG8_SCHED __builtin_amdgcn_sched_barrier(0)
; template <class Epi, class Sched>
; __device__ __forceinline__ void gemm_phase(PG8_LAS unsigned char* lds, const Gemm g, const Sched& S, const Epi& E) {
;     ...
;             PG8_STAGE(PG8_SB(0, 1), b2 + hstep, voffB);
;             PG8_WAIT_V(6); PG8_BAR; PG8_MMA(1, 1, At, B1); PG8_BAR;
;             PG8_LDB(B0, 1, 0); PG8_SCHED; PG8_LDA(At, 1, 0); PG8_STAGE(PG8_SA(0, 1), a2 + hstep, voffA);
;             PG8_WAIT_L(8); PG8_BAR; PG8_WAIT_L(0); PG8_MMA(0, 0, At, B0); PG8_BAR; PG8_SCHED;
;             PG8_LDB(B1, 1, 1); PG8_STAGE(PG8_SB(1, 0), b3, voffB);
;             PG8_BAR; PG8_WAIT_L(0); PG8_MMA(0, 1, At, B1); PG8_BAR;
	s_add_u32 s60, s20, 0x40000
	s_addc_u32 s61, s21, 0
	s_add_i32 s62, s62, s30
	v_lshl_add_u64 v[150:151], s[60:61], 0, v[138:139]
	s_mov_b32 m0, s62
	s_nop 0
	global_load_lds_dwordx4 v[150:151], off
	v_lshl_add_u64 v[150:151], s[60:61], 0, v[132:133]
	s_add_i32 m0, s62, 0x2000
	s_nop 0
	global_load_lds_dwordx4 v[150:151], off
	s_waitcnt vmcnt(6)
	s_barrier
	v_mfma_f32_16x16x32_bf16 v[52:55], v[226:229], v[170:173], v[52:55]
	v_mfma_f32_16x16x32_bf16 v[44:47], v[234:237], v[170:173], v[44:47]
	v_mfma_f32_16x16x32_bf16 v[36:39], v[226:229], v[178:181], v[36:39]
	v_mfma_f32_16x16x32_bf16 v[28:31], v[234:237], v[178:181], v[28:31]
	v_mfma_f32_16x16x32_bf16 v[20:23], v[226:229], v[210:213], v[20:23]
	v_mfma_f32_16x16x32_bf16 v[12:15], v[234:237], v[210:213], v[12:15]
	v_mfma_f32_16x16x32_bf16 v[4:7], v[226:229], v[218:221], v[4:7]
	v_mfma_f32_16x16x32_bf16 v[0:3], v[234:237], v[218:221], v[0:3]
	v_mfma_f32_16x16x32_bf16 v[52:55], v[230:233], v[174:177], v[52:55]
	v_mfma_f32_16x16x32_bf16 v[44:47], v[238:241], v[174:177], v[44:47]
	v_mfma_f32_16x16x32_bf16 v[36:39], v[230:233], v[182:185], v[36:39]
	v_mfma_f32_16x16x32_bf16 v[28:31], v[238:241], v[182:185], v[28:31]
	v_mfma_f32_16x16x32_bf16 v[20:23], v[230:233], v[214:217], v[20:23]
	v_mfma_f32_16x16x32_bf16 v[12:15], v[238:241], v[214:217], v[12:15]
	v_mfma_f32_16x16x32_bf16 v[4:7], v[230:233], v[222:225], v[4:7]
	v_mfma_f32_16x16x32_bf16 v[0:3], v[238:241], v[222:225], v[0:3]
	s_add_i32 s60, s51, 0x100
	v_add_u32_e32 v166, s60, v155
	s_barrier
	ds_read_b128 v[150:153], v166
	ds_read_b128 v[158:161], v166 offset:1024
	ds_read_b128 v[162:165], v166 offset:2048
	ds_read_b128 v[166:169], v166 offset:3072
	s_add_u32 s22, s22, 0x40000
	s_addc_u32 s23, s23, 0
	s_mov_b32 m0, s34
	v_lshl_add_u64 v[226:227], s[22:23], 0, v[128:129]
	ds_read_b128 v[170:173], v157 offset:32768
	ds_read_b128 v[174:177], v157 offset:33792
	ds_read_b128 v[178:181], v157 offset:34816
	ds_read_b128 v[182:185], v157 offset:35840
	ds_read_b128 v[210:213], v157 offset:36864
	ds_read_b128 v[214:217], v157 offset:37888
	ds_read_b128 v[218:221], v157 offset:38912
	ds_read_b128 v[222:225], v157 offset:39936
	global_load_lds_dwordx4 v[226:227], off
	v_lshl_add_u64 v[226:227], s[22:23], 0, v[130:131]
	s_mov_b32 m0, s35
	s_nop 0
	global_load_lds_dwordx4 v[226:227], off
	s_waitcnt lgkmcnt(8)
	s_barrier
	s_waitcnt lgkmcnt(0)
	v_mfma_f32_16x16x32_bf16 v[124:127], v[150:153], v[170:173], v[124:127]
	v_mfma_f32_16x16x32_bf16 v[120:123], v[162:165], v[170:173], v[120:123]
	v_mfma_f32_16x16x32_bf16 v[112:115], v[150:153], v[178:181], v[112:115]
	v_mfma_f32_16x16x32_bf16 v[104:107], v[162:165], v[178:181], v[104:107]
	v_mfma_f32_16x16x32_bf16 v[96:99], v[150:153], v[210:213], v[96:99]
	v_mfma_f32_16x16x32_bf16 v[88:91], v[162:165], v[210:213], v[88:91]
	v_mfma_f32_16x16x32_bf16 v[80:83], v[150:153], v[218:221], v[80:83]
	v_mfma_f32_16x16x32_bf16 v[72:75], v[162:165], v[218:221], v[72:75]
	v_mfma_f32_16x16x32_bf16 v[124:127], v[158:161], v[174:177], v[124:127]
	v_mfma_f32_16x16x32_bf16 v[120:123], v[166:169], v[174:177], v[120:123]
	v_mfma_f32_16x16x32_bf16 v[112:115], v[158:161], v[182:185], v[112:115]
	v_mfma_f32_16x16x32_bf16 v[104:107], v[166:169], v[182:185], v[104:107]
	v_mfma_f32_16x16x32_bf16 v[96:99], v[158:161], v[214:217], v[96:99]
	v_mfma_f32_16x16x32_bf16 v[88:91], v[166:169], v[214:217], v[88:91]
	v_mfma_f32_16x16x32_bf16 v[80:83], v[158:161], v[222:225], v[80:83]
	v_mfma_f32_16x16x32_bf16 v[72:75], v[166:169], v[222:225], v[72:75]
	s_barrier
	s_add_i32 s22, s55, 0x100
	s_add_i32 s23, s60, s30
	v_add_u32_e32 v209, s22, v155
	v_lshl_add_u64 v[186:187], v[186:187], 0, s[94:95]
	s_mov_b32 m0, s23
	ds_read_b128 v[226:229], v209
	ds_read_b128 v[230:233], v209 offset:1024
	ds_read_b128 v[234:237], v209 offset:2048
	ds_read_b128 v[238:241], v209 offset:3072
	global_load_lds_dwordx4 v[186:187], off
	v_lshl_add_u64 v[186:187], v[242:243], 0, s[94:95]
	s_add_i32 m0, s23, 0x2000
	s_nop 0
	global_load_lds_dwordx4 v[186:187], off
	s_barrier
;   __device__ __forceinline__ bf16* y() const { unsigned o_ = (unsigned)(OFF_y); asm volatile("" : "+s"(o_)); return (bf16*)(ws + o_); }
; __device__ __forceinline__ unsigned pk2(float a, float b) { unsigned r; asm("v_cvt_pk_bf16_f32 %0, %1, %2" : "=v"(r) : "v"(a), "v"(b)); return r; }
; #define PG8_STAGE(bufoff, gbase, voff) do { _Pragma("unroll") for (int _i = 0; _i < 2; ++_i) \
;         __builtin_amdgcn_global_load_lds((const unsigned*)((const char*)(gbase) + (voff)[_i]), (PG8_LAS unsigned*)(lds + (bufoff) + ldsw + _i * 8192), 16, 0, 0); } while (0)
; #define PG8_LDA(dst, b, h) do { _Pragma("unroll") for (int m = 0; m < 4; ++m) _Pragma("unroll") for (int k = 0; k < 2; ++k) dst[m][k] = *(const PG8_LAS bf16x8*)(lds + PG8_SA(b, h) + aoff + m * 2048 + k * 1024); } while (0)
; #define PG8_WAIT_V(n) asm volatile("s_waitcnt vmcnt(" #n ")" ::: "memory")
; #define PG8_WAIT_L(n) asm volatile("s_waitcnt lgkmcnt(" #n ")" ::: "memory")
; #define PG8_BAR __builtin_amdgcn_s_barrier()
; #define PG8_SCHED __builtin_amdgcn_sched_barrier(0)
; template <class Epi, class Sched>
; __device__ __forceinline__ void gemm_phase(PG8_LAS unsigned char* lds, const Gemm g, const Sched& S, const Epi& E) {
;     ...
;             PG8_BAR; PG8_WAIT_L(0); PG8_MMA(0, 1, At, B1); PG8_BAR;
;             PG8_LDA(At, 1, 1); PG8_STAGE(PG8_SA(1, 0), a3, voffA);
;             PG8_BAR; PG8_WAIT_L(0); PG8_MMA(1, 0, At, B0); PG8_BAR; PG8_SCHED;
;             PG8_STAGE(PG8_SB(1, 1), b3 + hstep, voffB);
;             PG8_WAIT_V(6); PG8_BAR; PG8_MMA(1, 1, At, B1); PG8_BAR;
;         }
;   __device__ __forceinline__ void operator()(const f32x4 (&acc)[2][2][4][2], const pg8::Unit& u, int wr, int wc, int fr, int fq) const {
;     const int row0 = u.pm * 256 + wr * 64 + fr, col0 = u.pn * 256 + wc * 32 + 8 * fq;
; #pragma unroll
;     for (int ai = 0; ai < 2; ++ai)
; #pragma unroll
;       for (int m = 0; m < 4; ++m) {
;         bf16* rowp = O + (size_t)(row0 + ai * 128 + m * 16) * US + col0;
; #pragma unroll
;         for (int bj = 0; bj < 2; ++bj) {
;           if (col0 + bj * 128 < US) {
;             uint4 o;
;             o.x = pk2(acc[ai][bj][m][0][0], acc[ai][bj][m][0][1]); o.y = pk2(acc[ai][bj][m][0][2], acc[ai][bj][m][0][3]);
;             o.z = pk2(acc[ai][bj][m][1][0], acc[ai][bj][m][1][1]); o.w = pk2(acc[ai][bj][m][1][2], acc[ai][bj][m][1][3]);
;             *(uint4*)(rowp + bj * 128) = o;
;           }
	s_waitcnt lgkmcnt(0)
	v_mfma_f32_16x16x32_bf16 v[116:119], v[226:229], v[170:173], v[116:119]
	v_mfma_f32_16x16x32_bf16 v[108:111], v[234:237], v[170:173], v[108:111]
	v_mfma_f32_16x16x32_bf16 v[100:103], v[226:229], v[178:181], v[100:103]
	v_mfma_f32_16x16x32_bf16 v[92:95], v[234:237], v[178:181], v[92:95]
	v_mfma_f32_16x16x32_bf16 v[84:87], v[226:229], v[210:213], v[84:87]
	v_mfma_f32_16x16x32_bf16 v[76:79], v[234:237], v[210:213], v[76:79]
	v_mfma_f32_16x16x32_bf16 v[68:71], v[226:229], v[218:221], v[68:71]
	v_mfma_f32_16x16x32_bf16 v[64:67], v[234:237], v[218:221], v[64:67]
	v_mfma_f32_16x16x32_bf16 v[116:119], v[230:233], v[174:177], v[116:119]
	v_mfma_f32_16x16x32_bf16 v[108:111], v[238:241], v[174:177], v[108:111]
	v_mfma_f32_16x16x32_bf16 v[100:103], v[230:233], v[182:185], v[100:103]
	v_mfma_f32_16x16x32_bf16 v[92:95], v[238:241], v[182:185], v[92:95]
	v_mfma_f32_16x16x32_bf16 v[84:87], v[230:233], v[214:217], v[84:87]
	v_mfma_f32_16x16x32_bf16 v[76:79], v[238:241], v[214:217], v[76:79]
	v_mfma_f32_16x16x32_bf16 v[68:71], v[230:233], v[222:225], v[68:71]
	v_mfma_f32_16x16x32_bf16 v[64:67], v[238:241], v[222:225], v[64:67]
	s_mov_b32 m0, s36
	v_lshl_add_u64 v[186:187], v[244:245], 0, s[94:95]
	s_barrier
	ds_read_b128 v[170:173], v157 offset:49152
	ds_read_b128 v[174:177], v157 offset:50176
	ds_read_b128 v[178:181], v157 offset:51200
	ds_read_b128 v[182:185], v157 offset:52224
	ds_read_b128 v[210:213], v157 offset:53248
	ds_read_b128 v[214:217], v157 offset:54272
	ds_read_b128 v[218:221], v157 offset:55296
	ds_read_b128 v[222:225], v157 offset:56320
	global_load_lds_dwordx4 v[186:187], off
	v_lshl_add_u64 v[186:187], v[246:247], 0, s[94:95]
	s_mov_b32 m0, s37
	s_nop 0
	global_load_lds_dwordx4 v[186:187], off
	s_barrier
	s_waitcnt lgkmcnt(0)
	v_mfma_f32_16x16x32_bf16 v[60:63], v[150:153], v[170:173], v[60:63]
	v_mfma_f32_16x16x32_bf16 v[56:59], v[162:165], v[170:173], v[56:59]
	v_mfma_f32_16x16x32_bf16 v[48:51], v[150:153], v[178:181], v[48:51]
	v_mfma_f32_16x16x32_bf16 v[40:43], v[162:165], v[178:181], v[40:43]
	v_mfma_f32_16x16x32_bf16 v[32:35], v[150:153], v[210:213], v[32:35]
	v_mfma_f32_16x16x32_bf16 v[24:27], v[162:165], v[210:213], v[24:27]
	v_mfma_f32_16x16x32_bf16 v[16:19], v[150:153], v[218:221], v[16:19]
	v_mfma_f32_16x16x32_bf16 v[8:11], v[162:165], v[218:221], v[8:11]
	v_mfma_f32_16x16x32_bf16 v[60:63], v[158:161], v[174:177], v[60:63]
	v_mfma_f32_16x16x32_bf16 v[56:59], v[166:169], v[174:177], v[56:59]
	v_mfma_f32_16x16x32_bf16 v[48:51], v[158:161], v[182:185], v[48:51]
	v_mfma_f32_16x16x32_bf16 v[40:43], v[166:169], v[182:185], v[40:43]
	v_mfma_f32_16x16x32_bf16 v[32:35], v[158:161], v[214:217], v[32:35]
	v_mfma_f32_16x16x32_bf16 v[24:27], v[166:169], v[214:217], v[24:27]
	v_mfma_f32_16x16x32_bf16 v[16:19], v[158:161], v[222:225], v[16:19]
	v_mfma_f32_16x16x32_bf16 v[8:11], v[166:169], v[222:225], v[8:11]
	s_barrier
	s_add_u32 s20, s20, 0x40080
	s_addc_u32 s21, s21, 0
	s_add_i32 s22, s22, s30
	v_lshl_add_u64 v[150:151], s[20:21], 0, v[138:139]
	s_mov_b32 m0, s22
	s_nop 0
	global_load_lds_dwordx4 v[150:151], off
	v_lshl_add_u64 v[150:151], s[20:21], 0, v[132:133]
	s_add_i32 m0, s22, 0x2000
	s_nop 0
	global_load_lds_dwordx4 v[150:151], off
	s_waitcnt vmcnt(6)
	s_barrier
	v_mfma_f32_16x16x32_bf16 v[52:55], v[226:229], v[170:173], v[52:55]
	v_mfma_f32_16x16x32_bf16 v[44:47], v[234:237], v[170:173], v[44:47]
	v_mfma_f32_16x16x32_bf16 v[36:39], v[226:229], v[178:181], v[36:39]
	v_mfma_f32_16x16x32_bf16 v[28:31], v[234:237], v[178:181], v[28:31]
	v_mfma_f32_16x16x32_bf16 v[20:23], v[226:229], v[210:213], v[20:23]
	v_mfma_f32_16x16x32_bf16 v[12:15], v[234:237], v[210:213], v[12:15]
	v_mfma_f32_16x16x32_bf16 v[4:7], v[226:229], v[218:221], v[4:7]
	v_mfma_f32_16x16x32_bf16 v[0:3], v[234:237], v[218:221], v[0:3]
	v_mfma_f32_16x16x32_bf16 v[52:55], v[230:233], v[174:177], v[52:55]
	v_mfma_f32_16x16x32_bf16 v[44:47], v[238:241], v[174:177], v[44:47]
	v_mfma_f32_16x16x32_bf16 v[36:39], v[230:233], v[182:185], v[36:39]
	v_mfma_f32_16x16x32_bf16 v[28:31], v[238:241], v[182:185], v[28:31]
	v_mfma_f32_16x16x32_bf16 v[20:23], v[230:233], v[214:217], v[20:23]
	v_mfma_f32_16x16x32_bf16 v[12:15], v[238:241], v[214:217], v[12:15]
	v_mfma_f32_16x16x32_bf16 v[4:7], v[230:233], v[222:225], v[4:7]
	v_mfma_f32_16x16x32_bf16 v[0:3], v[238:241], v[222:225], v[0:3]
	s_add_i32 s59, s59, 2
	s_add_u32 s18, s18, 0x100
	s_addc_u32 s19, s19, 0
	s_add_u32 s40, s40, 0x100
	s_addc_u32 s41, s41, 0
	s_cmp_gt_u32 s59, 13
	s_barrier
	s_cbranch_scc0 .LBB0_114
	v_lshl_add_u32 v158, s16, 8, v154
	v_lshl_or_b32 v150, s0, 8, v156
	v_mov_b64_e32 v[152:153], s[4:5]
	v_ashrrev_i32_e32 v151, 31, v150
	v_mad_i64_i32 v[152:153], s[0:1], v158, s54, v[152:153]
	v_lshl_add_u64 v[152:153], v[150:151], 1, v[152:153]
	v_cmp_gt_i32_e32 vcc, s11, v150
	s_and_saveexec_b64 s[0:1], vcc
	s_cbranch_execz .LBB0_117
	v_cvt_pk_bf16_f32 v124, v124, v125
	v_cvt_pk_bf16_f32 v125, v126, v127
	v_cvt_pk_bf16_f32 v126, v120, v121
	v_cvt_pk_bf16_f32 v127, v122, v123
	global_store_dwordx4 v[152:153], v[124:127], off

; #define PG8_STAGE(bufoff, gbase, voff) do { _Pragma("unroll") for (int _i = 0; _i < 2; ++_i) \
;         __builtin_amdgcn_global_load_lds((const unsigned*)((const char*)(gbase) + (voff)[_i]), (PG8_LAS unsigned*)(lds + (bufoff) + ldsw + _i * 8192), 16, 0, 0); } while (0)
; #define PG8_LDA(dst, b, h) do { _Pragma("unroll") for (int m = 0; m < 4; ++m) _Pragma("unroll") for (int k = 0; k < 2; ++k) dst[m][k] = *(const PG8_LAS bf16x8*)(lds + PG8_SA(b, h) + aoff + m * 2048 + k * 1024); } while (0)
; #define PG8_LDB(dst, b, h) do { _Pragma("unroll") for (int n = 0; n < 2; ++n) _Pragma("unroll") for (int k = 0; k < 2; ++k) dst[n][k] = *(const PG8_LAS bf16x8*)(lds + PG8_SB(b, h) + boff + n * 2048 + k * 1024); } while (0)
; #define PG8_WAIT_V(n) asm volatile("s_waitcnt vmcnt(" #n ")" ::: "memory")
; #define PG8_BAR __builtin_amdgcn_s_barrier()
; template <class Epi, class Sched>
; __device__ __forceinline__ void gemm_phase(PG8_LAS unsigned char* lds, const Gemm g, const Sched& S, const Epi& E) {
;     ...
;         for (int t = 0; t < nt; t += 2) {
;             const bool last = (t == nt - 2);
;             const char* a1 = cA + (size_t)(t + 1) * kstep;
;             const char* a2 = last ? nA : cA + (size_t)(t + 2) * kstep; const char* b2 = last ? nB : cB + (size_t)(t + 2) * kstep;
;             const char* a3 = a2 + kstep; const char* b3 = b2 + kstep;
;             if (last && has_next) S.a_ready(nxt);
;             PG8_LDB(B0, 0, 0); PG8_SCHED; PG8_LDA(At, 0, 0); PG8_STAGE(PG8_SA(1, 1), a1 + hstep, voffA);
;             PG8_WAIT_L(8); PG8_BAR; PG8_WAIT_L(0); PG8_MMA(0, 0, At, B0); PG8_BAR; PG8_SCHED;
;             PG8_LDB(B1, 0, 1); PG8_STAGE(PG8_SB(0, 0), b2, voffB);
;             PG8_BAR; PG8_WAIT_L(0); PG8_MMA(0, 1, At, B1); PG8_BAR;
;             PG8_LDA(At, 0, 1); PG8_STAGE(PG8_SA(0, 0), a2, voffA);
;             PG8_BAR; PG8_WAIT_L(0); PG8_MMA(1, 0, At, B0); PG8_BAR; PG8_SCHED;
;             PG8_STAGE(PG8_SB(0, 1), b2 + hstep, voffB);
;             PG8_WAIT_V(6); PG8_BAR; PG8_MMA(1, 1, At, B1); PG8_BAR;
;             PG8_LDB(B0, 1, 0); PG8_SCHED; PG8_LDA(At, 1, 0); PG8_STAGE(PG8_SA(0, 1), a2 + hstep, voffA);
;             PG8_WAIT_L(8); PG8_BAR; PG8_WAIT_L(0); PG8_MMA(0, 0, At, B0); PG8_BAR; PG8_SCHED;
;             PG8_LDB(B1, 1, 1); PG8_STAGE(PG8_SB(1, 0), b3, voffB);
;             PG8_BAR; PG8_WAIT_L(0); PG8_MMA(0, 1, At, B1); PG8_BAR;
.LBB0_803:
	s_add_u32 s12, s4, s24
	s_addc_u32 s13, s5, s25
	s_add_u32 s12, s12, 0x100
	s_addc_u32 s13, s13, 0
	s_add_u32 s26, s83, s24
	s_addc_u32 s27, s84, s25
	s_add_i32 s91, s46, 0x100
	v_add_u32_e32 v159, s91, v155
	ds_read_b128 v[160:163], v159
	ds_read_b128 v[164:167], v159 offset:1024
	ds_read_b128 v[168:171], v159 offset:2048
	ds_read_b128 v[172:175], v159 offset:3072
	s_cmpk_eq_i32 s24, 0x700
	s_cselect_b32 s29, s19, s13
	s_cselect_b32 s28, s85, s12
	s_cselect_b32 s27, s7, s27
	s_cselect_b32 s26, vcc_lo, s26
	v_lshl_add_u64 v[230:231], v[150:151], 0, s[24:25]
	s_add_i32 m0, s17, 0xc000
	ds_read_b128 v[176:179], v158
	ds_read_b128 v[180:183], v158 offset:1024
	ds_read_b128 v[184:187], v158 offset:2048
	ds_read_b128 v[210:213], v158 offset:3072
	ds_read_b128 v[214:217], v158 offset:4096
	ds_read_b128 v[218:221], v158 offset:5120
	ds_read_b128 v[222:225], v158 offset:6144
	ds_read_b128 v[226:229], v158 offset:7168
	global_load_lds_dwordx4 v[230:231], off
	v_lshl_add_u64 v[230:231], v[152:153], 0, s[24:25]
	s_add_i32 m0, s17, 0xe000
	s_nop 0
	global_load_lds_dwordx4 v[230:231], off
	s_waitcnt lgkmcnt(8)
	s_barrier
	s_waitcnt lgkmcnt(0)
	v_mfma_f32_16x16x32_bf16 v[124:127], v[160:163], v[176:179], v[124:127]
	v_mfma_f32_16x16x32_bf16 v[120:123], v[168:171], v[176:179], v[120:123]
	v_mfma_f32_16x16x32_bf16 v[116:119], v[160:163], v[184:187], v[116:119]
	v_mfma_f32_16x16x32_bf16 v[112:115], v[168:171], v[184:187], v[112:115]
	v_mfma_f32_16x16x32_bf16 v[108:111], v[160:163], v[214:217], v[108:111]
	v_mfma_f32_16x16x32_bf16 v[104:107], v[168:171], v[214:217], v[104:107]
	v_mfma_f32_16x16x32_bf16 v[100:103], v[160:163], v[222:225], v[100:103]
	v_mfma_f32_16x16x32_bf16 v[96:99], v[168:171], v[222:225], v[96:99]
	v_mfma_f32_16x16x32_bf16 v[124:127], v[164:167], v[180:183], v[124:127]
	v_mfma_f32_16x16x32_bf16 v[120:123], v[172:175], v[180:183], v[120:123]
	v_mfma_f32_16x16x32_bf16 v[116:119], v[164:167], v[210:213], v[116:119]
	v_mfma_f32_16x16x32_bf16 v[112:115], v[172:175], v[210:213], v[112:115]
	v_mfma_f32_16x16x32_bf16 v[108:111], v[164:167], v[218:221], v[108:111]
	v_mfma_f32_16x16x32_bf16 v[104:107], v[172:175], v[218:221], v[104:107]
	v_mfma_f32_16x16x32_bf16 v[100:103], v[164:167], v[226:229], v[100:103]
	v_mfma_f32_16x16x32_bf16 v[96:99], v[172:175], v[226:229], v[96:99]
	s_barrier
	s_add_i32 s69, s48, 0x100
	s_add_i32 s12, s91, s59
	v_add_u32_e32 v159, s69, v155
	v_lshl_add_u64 v[246:247], s[26:27], 0, v[138:139]
	s_mov_b32 m0, s12
	ds_read_b128 v[230:233], v159
	ds_read_b128 v[234:237], v159 offset:1024
	ds_read_b128 v[238:241], v159 offset:2048
	ds_read_b128 v[242:245], v159 offset:3072
	global_load_lds_dwordx4 v[246:247], off
	v_lshl_add_u64 v[248:249], s[26:27], 0, v[132:133]
	s_add_i32 m0, s12, 0x2000
	s_nop 0
	global_load_lds_dwordx4 v[248:249], off
	s_barrier
	s_waitcnt lgkmcnt(0)
	v_mfma_f32_16x16x32_bf16 v[60:63], v[230:233], v[176:179], v[60:63]
	v_mfma_f32_16x16x32_bf16 v[56:59], v[238:241], v[176:179], v[56:59]
	v_mfma_f32_16x16x32_bf16 v[52:55], v[230:233], v[184:187], v[52:55]
	v_mfma_f32_16x16x32_bf16 v[48:51], v[238:241], v[184:187], v[48:51]
	v_mfma_f32_16x16x32_bf16 v[44:47], v[230:233], v[214:217], v[44:47]
	v_mfma_f32_16x16x32_bf16 v[40:43], v[238:241], v[214:217], v[40:43]
	v_mfma_f32_16x16x32_bf16 v[36:39], v[230:233], v[222:225], v[36:39]
	v_mfma_f32_16x16x32_bf16 v[32:35], v[238:241], v[222:225], v[32:35]
	v_mfma_f32_16x16x32_bf16 v[60:63], v[234:237], v[180:183], v[60:63]
	v_mfma_f32_16x16x32_bf16 v[56:59], v[242:245], v[180:183], v[56:59]
	v_mfma_f32_16x16x32_bf16 v[52:55], v[234:237], v[210:213], v[52:55]
	v_mfma_f32_16x16x32_bf16 v[48:51], v[242:245], v[210:213], v[48:51]
	v_mfma_f32_16x16x32_bf16 v[44:47], v[234:237], v[218:221], v[44:47]
	v_mfma_f32_16x16x32_bf16 v[40:43], v[242:245], v[218:221], v[40:43]
	v_mfma_f32_16x16x32_bf16 v[36:39], v[234:237], v[226:229], v[36:39]
	v_mfma_f32_16x16x32_bf16 v[32:35], v[242:245], v[226:229], v[32:35]
	s_mov_b32 m0, s17
	v_lshl_add_u64 v[250:251], s[28:29], 0, v[128:129]
	s_barrier
	ds_read_b128 v[176:179], v158 offset:16384
	ds_read_b128 v[180:183], v158 offset:17408
	ds_read_b128 v[184:187], v158 offset:18432
	ds_read_b128 v[210:213], v158 offset:19456
	ds_read_b128 v[214:217], v158 offset:20480
	ds_read_b128 v[218:221], v158 offset:21504
	ds_read_b128 v[222:225], v158 offset:22528
	ds_read_b128 v[226:229], v158 offset:23552
	global_load_lds_dwordx4 v[250:251], off
	v_lshl_add_u64 v[252:253], s[28:29], 0, v[130:131]
	s_mov_b32 m0, s63
	s_nop 0
	global_load_lds_dwordx4 v[252:253], off
	s_barrier
	s_waitcnt lgkmcnt(0)
	v_mfma_f32_16x16x32_bf16 v[92:95], v[160:163], v[176:179], v[92:95]
	v_mfma_f32_16x16x32_bf16 v[88:91], v[168:171], v[176:179], v[88:91]
	v_mfma_f32_16x16x32_bf16 v[84:87], v[160:163], v[184:187], v[84:87]
	v_mfma_f32_16x16x32_bf16 v[80:83], v[168:171], v[184:187], v[80:83]
	v_mfma_f32_16x16x32_bf16 v[76:79], v[160:163], v[214:217], v[76:79]
	v_mfma_f32_16x16x32_bf16 v[72:75], v[168:171], v[214:217], v[72:75]
	v_mfma_f32_16x16x32_bf16 v[68:71], v[160:163], v[222:225], v[68:71]
	v_mfma_f32_16x16x32_bf16 v[64:67], v[168:171], v[222:225], v[64:67]
	v_mfma_f32_16x16x32_bf16 v[92:95], v[164:167], v[180:183], v[92:95]
	v_mfma_f32_16x16x32_bf16 v[88:91], v[172:175], v[180:183], v[88:91]
	v_mfma_f32_16x16x32_bf16 v[84:87], v[164:167], v[210:213], v[84:87]
	v_mfma_f32_16x16x32_bf16 v[80:83], v[172:175], v[210:213], v[80:83]
	v_mfma_f32_16x16x32_bf16 v[76:79], v[164:167], v[218:221], v[76:79]
	v_mfma_f32_16x16x32_bf16 v[72:75], v[172:175], v[218:221], v[72:75]
	v_mfma_f32_16x16x32_bf16 v[68:71], v[164:167], v[226:229], v[68:71]
	v_mfma_f32_16x16x32_bf16 v[64:67], v[172:175], v[226:229], v[64:67]
	s_barrier
; #define PG8_STAGE(bufoff, gbase, voff) do { _Pragma("unroll") for (int _i = 0; _i < 2; ++_i) \
;         __builtin_amdgcn_global_load_lds((const unsigned*)((const char*)(gbase) + (voff)[_i]), (PG8_LAS unsigned*)(lds + (bufoff) + ldsw + _i * 8192), 16, 0, 0); } while (0)
; #define PG8_LDA(dst, b, h) do { _Pragma("unroll") for (int m = 0; m < 4; ++m) _Pragma("unroll") for (int k = 0; k < 2; ++k) dst[m][k] = *(const PG8_LAS bf16x8*)(lds + PG8_SA(b, h) + aoff + m * 2048 + k * 1024); } while (0)
; #define PG8_LDB(dst, b, h) do { _Pragma("unroll") for (int n = 0; n < 2; ++n) _Pragma("unroll") for (int k = 0; k < 2; ++k) dst[n][k] = *(const PG8_LAS bf16x8*)(lds + PG8_SB(b, h) + boff + n * 2048 + k * 1024); } while (0)
; #define PG8_MMA(ai, bj, At, Bt) do { __builtin_amdgcn_s_setprio(1); _Pragma("unroll") for (int m = 0; m < 4; ++m) _Pragma("unroll") for (int n = 0; n < 2; ++n) _Pragma("unroll") for (int k = 0; k < 2; ++k) \
;         acc[ai][bj][m][n] = __builtin_amdgcn_mfma_f32_16x16x32_bf16(Bt[n][k], At[m][k], acc[ai][bj][m][n], 0, 0, 0); __builtin_amdgcn_s_setprio(0); } while (0)
; #define PG8_WAIT_V(n) asm volatile("s_waitcnt vmcnt(" #n ")" ::: "memory")
; #define PG8_WAIT_L(n) asm volatile("s_waitcnt lgkmcnt(" #n ")" ::: "memory")
; #define PG8_BAR __builtin_amdgcn_s_barrier()
; #define PG8_SCHED __builtin_amdgcn_sched_barrier(0)
; template <class Epi, class Sched>
; __device__ __forceinline__ void gemm_phase(PG8_LAS unsigned char* lds, const Gemm g, const Sched& S, const Epi& E) {
;     ...
;             PG8_STAGE(PG8_SB(0, 1), b2 + hstep, voffB);
;             PG8_WAIT_V(6); PG8_BAR; PG8_MMA(1, 1, At, B1); PG8_BAR;
;             PG8_LDB(B0, 1, 0); PG8_SCHED; PG8_LDA(At, 1, 0); PG8_STAGE(PG8_SA(0, 1), a2 + hstep, voffA);
;             PG8_WAIT_L(8); PG8_BAR; PG8_WAIT_L(0); PG8_MMA(0, 0, At, B0); PG8_BAR; PG8_SCHED;
;             PG8_LDB(B1, 1, 1); PG8_STAGE(PG8_SB(1, 0), b3, voffB);
;             PG8_BAR; PG8_WAIT_L(0); PG8_MMA(0, 1, At, B1); PG8_BAR;
;             PG8_LDA(At, 1, 1); PG8_STAGE(PG8_SA(1, 0), a3, voffA);
;             PG8_BAR; PG8_WAIT_L(0); PG8_MMA(1, 0, At, B0); PG8_BAR; PG8_SCHED;
	s_add_u32 s12, s26, 0x40000
	s_addc_u32 s13, s27, 0
	s_add_i32 s69, s69, s59
	v_lshl_add_u64 v[160:161], s[12:13], 0, v[138:139]
	s_mov_b32 m0, s69
	s_nop 0
	global_load_lds_dwordx4 v[160:161], off
	v_lshl_add_u64 v[160:161], s[12:13], 0, v[132:133]
	s_add_i32 m0, s69, 0x2000
	s_nop 0
	global_load_lds_dwordx4 v[160:161], off
	s_waitcnt vmcnt(6)
	s_barrier
	v_mfma_f32_16x16x32_bf16 v[28:31], v[230:233], v[176:179], v[28:31]
	v_mfma_f32_16x16x32_bf16 v[24:27], v[238:241], v[176:179], v[24:27]
	v_mfma_f32_16x16x32_bf16 v[20:23], v[230:233], v[184:187], v[20:23]
	v_mfma_f32_16x16x32_bf16 v[16:19], v[238:241], v[184:187], v[16:19]
	v_mfma_f32_16x16x32_bf16 v[12:15], v[230:233], v[214:217], v[12:15]
	v_mfma_f32_16x16x32_bf16 v[8:11], v[238:241], v[214:217], v[8:11]
	v_mfma_f32_16x16x32_bf16 v[4:7], v[230:233], v[222:225], v[4:7]
	v_mfma_f32_16x16x32_bf16 v[0:3], v[238:241], v[222:225], v[0:3]
	v_mfma_f32_16x16x32_bf16 v[28:31], v[234:237], v[180:183], v[28:31]
	v_mfma_f32_16x16x32_bf16 v[24:27], v[242:245], v[180:183], v[24:27]
	v_mfma_f32_16x16x32_bf16 v[20:23], v[234:237], v[210:213], v[20:23]
	v_mfma_f32_16x16x32_bf16 v[16:19], v[242:245], v[210:213], v[16:19]
	v_mfma_f32_16x16x32_bf16 v[12:15], v[234:237], v[218:221], v[12:15]
	v_mfma_f32_16x16x32_bf16 v[8:11], v[242:245], v[218:221], v[8:11]
	v_mfma_f32_16x16x32_bf16 v[4:7], v[234:237], v[226:229], v[4:7]
	v_mfma_f32_16x16x32_bf16 v[0:3], v[242:245], v[226:229], v[0:3]
	s_add_i32 s69, s51, 0x100
	v_add_u32_e32 v159, s69, v155
	s_barrier
	ds_read_b128 v[160:163], v159
	ds_read_b128 v[164:167], v159 offset:1024
	ds_read_b128 v[168:171], v159 offset:2048
	ds_read_b128 v[172:175], v159 offset:3072
	s_add_u32 s12, s28, 0x40000
	s_addc_u32 s13, s29, 0
	s_mov_b32 m0, s64
	v_lshl_add_u64 v[230:231], s[12:13], 0, v[128:129]
	ds_read_b128 v[176:179], v158 offset:32768
	ds_read_b128 v[180:183], v158 offset:33792
	ds_read_b128 v[184:187], v158 offset:34816
	ds_read_b128 v[210:213], v158 offset:35840
	ds_read_b128 v[214:217], v158 offset:36864
	ds_read_b128 v[218:221], v158 offset:37888
	ds_read_b128 v[222:225], v158 offset:38912
	ds_read_b128 v[226:229], v158 offset:39936
	global_load_lds_dwordx4 v[230:231], off
	v_lshl_add_u64 v[230:231], s[12:13], 0, v[130:131]
	s_mov_b32 m0, s65
	s_nop 0
	global_load_lds_dwordx4 v[230:231], off
	s_waitcnt lgkmcnt(8)
	s_barrier
	s_waitcnt lgkmcnt(0)
	v_mfma_f32_16x16x32_bf16 v[124:127], v[160:163], v[176:179], v[124:127]
	v_mfma_f32_16x16x32_bf16 v[120:123], v[168:171], v[176:179], v[120:123]
	v_mfma_f32_16x16x32_bf16 v[116:119], v[160:163], v[184:187], v[116:119]
	v_mfma_f32_16x16x32_bf16 v[112:115], v[168:171], v[184:187], v[112:115]
	v_mfma_f32_16x16x32_bf16 v[108:111], v[160:163], v[214:217], v[108:111]
	v_mfma_f32_16x16x32_bf16 v[104:107], v[168:171], v[214:217], v[104:107]
	v_mfma_f32_16x16x32_bf16 v[100:103], v[160:163], v[222:225], v[100:103]
	v_mfma_f32_16x16x32_bf16 v[96:99], v[168:171], v[222:225], v[96:99]
	v_mfma_f32_16x16x32_bf16 v[124:127], v[164:167], v[180:183], v[124:127]
	v_mfma_f32_16x16x32_bf16 v[120:123], v[172:175], v[180:183], v[120:123]
	v_mfma_f32_16x16x32_bf16 v[116:119], v[164:167], v[210:213], v[116:119]
	v_mfma_f32_16x16x32_bf16 v[112:115], v[172:175], v[210:213], v[112:115]
	v_mfma_f32_16x16x32_bf16 v[108:111], v[164:167], v[218:221], v[108:111]
	v_mfma_f32_16x16x32_bf16 v[104:107], v[172:175], v[218:221], v[104:107]
	v_mfma_f32_16x16x32_bf16 v[100:103], v[164:167], v[226:229], v[100:103]
	v_mfma_f32_16x16x32_bf16 v[96:99], v[172:175], v[226:229], v[96:99]
	s_barrier
	s_add_i32 s28, s55, 0x100
	s_add_i32 s12, s69, s59
	v_add_u32_e32 v159, s28, v155
	v_lshl_add_u64 v[246:247], v[246:247], 0, s[94:95]
	s_mov_b32 m0, s12
	ds_read_b128 v[230:233], v159
	ds_read_b128 v[234:237], v159 offset:1024
	ds_read_b128 v[238:241], v159 offset:2048
	ds_read_b128 v[242:245], v159 offset:3072
	global_load_lds_dwordx4 v[246:247], off
	v_lshl_add_u64 v[246:247], v[248:249], 0, s[94:95]
	s_add_i32 m0, s12, 0x2000
	s_nop 0
	global_load_lds_dwordx4 v[246:247], off
	s_barrier
	s_waitcnt lgkmcnt(0)
	v_mfma_f32_16x16x32_bf16 v[60:63], v[230:233], v[176:179], v[60:63]
	v_mfma_f32_16x16x32_bf16 v[56:59], v[238:241], v[176:179], v[56:59]
	v_mfma_f32_16x16x32_bf16 v[52:55], v[230:233], v[184:187], v[52:55]
	v_mfma_f32_16x16x32_bf16 v[48:51], v[238:241], v[184:187], v[48:51]
	v_mfma_f32_16x16x32_bf16 v[44:47], v[230:233], v[214:217], v[44:47]
	v_mfma_f32_16x16x32_bf16 v[40:43], v[238:241], v[214:217], v[40:43]
	v_mfma_f32_16x16x32_bf16 v[36:39], v[230:233], v[222:225], v[36:39]
	v_mfma_f32_16x16x32_bf16 v[32:35], v[238:241], v[222:225], v[32:35]
	v_mfma_f32_16x16x32_bf16 v[60:63], v[234:237], v[180:183], v[60:63]
	v_mfma_f32_16x16x32_bf16 v[56:59], v[242:245], v[180:183], v[56:59]
	v_mfma_f32_16x16x32_bf16 v[52:55], v[234:237], v[210:213], v[52:55]
	v_mfma_f32_16x16x32_bf16 v[48:51], v[242:245], v[210:213], v[48:51]
	v_mfma_f32_16x16x32_bf16 v[44:47], v[234:237], v[218:221], v[44:47]
	v_mfma_f32_16x16x32_bf16 v[40:43], v[242:245], v[218:221], v[40:43]
	v_mfma_f32_16x16x32_bf16 v[36:39], v[234:237], v[226:229], v[36:39]
	v_mfma_f32_16x16x32_bf16 v[32:35], v[242:245], v[226:229], v[32:35]
	s_mov_b32 m0, s66
	v_lshl_add_u64 v[246:247], v[250:251], 0, s[94:95]
	s_barrier
	ds_read_b128 v[176:179], v158 offset:49152
	ds_read_b128 v[180:183], v158 offset:50176
	ds_read_b128 v[184:187], v158 offset:51200
	ds_read_b128 v[210:213], v158 offset:52224
	ds_read_b128 v[214:217], v158 offset:53248
	ds_read_b128 v[218:221], v158 offset:54272
	ds_read_b128 v[222:225], v158 offset:55296
	ds_read_b128 v[226:229], v158 offset:56320
	global_load_lds_dwordx4 v[246:247], off
	v_lshl_add_u64 v[246:247], v[252:253], 0, s[94:95]
	s_mov_b32 m0, s67
	s_nop 0
	global_load_lds_dwordx4 v[246:247], off
	s_barrier
; #define PG8_STAGE(bufoff, gbase, voff) do { _Pragma("unroll") for (int _i = 0; _i < 2; ++_i) \
;         __builtin_amdgcn_global_load_lds((const unsigned*)((const char*)(gbase) + (voff)[_i]), (PG8_LAS unsigned*)(lds + (bufoff) + ldsw + _i * 8192), 16, 0, 0); } while (0)
; #define PG8_LDA(dst, b, h) do { _Pragma("unroll") for (int m = 0; m < 4; ++m) _Pragma("unroll") for (int k = 0; k < 2; ++k) dst[m][k] = *(const PG8_LAS bf16x8*)(lds + PG8_SA(b, h) + aoff + m * 2048 + k * 1024); } while (0)
; #define PG8_MMA(ai, bj, At, Bt) do { __builtin_amdgcn_s_setprio(1); _Pragma("unroll") for (int m = 0; m < 4; ++m) _Pragma("unroll") for (int n = 0; n < 2; ++n) _Pragma("unroll") for (int k = 0; k < 2; ++k) \
;         acc[ai][bj][m][n] = __builtin_amdgcn_mfma_f32_16x16x32_bf16(Bt[n][k], At[m][k], acc[ai][bj][m][n], 0, 0, 0); __builtin_amdgcn_s_setprio(0); } while (0)
; #define PG8_WAIT_V(n) asm volatile("s_waitcnt vmcnt(" #n ")" ::: "memory")
; #define PG8_WAIT_L(n) asm volatile("s_waitcnt lgkmcnt(" #n ")" ::: "memory")
; #define PG8_BAR __builtin_amdgcn_s_barrier()
; #define PG8_SCHED __builtin_amdgcn_sched_barrier(0)
; template <class Epi, class Sched>
; __device__ __forceinline__ void gemm_phase(PG8_LAS unsigned char* lds, const Gemm g, const Sched& S, const Epi& E) {
;     ...
;             PG8_LDA(At, 1, 1); PG8_STAGE(PG8_SA(1, 0), a3, voffA);
;             PG8_BAR; PG8_WAIT_L(0); PG8_MMA(1, 0, At, B0); PG8_BAR; PG8_SCHED;
;             PG8_STAGE(PG8_SB(1, 1), b3 + hstep, voffB);
;             PG8_WAIT_V(6); PG8_BAR; PG8_MMA(1, 1, At, B1); PG8_BAR;
;         }
;         if constexpr (!Epi::AFTER_DRAIN) { E(acc, cur, wr, wc, fr, fq); S.done(cur); }
;         if (!has_next) break;
; #pragma unroll
;         for (int a = 0; a < 2; ++a)
; #pragma unroll
;             for (int b = 0; b < 2; ++b)
; #pragma unroll
;                 for (int m = 0; m < 4; ++m)
; #pragma unroll
;                     for (int n = 0; n < 2; ++n) acc[a][b][m][n] = (f32x4){0.f, 0.f, 0.f, 0.f};
;         cur = nxt; cA = nA; cB = nB; ++ui;
	s_waitcnt lgkmcnt(0)
	v_mfma_f32_16x16x32_bf16 v[92:95], v[160:163], v[176:179], v[92:95]
	v_mfma_f32_16x16x32_bf16 v[88:91], v[168:171], v[176:179], v[88:91]
	v_mfma_f32_16x16x32_bf16 v[84:87], v[160:163], v[184:187], v[84:87]
	v_mfma_f32_16x16x32_bf16 v[80:83], v[168:171], v[184:187], v[80:83]
	v_mfma_f32_16x16x32_bf16 v[76:79], v[160:163], v[214:217], v[76:79]
	v_mfma_f32_16x16x32_bf16 v[72:75], v[168:171], v[214:217], v[72:75]
	v_mfma_f32_16x16x32_bf16 v[68:71], v[160:163], v[222:225], v[68:71]
	v_mfma_f32_16x16x32_bf16 v[64:67], v[168:171], v[222:225], v[64:67]
	v_mfma_f32_16x16x32_bf16 v[92:95], v[164:167], v[180:183], v[92:95]
	v_mfma_f32_16x16x32_bf16 v[88:91], v[172:175], v[180:183], v[88:91]
	v_mfma_f32_16x16x32_bf16 v[84:87], v[164:167], v[210:213], v[84:87]
	v_mfma_f32_16x16x32_bf16 v[80:83], v[172:175], v[210:213], v[80:83]
	v_mfma_f32_16x16x32_bf16 v[76:79], v[164:167], v[218:221], v[76:79]
	v_mfma_f32_16x16x32_bf16 v[72:75], v[172:175], v[218:221], v[72:75]
	v_mfma_f32_16x16x32_bf16 v[68:71], v[164:167], v[226:229], v[68:71]
	v_mfma_f32_16x16x32_bf16 v[64:67], v[172:175], v[226:229], v[64:67]
	s_barrier
	s_add_u32 s12, s26, 0x40080
	s_addc_u32 s13, s27, 0
	s_add_i32 s26, s28, s59
	v_lshl_add_u64 v[160:161], s[12:13], 0, v[138:139]
	s_mov_b32 m0, s26
	s_nop 0
	global_load_lds_dwordx4 v[160:161], off
	v_lshl_add_u64 v[160:161], s[12:13], 0, v[132:133]
	s_add_i32 m0, s26, 0x2000
	s_nop 0
	global_load_lds_dwordx4 v[160:161], off
	s_waitcnt vmcnt(6)
	s_barrier
	v_mfma_f32_16x16x32_bf16 v[28:31], v[230:233], v[176:179], v[28:31]
	v_mfma_f32_16x16x32_bf16 v[24:27], v[238:241], v[176:179], v[24:27]
	v_mfma_f32_16x16x32_bf16 v[20:23], v[230:233], v[184:187], v[20:23]
	v_mfma_f32_16x16x32_bf16 v[16:19], v[238:241], v[184:187], v[16:19]
	v_mfma_f32_16x16x32_bf16 v[12:15], v[230:233], v[214:217], v[12:15]
	v_mfma_f32_16x16x32_bf16 v[8:11], v[238:241], v[214:217], v[8:11]
	v_mfma_f32_16x16x32_bf16 v[4:7], v[230:233], v[222:225], v[4:7]
	v_mfma_f32_16x16x32_bf16 v[0:3], v[238:241], v[222:225], v[0:3]
	v_mfma_f32_16x16x32_bf16 v[28:31], v[234:237], v[180:183], v[28:31]
	v_mfma_f32_16x16x32_bf16 v[24:27], v[242:245], v[180:183], v[24:27]
	v_mfma_f32_16x16x32_bf16 v[20:23], v[234:237], v[210:213], v[20:23]
	v_mfma_f32_16x16x32_bf16 v[16:19], v[242:245], v[210:213], v[16:19]
	v_mfma_f32_16x16x32_bf16 v[12:15], v[234:237], v[218:221], v[12:15]
	v_mfma_f32_16x16x32_bf16 v[8:11], v[242:245], v[218:221], v[8:11]
	v_mfma_f32_16x16x32_bf16 v[4:7], v[234:237], v[226:229], v[4:7]
	v_mfma_f32_16x16x32_bf16 v[0:3], v[242:245], v[226:229], v[0:3]
	s_add_i32 vcc_hi, vcc_hi, 2
	s_add_u32 s24, s24, 0x100
	s_addc_u32 s25, s25, 0
	s_cmp_gt_u32 vcc_hi, 13
	s_barrier
	s_cbranch_scc0 .LBB0_803
	s_add_u32 s24, s83, 0xffffff00
	s_addc_u32 s25, s84, -1
	s_andn2_b64 vcc, exec, s[0:1]
	s_cbranch_vccnz .LBB0_806
	v_mov_b32_e32 v0, 0
	s_mov_b32 s34, s6
	s_mov_b32 s16, s18
	s_mov_b64 s[4:5], s[22:23]
	s_mov_b32 s68, s82
	v_mov_b32_e32 v1, v0
	v_mov_b32_e32 v2, v0
	v_mov_b32_e32 v3, v0
	v_mov_b32_e32 v4, v0
	v_mov_b32_e32 v5, v0
	v_mov_b32_e32 v6, v0
	v_mov_b32_e32 v7, v0
	v_mov_b32_e32 v8, v0
	v_mov_b32_e32 v9, v0
	v_mov_b32_e32 v10, v0
	v_mov_b32_e32 v11, v0
	v_mov_b32_e32 v12, v0
	v_mov_b32_e32 v13, v0
	v_mov_b32_e32 v14, v0
	v_mov_b32_e32 v15, v0
	v_mov_b32_e32 v16, v0
	v_mov_b32_e32 v17, v0
	v_mov_b32_e32 v18, v0
	v_mov_b32_e32 v19, v0
	v_mov_b32_e32 v20, v0
	v_mov_b32_e32 v21, v0
	v_mov_b32_e32 v22, v0
	v_mov_b32_e32 v23, v0
	v_mov_b32_e32 v24, v0
	v_mov_b32_e32 v25, v0
	v_mov_b32_e32 v26, v0
	v_mov_b32_e32 v27, v0
	v_mov_b32_e32 v28, v0
	v_mov_b32_e32 v29, v0
	v_mov_b32_e32 v30, v0
	v_mov_b32_e32 v31, v0
	v_mov_b32_e32 v64, v0
	v_mov_b32_e32 v65, v0
	v_mov_b32_e32 v66, v0
	v_mov_b32_e32 v67, v0
	v_mov_b32_e32 v68, v0
	v_mov_b32_e32 v69, v0
	v_mov_b32_e32 v70, v0
	v_mov_b32_e32 v71, v0
	v_mov_b32_e32 v72, v0
	v_mov_b32_e32 v73, v0
	v_mov_b32_e32 v74, v0
	v_mov_b32_e32 v75, v0
	v_mov_b32_e32 v76, v0
	v_mov_b32_e32 v77, v0
	v_mov_b32_e32 v78, v0
	v_mov_b32_e32 v79, v0
	v_mov_b32_e32 v80, v0
	v_mov_b32_e32 v81, v0
	v_mov_b32_e32 v82, v0
	v_mov_b32_e32 v83, v0
	v_mov_b32_e32 v84, v0
	v_mov_b32_e32 v85, v0
	v_mov_b32_e32 v86, v0
	v_mov_b32_e32 v87, v0
	v_mov_b32_e32 v88, v0
	v_mov_b32_e32 v89, v0
	v_mov_b32_e32 v90, v0
	v_mov_b32_e32 v91, v0
	v_mov_b32_e32 v92, v0
	v_mov_b32_e32 v93, v0
	v_mov_b32_e32 v94, v0
	v_mov_b32_e32 v95, v0
	v_mov_b32_e32 v32, v0
	v_mov_b32_e32 v33, v0
	v_mov_b32_e32 v34, v0
	v_mov_b32_e32 v35, v0
	v_mov_b32_e32 v36, v0
	v_mov_b32_e32 v37, v0
	v_mov_b32_e32 v38, v0
	v_mov_b32_e32 v39, v0
	v_mov_b32_e32 v40, v0
	v_mov_b32_e32 v41, v0
	v_mov_b32_e32 v42, v0
	v_mov_b32_e32 v43, v0
	v_mov_b32_e32 v44, v0
	v_mov_b32_e32 v45, v0
	v_mov_b32_e32 v46, v0
	v_mov_b32_e32 v47, v0
	v_mov_b32_e32 v48, v0
	v_mov_b32_e32 v49, v0
	v_mov_b32_e32 v50, v0
	v_mov_b32_e32 v51, v0
	v_mov_b32_e32 v52, v0
	v_mov_b32_e32 v53, v0
	v_mov_b32_e32 v54, v0
	v_mov_b32_e32 v55, v0
	v_mov_b32_e32 v56, v0
	v_mov_b32_e32 v57, v0
	v_mov_b32_e32 v58, v0
	v_mov_b32_e32 v59, v0
	v_mov_b32_e32 v60, v0
	v_mov_b32_e32 v61, v0
	v_mov_b32_e32 v62, v0
	v_mov_b32_e32 v63, v0
	v_mov_b32_e32 v96, v0
	v_mov_b32_e32 v97, v0
	v_mov_b32_e32 v98, v0
	v_mov_b32_e32 v99, v0
	v_mov_b32_e32 v100, v0
	v_mov_b32_e32 v101, v0
	v_mov_b32_e32 v102, v0
	v_mov_b32_e32 v103, v0
	v_mov_b32_e32 v104, v0
	v_mov_b32_e32 v105, v0
	v_mov_b32_e32 v106, v0
	v_mov_b32_e32 v107, v0
	v_mov_b32_e32 v108, v0
	v_mov_b32_e32 v109, v0
	v_mov_b32_e32 v110, v0
	v_mov_b32_e32 v111, v0
	v_mov_b32_e32 v112, v0
	v_mov_b32_e32 v113, v0
	v_mov_b32_e32 v114, v0
	v_mov_b32_e32 v115, v0
	v_mov_b32_e32 v116, v0
	v_mov_b32_e32 v117, v0
	v_mov_b32_e32 v118, v0
	v_mov_b32_e32 v119, v0
	v_mov_b32_e32 v120, v0
	v_mov_b32_e32 v121, v0
	v_mov_b32_e32 v122, v0
	v_mov_b32_e32 v123, v0
	v_mov_b32_e32 v124, v0
	v_mov_b32_e32 v125, v0
	v_mov_b32_e32 v126, v0
	v_mov_b32_e32 v127, v0
	s_mov_b32 s91, 0x12000
	s_andn2_b64 vcc, exec, s[2:3]
	s_cbranch_vccnz .LBB0_807
	s_branch .LBB0_808

; #define PG8_STAGE(bufoff, gbase, voff) do { _Pragma("unroll") for (int _i = 0; _i < 2; ++_i) \
;         __builtin_amdgcn_global_load_lds((const unsigned*)((const char*)(gbase) + (voff)[_i]), (PG8_LAS unsigned*)(lds + (bufoff) + ldsw + _i * 8192), 16, 0, 0); } while (0)
; #define PG8_LDA(dst, b, h) do { _Pragma("unroll") for (int m = 0; m < 4; ++m) _Pragma("unroll") for (int k = 0; k < 2; ++k) dst[m][k] = *(const PG8_LAS bf16x8*)(lds + PG8_SA(b, h) + aoff + m * 2048 + k * 1024); } while (0)
; #define PG8_LDB(dst, b, h) do { _Pragma("unroll") for (int n = 0; n < 2; ++n) _Pragma("unroll") for (int k = 0; k < 2; ++k) dst[n][k] = *(const PG8_LAS bf16x8*)(lds + PG8_SB(b, h) + boff + n * 2048 + k * 1024); } while (0)
; #define PG8_WAIT_V(n) asm volatile("s_waitcnt vmcnt(" #n ")" ::: "memory")
; #define PG8_BAR __builtin_amdgcn_s_barrier()
; template <class Epi, class Sched>
; __device__ __forceinline__ void gemm_phase(PG8_LAS unsigned char* lds, const Gemm g, const Sched& S, const Epi& E) {
;     ...
;         for (int t = 0; t < nt; t += 2) {
;             const bool last = (t == nt - 2);
;             const char* a1 = cA + (size_t)(t + 1) * kstep;
;             const char* a2 = last ? nA : cA + (size_t)(t + 2) * kstep; const char* b2 = last ? nB : cB + (size_t)(t + 2) * kstep;
;             const char* a3 = a2 + kstep; const char* b3 = b2 + kstep;
;             if (last && has_next) S.a_ready(nxt);
;             PG8_LDB(B0, 0, 0); PG8_SCHED; PG8_LDA(At, 0, 0); PG8_STAGE(PG8_SA(1, 1), a1 + hstep, voffA);
;             PG8_WAIT_L(8); PG8_BAR; PG8_WAIT_L(0); PG8_MMA(0, 0, At, B0); PG8_BAR; PG8_SCHED;
;             PG8_LDB(B1, 0, 1); PG8_STAGE(PG8_SB(0, 0), b2, voffB);
;             PG8_BAR; PG8_WAIT_L(0); PG8_MMA(0, 1, At, B1); PG8_BAR;
;             PG8_LDA(At, 0, 1); PG8_STAGE(PG8_SA(0, 0), a2, voffA);
;             PG8_BAR; PG8_WAIT_L(0); PG8_MMA(1, 0, At, B0); PG8_BAR; PG8_SCHED;
;             PG8_STAGE(PG8_SB(0, 1), b2 + hstep, voffB);
;             PG8_WAIT_V(6); PG8_BAR; PG8_MMA(1, 1, At, B1); PG8_BAR;
;             PG8_LDB(B0, 1, 0); PG8_SCHED; PG8_LDA(At, 1, 0); PG8_STAGE(PG8_SA(0, 1), a2 + hstep, voffA);
;             PG8_WAIT_L(8); PG8_BAR; PG8_WAIT_L(0); PG8_MMA(0, 0, At, B0); PG8_BAR; PG8_SCHED;
;             PG8_LDB(B1, 1, 1); PG8_STAGE(PG8_SB(1, 0), b3, voffB);
;             PG8_BAR; PG8_WAIT_L(0); PG8_MMA(0, 1, At, B1); PG8_BAR;
.LBB0_997:
	s_add_u32 s12, s18, 0xfffc0080
	s_addc_u32 s13, s19, -1
	s_add_i32 s61, s46, 0x100
	v_add_u32_e32 v166, s61, v155
	ds_read_b128 v[150:153], v166
	ds_read_b128 v[158:161], v166 offset:1024
	ds_read_b128 v[162:165], v166 offset:2048
	ds_read_b128 v[166:169], v166 offset:3072
	s_cmp_eq_u32 s60, 12
	s_cselect_b32 s23, s7, s13
	s_cselect_b32 s22, s40, s12
	s_cselect_b32 s21, s5, s59
	s_cselect_b32 s20, s41, s58
	v_lshl_add_u64 v[186:187], s[18:19], 0, v[134:135]
	s_add_i32 m0, s17, 0xc000
	ds_read_b128 v[170:173], v157
	ds_read_b128 v[174:177], v157 offset:1024
	ds_read_b128 v[178:181], v157 offset:2048
	ds_read_b128 v[182:185], v157 offset:3072
	ds_read_b128 v[210:213], v157 offset:4096
	ds_read_b128 v[214:217], v157 offset:5120
	ds_read_b128 v[218:221], v157 offset:6144
	ds_read_b128 v[222:225], v157 offset:7168
	global_load_lds_dwordx4 v[186:187], off
	v_lshl_add_u64 v[186:187], s[18:19], 0, v[148:149]
	s_add_i32 m0, s17, 0xe000
	s_nop 0
	global_load_lds_dwordx4 v[186:187], off
	s_waitcnt lgkmcnt(8)
	s_barrier
	s_waitcnt lgkmcnt(0)
	v_mfma_f32_16x16x32_bf16 v[124:127], v[150:153], v[170:173], v[124:127]
	v_mfma_f32_16x16x32_bf16 v[116:119], v[162:165], v[170:173], v[116:119]
	v_mfma_f32_16x16x32_bf16 v[108:111], v[150:153], v[178:181], v[108:111]
	v_mfma_f32_16x16x32_bf16 v[100:103], v[162:165], v[178:181], v[100:103]
	v_mfma_f32_16x16x32_bf16 v[92:95], v[150:153], v[210:213], v[92:95]
	v_mfma_f32_16x16x32_bf16 v[84:87], v[162:165], v[210:213], v[84:87]
	v_mfma_f32_16x16x32_bf16 v[76:79], v[150:153], v[218:221], v[76:79]
	v_mfma_f32_16x16x32_bf16 v[68:71], v[162:165], v[218:221], v[68:71]
	v_mfma_f32_16x16x32_bf16 v[124:127], v[158:161], v[174:177], v[124:127]
	v_mfma_f32_16x16x32_bf16 v[116:119], v[166:169], v[174:177], v[116:119]
	v_mfma_f32_16x16x32_bf16 v[108:111], v[158:161], v[182:185], v[108:111]
	v_mfma_f32_16x16x32_bf16 v[100:103], v[166:169], v[182:185], v[100:103]
	v_mfma_f32_16x16x32_bf16 v[92:95], v[158:161], v[214:217], v[92:95]
	v_mfma_f32_16x16x32_bf16 v[84:87], v[166:169], v[214:217], v[84:87]
	v_mfma_f32_16x16x32_bf16 v[76:79], v[158:161], v[222:225], v[76:79]
	v_mfma_f32_16x16x32_bf16 v[68:71], v[166:169], v[222:225], v[68:71]
	s_barrier
	s_add_i32 s62, s48, 0x100
	v_add_u32_e32 v186, s62, v155
	s_add_i32 s12, s61, s31
	ds_read_b128 v[226:229], v186
	ds_read_b128 v[230:233], v186 offset:1024
	ds_read_b128 v[234:237], v186 offset:2048
	ds_read_b128 v[238:241], v186 offset:3072
	v_lshl_add_u64 v[186:187], s[20:21], 0, v[138:139]
	s_mov_b32 m0, s12
	v_lshl_add_u64 v[242:243], s[20:21], 0, v[132:133]
	global_load_lds_dwordx4 v[186:187], off
	s_add_i32 m0, s12, 0x2000
	s_nop 0
	global_load_lds_dwordx4 v[242:243], off
	s_barrier
	s_waitcnt lgkmcnt(0)
	v_mfma_f32_16x16x32_bf16 v[120:123], v[226:229], v[170:173], v[120:123]
	v_mfma_f32_16x16x32_bf16 v[112:115], v[234:237], v[170:173], v[112:115]
	v_mfma_f32_16x16x32_bf16 v[104:107], v[226:229], v[178:181], v[104:107]
	v_mfma_f32_16x16x32_bf16 v[96:99], v[234:237], v[178:181], v[96:99]
	v_mfma_f32_16x16x32_bf16 v[88:91], v[226:229], v[210:213], v[88:91]
	v_mfma_f32_16x16x32_bf16 v[80:83], v[234:237], v[210:213], v[80:83]
	v_mfma_f32_16x16x32_bf16 v[72:75], v[226:229], v[218:221], v[72:75]
	v_mfma_f32_16x16x32_bf16 v[64:67], v[234:237], v[218:221], v[64:67]
	v_mfma_f32_16x16x32_bf16 v[120:123], v[230:233], v[174:177], v[120:123]
	v_mfma_f32_16x16x32_bf16 v[112:115], v[238:241], v[174:177], v[112:115]
	v_mfma_f32_16x16x32_bf16 v[104:107], v[230:233], v[182:185], v[104:107]
	v_mfma_f32_16x16x32_bf16 v[96:99], v[238:241], v[182:185], v[96:99]
	v_mfma_f32_16x16x32_bf16 v[88:91], v[230:233], v[214:217], v[88:91]
	v_mfma_f32_16x16x32_bf16 v[80:83], v[238:241], v[214:217], v[80:83]
	v_mfma_f32_16x16x32_bf16 v[72:75], v[230:233], v[222:225], v[72:75]
	v_mfma_f32_16x16x32_bf16 v[64:67], v[238:241], v[222:225], v[64:67]
	s_mov_b32 m0, s17
	v_lshl_add_u64 v[244:245], s[22:23], 0, v[128:129]
	s_barrier
	ds_read_b128 v[170:173], v157 offset:16384
	ds_read_b128 v[174:177], v157 offset:17408
	ds_read_b128 v[178:181], v157 offset:18432
	ds_read_b128 v[182:185], v157 offset:19456
	ds_read_b128 v[210:213], v157 offset:20480
	ds_read_b128 v[214:217], v157 offset:21504
	ds_read_b128 v[218:221], v157 offset:22528
	ds_read_b128 v[222:225], v157 offset:23552
	global_load_lds_dwordx4 v[244:245], off
	v_lshl_add_u64 v[246:247], s[22:23], 0, v[130:131]
	s_mov_b32 m0, s33
	s_nop 0
	global_load_lds_dwordx4 v[246:247], off
	s_barrier
	s_waitcnt lgkmcnt(0)
	v_mfma_f32_16x16x32_bf16 v[60:63], v[150:153], v[170:173], v[60:63]
	v_mfma_f32_16x16x32_bf16 v[52:55], v[162:165], v[170:173], v[52:55]
	v_mfma_f32_16x16x32_bf16 v[44:47], v[150:153], v[178:181], v[44:47]
	v_mfma_f32_16x16x32_bf16 v[36:39], v[162:165], v[178:181], v[36:39]
	v_mfma_f32_16x16x32_bf16 v[28:31], v[150:153], v[210:213], v[28:31]
	v_mfma_f32_16x16x32_bf16 v[20:23], v[162:165], v[210:213], v[20:23]
	v_mfma_f32_16x16x32_bf16 v[12:15], v[150:153], v[218:221], v[12:15]
	v_mfma_f32_16x16x32_bf16 v[4:7], v[162:165], v[218:221], v[4:7]
	v_mfma_f32_16x16x32_bf16 v[60:63], v[158:161], v[174:177], v[60:63]
	v_mfma_f32_16x16x32_bf16 v[52:55], v[166:169], v[174:177], v[52:55]
	v_mfma_f32_16x16x32_bf16 v[44:47], v[158:161], v[182:185], v[44:47]
	v_mfma_f32_16x16x32_bf16 v[36:39], v[166:169], v[182:185], v[36:39]
	v_mfma_f32_16x16x32_bf16 v[28:31], v[158:161], v[214:217], v[28:31]
	v_mfma_f32_16x16x32_bf16 v[20:23], v[166:169], v[214:217], v[20:23]
	v_mfma_f32_16x16x32_bf16 v[12:15], v[158:161], v[222:225], v[12:15]
	v_mfma_f32_16x16x32_bf16 v[4:7], v[166:169], v[222:225], v[4:7]
	s_barrier
; #define PG8_STAGE(bufoff, gbase, voff) do { _Pragma("unroll") for (int _i = 0; _i < 2; ++_i) \
;         __builtin_amdgcn_global_load_lds((const unsigned*)((const char*)(gbase) + (voff)[_i]), (PG8_LAS unsigned*)(lds + (bufoff) + ldsw + _i * 8192), 16, 0, 0); } while (0)
; #define PG8_LDA(dst, b, h) do { _Pragma("unroll") for (int m = 0; m < 4; ++m) _Pragma("unroll") for (int k = 0; k < 2; ++k) dst[m][k] = *(const PG8_LAS bf16x8*)(lds + PG8_SA(b, h) + aoff + m * 2048 + k * 1024); } while (0)
; #define PG8_LDB(dst, b, h) do { _Pragma("unroll") for (int n = 0; n < 2; ++n) _Pragma("unroll") for (int k = 0; k < 2; ++k) dst[n][k] = *(const PG8_LAS bf16x8*)(lds + PG8_SB(b, h) + boff + n * 2048 + k * 1024); } while (0)
; #define PG8_MMA(ai, bj, At, Bt) do { __builtin_amdgcn_s_setprio(1); _Pragma("unroll") for (int m = 0; m < 4; ++m) _Pragma("unroll") for (int n = 0; n < 2; ++n) _Pragma("unroll") for (int k = 0; k < 2; ++k) \
;         acc[ai][bj][m][n] = __builtin_amdgcn_mfma_f32_16x16x32_bf16(Bt[n][k], At[m][k], acc[ai][bj][m][n], 0, 0, 0); __builtin_amdgcn_s_setprio(0); } while (0)
; #define PG8_WAIT_V(n) asm volatile("s_waitcnt vmcnt(" #n ")" ::: "memory")
; #define PG8_WAIT_L(n) asm volatile("s_waitcnt lgkmcnt(" #n ")" ::: "memory")
; #define PG8_BAR __builtin_amdgcn_s_barrier()
; #define PG8_SCHED __builtin_amdgcn_sched_barrier(0)
; template <class Epi, class Sched>
; __device__ __forceinline__ void gemm_phase(PG8_LAS unsigned char* lds, const Gemm g, const Sched& S, const Epi& E) {
;     ...
;             PG8_STAGE(PG8_SB(0, 1), b2 + hstep, voffB);
;             PG8_WAIT_V(6); PG8_BAR; PG8_MMA(1, 1, At, B1); PG8_BAR;
;             PG8_LDB(B0, 1, 0); PG8_SCHED; PG8_LDA(At, 1, 0); PG8_STAGE(PG8_SA(0, 1), a2 + hstep, voffA);
;             PG8_WAIT_L(8); PG8_BAR; PG8_WAIT_L(0); PG8_MMA(0, 0, At, B0); PG8_BAR; PG8_SCHED;
;             PG8_LDB(B1, 1, 1); PG8_STAGE(PG8_SB(1, 0), b3, voffB);
;             PG8_BAR; PG8_WAIT_L(0); PG8_MMA(0, 1, At, B1); PG8_BAR;
;             PG8_LDA(At, 1, 1); PG8_STAGE(PG8_SA(1, 0), a3, voffA);
;             PG8_BAR; PG8_WAIT_L(0); PG8_MMA(1, 0, At, B0); PG8_BAR; PG8_SCHED;
	s_add_u32 s12, s20, 0x40000
	s_addc_u32 s13, s21, 0
	s_add_i32 s61, s62, s31
	v_lshl_add_u64 v[150:151], s[12:13], 0, v[138:139]
	s_mov_b32 m0, s61
	s_nop 0
	global_load_lds_dwordx4 v[150:151], off
	v_lshl_add_u64 v[150:151], s[12:13], 0, v[132:133]
	s_add_i32 m0, s61, 0x2000
	s_nop 0
	global_load_lds_dwordx4 v[150:151], off
	s_waitcnt vmcnt(6)
	s_barrier
	v_mfma_f32_16x16x32_bf16 v[56:59], v[226:229], v[170:173], v[56:59]
	v_mfma_f32_16x16x32_bf16 v[48:51], v[234:237], v[170:173], v[48:51]
	v_mfma_f32_16x16x32_bf16 v[40:43], v[226:229], v[178:181], v[40:43]
	v_mfma_f32_16x16x32_bf16 v[32:35], v[234:237], v[178:181], v[32:35]
	v_mfma_f32_16x16x32_bf16 v[24:27], v[226:229], v[210:213], v[24:27]
	v_mfma_f32_16x16x32_bf16 v[16:19], v[234:237], v[210:213], v[16:19]
	v_mfma_f32_16x16x32_bf16 v[8:11], v[226:229], v[218:221], v[8:11]
	v_mfma_f32_16x16x32_bf16 v[0:3], v[234:237], v[218:221], v[0:3]
	v_mfma_f32_16x16x32_bf16 v[56:59], v[230:233], v[174:177], v[56:59]
	v_mfma_f32_16x16x32_bf16 v[48:51], v[238:241], v[174:177], v[48:51]
	v_mfma_f32_16x16x32_bf16 v[40:43], v[230:233], v[182:185], v[40:43]
	v_mfma_f32_16x16x32_bf16 v[32:35], v[238:241], v[182:185], v[32:35]
	v_mfma_f32_16x16x32_bf16 v[24:27], v[230:233], v[214:217], v[24:27]
	v_mfma_f32_16x16x32_bf16 v[16:19], v[238:241], v[214:217], v[16:19]
	v_mfma_f32_16x16x32_bf16 v[8:11], v[230:233], v[222:225], v[8:11]
	v_mfma_f32_16x16x32_bf16 v[0:3], v[238:241], v[222:225], v[0:3]
	s_add_i32 s61, s51, 0x100
	v_add_u32_e32 v166, s61, v155
	s_barrier
	ds_read_b128 v[150:153], v166
	ds_read_b128 v[158:161], v166 offset:1024
	ds_read_b128 v[162:165], v166 offset:2048
	ds_read_b128 v[166:169], v166 offset:3072
	s_add_u32 s12, s22, 0x40000
	s_addc_u32 s13, s23, 0
	s_mov_b32 m0, s34
	v_lshl_add_u64 v[226:227], s[12:13], 0, v[128:129]
	ds_read_b128 v[170:173], v157 offset:32768
	ds_read_b128 v[174:177], v157 offset:33792
	ds_read_b128 v[178:181], v157 offset:34816
	ds_read_b128 v[182:185], v157 offset:35840
	ds_read_b128 v[210:213], v157 offset:36864
	ds_read_b128 v[214:217], v157 offset:37888
	ds_read_b128 v[218:221], v157 offset:38912
	ds_read_b128 v[222:225], v157 offset:39936
	global_load_lds_dwordx4 v[226:227], off
	v_lshl_add_u64 v[226:227], s[12:13], 0, v[130:131]
	s_mov_b32 m0, s35
	s_nop 0
	global_load_lds_dwordx4 v[226:227], off
	s_waitcnt lgkmcnt(8)
	s_barrier
	s_waitcnt lgkmcnt(0)
	v_mfma_f32_16x16x32_bf16 v[124:127], v[150:153], v[170:173], v[124:127]
	v_mfma_f32_16x16x32_bf16 v[116:119], v[162:165], v[170:173], v[116:119]
	v_mfma_f32_16x16x32_bf16 v[108:111], v[150:153], v[178:181], v[108:111]
	v_mfma_f32_16x16x32_bf16 v[100:103], v[162:165], v[178:181], v[100:103]
	v_mfma_f32_16x16x32_bf16 v[92:95], v[150:153], v[210:213], v[92:95]
	v_mfma_f32_16x16x32_bf16 v[84:87], v[162:165], v[210:213], v[84:87]
	v_mfma_f32_16x16x32_bf16 v[76:79], v[150:153], v[218:221], v[76:79]
	v_mfma_f32_16x16x32_bf16 v[68:71], v[162:165], v[218:221], v[68:71]
	v_mfma_f32_16x16x32_bf16 v[124:127], v[158:161], v[174:177], v[124:127]
	v_mfma_f32_16x16x32_bf16 v[116:119], v[166:169], v[174:177], v[116:119]
	v_mfma_f32_16x16x32_bf16 v[108:111], v[158:161], v[182:185], v[108:111]
	v_mfma_f32_16x16x32_bf16 v[100:103], v[166:169], v[182:185], v[100:103]
	v_mfma_f32_16x16x32_bf16 v[92:95], v[158:161], v[214:217], v[92:95]
	v_mfma_f32_16x16x32_bf16 v[84:87], v[166:169], v[214:217], v[84:87]
	v_mfma_f32_16x16x32_bf16 v[76:79], v[158:161], v[222:225], v[76:79]
	v_mfma_f32_16x16x32_bf16 v[68:71], v[166:169], v[222:225], v[68:71]
	s_barrier
	s_add_i32 s22, s55, 0x100
	s_add_i32 s12, s61, s31
	v_add_u32_e32 v209, s22, v155
	v_lshl_add_u64 v[186:187], v[186:187], 0, s[94:95]
	s_mov_b32 m0, s12
	ds_read_b128 v[226:229], v209
	ds_read_b128 v[230:233], v209 offset:1024
	ds_read_b128 v[234:237], v209 offset:2048
	ds_read_b128 v[238:241], v209 offset:3072
	global_load_lds_dwordx4 v[186:187], off
	v_lshl_add_u64 v[186:187], v[242:243], 0, s[94:95]
	s_add_i32 m0, s12, 0x2000
	s_nop 0
	global_load_lds_dwordx4 v[186:187], off
	s_barrier
	s_waitcnt lgkmcnt(0)
	v_mfma_f32_16x16x32_bf16 v[120:123], v[226:229], v[170:173], v[120:123]
	v_mfma_f32_16x16x32_bf16 v[112:115], v[234:237], v[170:173], v[112:115]
	v_mfma_f32_16x16x32_bf16 v[104:107], v[226:229], v[178:181], v[104:107]
	v_mfma_f32_16x16x32_bf16 v[96:99], v[234:237], v[178:181], v[96:99]
	v_mfma_f32_16x16x32_bf16 v[88:91], v[226:229], v[210:213], v[88:91]
	v_mfma_f32_16x16x32_bf16 v[80:83], v[234:237], v[210:213], v[80:83]
	v_mfma_f32_16x16x32_bf16 v[72:75], v[226:229], v[218:221], v[72:75]
	v_mfma_f32_16x16x32_bf16 v[64:67], v[234:237], v[218:221], v[64:67]
	v_mfma_f32_16x16x32_bf16 v[120:123], v[230:233], v[174:177], v[120:123]
	v_mfma_f32_16x16x32_bf16 v[112:115], v[238:241], v[174:177], v[112:115]
	v_mfma_f32_16x16x32_bf16 v[104:107], v[230:233], v[182:185], v[104:107]
	v_mfma_f32_16x16x32_bf16 v[96:99], v[238:241], v[182:185], v[96:99]
	v_mfma_f32_16x16x32_bf16 v[88:91], v[230:233], v[214:217], v[88:91]
	v_mfma_f32_16x16x32_bf16 v[80:83], v[238:241], v[214:217], v[80:83]
	v_mfma_f32_16x16x32_bf16 v[72:75], v[230:233], v[222:225], v[72:75]
	v_mfma_f32_16x16x32_bf16 v[64:67], v[238:241], v[222:225], v[64:67]
	s_mov_b32 m0, s36
	v_lshl_add_u64 v[186:187], v[244:245], 0, s[94:95]
	s_barrier
	ds_read_b128 v[170:173], v157 offset:49152
	ds_read_b128 v[174:177], v157 offset:50176
	ds_read_b128 v[178:181], v157 offset:51200
	ds_read_b128 v[182:185], v157 offset:52224
	ds_read_b128 v[210:213], v157 offset:53248
	ds_read_b128 v[214:217], v157 offset:54272
	ds_read_b128 v[218:221], v157 offset:55296
	ds_read_b128 v[222:225], v157 offset:56320
	global_load_lds_dwordx4 v[186:187], off
	v_lshl_add_u64 v[186:187], v[246:247], 0, s[94:95]
	s_mov_b32 m0, s37
	s_nop 0
	global_load_lds_dwordx4 v[186:187], off
	s_barrier
;   __device__ __forceinline__ bf16* y() const { unsigned o_ = (unsigned)(OFF_y); asm volatile("" : "+s"(o_)); return (bf16*)(ws + o_); }
; __device__ __forceinline__ unsigned pk2(float a, float b) { unsigned r; asm("v_cvt_pk_bf16_f32 %0, %1, %2" : "=v"(r) : "v"(a), "v"(b)); return r; }
; __device__ __forceinline__ float silu(float x) { return x * sigm(x); }
; #define PG8_STAGE(bufoff, gbase, voff) do { _Pragma("unroll") for (int _i = 0; _i < 2; ++_i) \
;         __builtin_amdgcn_global_load_lds((const unsigned*)((const char*)(gbase) + (voff)[_i]), (PG8_LAS unsigned*)(lds + (bufoff) + ldsw + _i * 8192), 16, 0, 0); } while (0)
; #define PG8_LDA(dst, b, h) do { _Pragma("unroll") for (int m = 0; m < 4; ++m) _Pragma("unroll") for (int k = 0; k < 2; ++k) dst[m][k] = *(const PG8_LAS bf16x8*)(lds + PG8_SA(b, h) + aoff + m * 2048 + k * 1024); } while (0)
; #define PG8_WAIT_V(n) asm volatile("s_waitcnt vmcnt(" #n ")" ::: "memory")
; #define PG8_WAIT_L(n) asm volatile("s_waitcnt lgkmcnt(" #n ")" ::: "memory")
; #define PG8_BAR __builtin_amdgcn_s_barrier()
; #define PG8_SCHED __builtin_amdgcn_sched_barrier(0)
; template <class Epi, class Sched>
; __device__ __forceinline__ void gemm_phase(PG8_LAS unsigned char* lds, const Gemm g, const Sched& S, const Epi& E) {
;     ...
;             PG8_LDA(At, 1, 1); PG8_STAGE(PG8_SA(1, 0), a3, voffA);
;             PG8_BAR; PG8_WAIT_L(0); PG8_MMA(1, 0, At, B0); PG8_BAR; PG8_SCHED;
;             PG8_STAGE(PG8_SB(1, 1), b3 + hstep, voffB);
;             PG8_WAIT_V(6); PG8_BAR; PG8_MMA(1, 1, At, B1); PG8_BAR;
;         }
;   __device__ __forceinline__ void operator()(const f32x4 (&acc)[2][2][4][2], const pg8::Unit& u, int wr, int wc, int fr, int fq) const {
;     const int row0 = u.pm * 256 + wr * 64 + fr, col0 = u.pn * 128 + wc * 32 + 8 * fq;
; #pragma unroll
;     for (int ai = 0; ai < 2; ++ai)
; #pragma unroll
;       for (int m = 0; m < 4; ++m) {
;         bf16* rowp = O + (size_t)(row0 + ai * 128 + m * 16) * FF + col0;
;         const f32x4 g0 = acc[ai][0][m][0], g1 = acc[ai][0][m][1], u0 = acc[ai][1][m][0], u1 = acc[ai][1][m][1];
;         uint4 o;
;         o.x = pk2(silu(g0[0]) * u0[0], silu(g0[1]) * u0[1]); o.y = pk2(silu(g0[2]) * u0[2], silu(g0[3]) * u0[3]);
;         o.z = pk2(silu(g1[0]) * u1[0], silu(g1[1]) * u1[1]); o.w = pk2(silu(g1[2]) * u1[2], silu(g1[3]) * u1[3]);
;         *(uint4*)rowp = o;
	s_waitcnt lgkmcnt(0)
	v_mfma_f32_16x16x32_bf16 v[60:63], v[150:153], v[170:173], v[60:63]
	v_mfma_f32_16x16x32_bf16 v[52:55], v[162:165], v[170:173], v[52:55]
	v_mfma_f32_16x16x32_bf16 v[44:47], v[150:153], v[178:181], v[44:47]
	v_mfma_f32_16x16x32_bf16 v[36:39], v[162:165], v[178:181], v[36:39]
	v_mfma_f32_16x16x32_bf16 v[28:31], v[150:153], v[210:213], v[28:31]
	v_mfma_f32_16x16x32_bf16 v[20:23], v[162:165], v[210:213], v[20:23]
	v_mfma_f32_16x16x32_bf16 v[12:15], v[150:153], v[218:221], v[12:15]
	v_mfma_f32_16x16x32_bf16 v[4:7], v[162:165], v[218:221], v[4:7]
	v_mfma_f32_16x16x32_bf16 v[60:63], v[158:161], v[174:177], v[60:63]
	v_mfma_f32_16x16x32_bf16 v[52:55], v[166:169], v[174:177], v[52:55]
	v_mfma_f32_16x16x32_bf16 v[44:47], v[158:161], v[182:185], v[44:47]
	v_mfma_f32_16x16x32_bf16 v[36:39], v[166:169], v[182:185], v[36:39]
	v_mfma_f32_16x16x32_bf16 v[28:31], v[158:161], v[214:217], v[28:31]
	v_mfma_f32_16x16x32_bf16 v[20:23], v[166:169], v[214:217], v[20:23]
	v_mfma_f32_16x16x32_bf16 v[12:15], v[158:161], v[222:225], v[12:15]
	v_mfma_f32_16x16x32_bf16 v[4:7], v[166:169], v[222:225], v[4:7]
	s_barrier
	s_add_u32 s12, s20, 0x40080
	s_addc_u32 s13, s21, 0
	s_add_i32 s20, s22, s31
	v_lshl_add_u64 v[150:151], s[12:13], 0, v[138:139]
	s_mov_b32 m0, s20
	s_nop 0
	global_load_lds_dwordx4 v[150:151], off
	v_lshl_add_u64 v[150:151], s[12:13], 0, v[132:133]
	s_add_i32 m0, s20, 0x2000
	s_nop 0
	global_load_lds_dwordx4 v[150:151], off
	s_waitcnt vmcnt(6)
	s_barrier
	v_mfma_f32_16x16x32_bf16 v[56:59], v[226:229], v[170:173], v[56:59]
	v_mfma_f32_16x16x32_bf16 v[48:51], v[234:237], v[170:173], v[48:51]
	v_mfma_f32_16x16x32_bf16 v[40:43], v[226:229], v[178:181], v[40:43]
	v_mfma_f32_16x16x32_bf16 v[32:35], v[234:237], v[178:181], v[32:35]
	v_mfma_f32_16x16x32_bf16 v[24:27], v[226:229], v[210:213], v[24:27]
	v_mfma_f32_16x16x32_bf16 v[16:19], v[234:237], v[210:213], v[16:19]
	v_mfma_f32_16x16x32_bf16 v[8:11], v[226:229], v[218:221], v[8:11]
	v_mfma_f32_16x16x32_bf16 v[0:3], v[234:237], v[218:221], v[0:3]
	v_mfma_f32_16x16x32_bf16 v[56:59], v[230:233], v[174:177], v[56:59]
	v_mfma_f32_16x16x32_bf16 v[48:51], v[238:241], v[174:177], v[48:51]
	v_mfma_f32_16x16x32_bf16 v[40:43], v[230:233], v[182:185], v[40:43]
	v_mfma_f32_16x16x32_bf16 v[32:35], v[238:241], v[182:185], v[32:35]
	v_mfma_f32_16x16x32_bf16 v[24:27], v[230:233], v[214:217], v[24:27]
	v_mfma_f32_16x16x32_bf16 v[16:19], v[238:241], v[214:217], v[16:19]
	v_mfma_f32_16x16x32_bf16 v[8:11], v[230:233], v[222:225], v[8:11]
	v_mfma_f32_16x16x32_bf16 v[0:3], v[238:241], v[222:225], v[0:3]
	s_add_i32 s60, s60, 2
	s_add_u32 s18, s18, 0x100
	s_addc_u32 s19, s19, 0
	s_add_u32 s58, s58, 0x100
	s_addc_u32 s59, s59, 0
	s_cmp_gt_u32 s60, 13
	s_barrier
	s_cbranch_scc0 .LBB0_997
	v_mul_f32_e32 v159, 0xbfb8aa3b, v124
	v_exp_f32_e32 v159, v159
	v_lshl_add_u32 v158, s16, 8, v154
	v_lshl_or_b32 v152, s39, 7, v156
	v_ashrrev_i32_e32 v153, 31, v152
	v_add_f32_e32 v159, 1.0, v159
	v_rcp_f32_e32 v159, v159
	v_mov_b64_e32 v[150:151], s[0:1]
	v_mad_i64_i32 v[160:161], s[12:13], v158, s52, v[150:151]
	v_mul_f32_e32 v124, v124, v159
	v_mul_f32_e32 v120, v124, v120
	v_mul_f32_e32 v124, 0xbfb8aa3b, v125
	v_exp_f32_e32 v124, v124
	v_lshlrev_b64 v[152:153], 1, v[152:153]
	v_lshl_add_u64 v[160:161], v[160:161], 0, v[152:153]
	s_and_b64 vcc, exec, s[2:3]
	v_add_f32_e32 v124, 1.0, v124
	v_rcp_f32_e32 v124, v124
	s_mov_b32 s39, s4
	s_mov_b32 s16, s6
	s_mov_b64 s[20:21], s[14:15]
	v_mul_f32_e32 v124, v125, v124
	v_mul_f32_e32 v121, v124, v121
	v_cvt_pk_bf16_f32 v120, v120, v121
	v_mul_f32_e32 v121, 0xbfb8aa3b, v126
	v_exp_f32_e32 v121, v121
	s_mov_b64 s[18:19], s[8:9]
	v_add_f32_e32 v121, 1.0, v121
	v_rcp_f32_e32 v121, v121
	s_nop 0
	v_mul_f32_e32 v121, v126, v121
	v_mul_f32_e32 v121, v121, v122
	v_mul_f32_e32 v122, 0xbfb8aa3b, v127
	v_exp_f32_e32 v122, v122
	s_nop 0
	v_add_f32_e32 v122, 1.0, v122
	v_rcp_f32_e32 v122, v122
	s_nop 0
	v_mul_f32_e32 v122, v127, v122
	v_mul_f32_e32 v122, v122, v123
	v_cvt_pk_bf16_f32 v121, v121, v122
	v_mul_f32_e32 v122, 0xbfb8aa3b, v116
	v_exp_f32_e32 v122, v122
	s_nop 0
	v_add_f32_e32 v122, 1.0, v122
	v_rcp_f32_e32 v122, v122
	s_nop 0
	v_mul_f32_e32 v116, v116, v122
	v_mul_f32_e32 v112, v116, v112
	v_mul_f32_e32 v116, 0xbfb8aa3b, v117
	v_exp_f32_e32 v116, v116
	s_nop 0
	v_add_f32_e32 v116, 1.0, v116
	v_rcp_f32_e32 v116, v116
	s_nop 0
	v_mul_f32_e32 v116, v117, v116
	v_mul_f32_e32 v113, v116, v113
	v_cvt_pk_bf16_f32 v122, v112, v113
	v_mul_f32_e32 v112, 0xbfb8aa3b, v118
	v_exp_f32_e32 v112, v112
	v_mul_f32_e32 v113, 0xbfb8aa3b, v119
	v_exp_f32_e32 v113, v113
	v_add_f32_e32 v112, 1.0, v112
	v_rcp_f32_e32 v112, v112
	v_add_f32_e32 v113, 1.0, v113
	v_rcp_f32_e32 v113, v113
	v_mul_f32_e32 v112, v118, v112
	v_mul_f32_e32 v112, v112, v114
	v_mul_f32_e32 v114, 0xbfb8aa3b, v108
	v_exp_f32_e32 v114, v114
	v_mul_f32_e32 v113, v119, v113
	v_mul_f32_e32 v113, v113, v115
	v_cvt_pk_bf16_f32 v123, v112, v113
	v_add_f32_e32 v114, 1.0, v114
	v_rcp_f32_e32 v114, v114
	v_or_b32_e32 v112, 16, v158
	v_mad_i64_i32 v[112:113], s[12:13], v112, s52, v[150:151]
	v_mul_f32_e32 v108, v108, v114
	v_mul_f32_e32 v104, v108, v104
	v_mul_f32_e32 v108, 0xbfb8aa3b, v109
	v_exp_f32_e32 v108, v108
	v_lshl_add_u64 v[112:113], v[112:113], 0, v[152:153]
	global_store_dwordx4 v[160:161], v[120:123], off
	v_add_f32_e32 v108, 1.0, v108
	v_rcp_f32_e32 v108, v108
	s_nop 0
	v_mul_f32_e32 v108, v109, v108
	v_mul_f32_e32 v105, v108, v105
	v_cvt_pk_bf16_f32 v104, v104, v105
	v_mul_f32_e32 v105, 0xbfb8aa3b, v110
	v_exp_f32_e32 v105, v105
	s_nop 0
	v_add_f32_e32 v105, 1.0, v105
	v_rcp_f32_e32 v105, v105
	s_nop 0
	v_mul_f32_e32 v105, v110, v105
;   __device__ __forceinline__ bf16* y() const { unsigned o_ = (unsigned)(OFF_y); asm volatile("" : "+s"(o_)); return (bf16*)(ws + o_); }
; __device__ __forceinline__ unsigned pk2(float a, float b) { unsigned r; asm("v_cvt_pk_bf16_f32 %0, %1, %2" : "=v"(r) : "v"(a), "v"(b)); return r; }
; __device__ __forceinline__ float silu(float x) { return x * sigm(x); }
;   __device__ __forceinline__ void operator()(const f32x4 (&acc)[2][2][4][2], const pg8::Unit& u, int wr, int wc, int fr, int fq) const {
;     const int row0 = u.pm * 256 + wr * 64 + fr, col0 = u.pn * 128 + wc * 32 + 8 * fq;
; #pragma unroll
;     for (int ai = 0; ai < 2; ++ai)
; #pragma unroll
;       for (int m = 0; m < 4; ++m) {
;         bf16* rowp = O + (size_t)(row0 + ai * 128 + m * 16) * FF + col0;
;         const f32x4 g0 = acc[ai][0][m][0], g1 = acc[ai][0][m][1], u0 = acc[ai][1][m][0], u1 = acc[ai][1][m][1];
;         uint4 o;
;         o.x = pk2(silu(g0[0]) * u0[0], silu(g0[1]) * u0[1]); o.y = pk2(silu(g0[2]) * u0[2], silu(g0[3]) * u0[3]);
;         o.z = pk2(silu(g1[0]) * u1[0], silu(g1[1]) * u1[1]); o.w = pk2(silu(g1[2]) * u1[2], silu(g1[3]) * u1[3]);
;         *(uint4*)rowp = o;
;       }
	v_mul_f32_e32 v105, v105, v106
	v_mul_f32_e32 v106, 0xbfb8aa3b, v111
	v_exp_f32_e32 v106, v106
	s_nop 0
	v_add_f32_e32 v106, 1.0, v106
	v_rcp_f32_e32 v106, v106
	s_nop 0
	v_mul_f32_e32 v106, v111, v106
	v_mul_f32_e32 v106, v106, v107
	v_cvt_pk_bf16_f32 v105, v105, v106
	v_mul_f32_e32 v106, 0xbfb8aa3b, v100
	v_exp_f32_e32 v106, v106
	s_nop 0
	v_add_f32_e32 v106, 1.0, v106
	v_rcp_f32_e32 v106, v106
	s_nop 0
	v_mul_f32_e32 v100, v100, v106
	v_mul_f32_e32 v96, v100, v96
	v_mul_f32_e32 v100, 0xbfb8aa3b, v101
	v_exp_f32_e32 v100, v100
	s_nop 0
	v_add_f32_e32 v100, 1.0, v100
	v_rcp_f32_e32 v100, v100
	s_nop 0
	v_mul_f32_e32 v100, v101, v100
	v_mul_f32_e32 v97, v100, v97
	v_cvt_pk_bf16_f32 v106, v96, v97
	v_mul_f32_e32 v96, 0xbfb8aa3b, v102
	v_exp_f32_e32 v96, v96
	v_mul_f32_e32 v97, 0xbfb8aa3b, v103
	v_exp_f32_e32 v97, v97
	v_add_f32_e32 v96, 1.0, v96
	v_rcp_f32_e32 v96, v96
	v_add_f32_e32 v97, 1.0, v97
	v_rcp_f32_e32 v97, v97
	v_mul_f32_e32 v96, v102, v96
	v_mul_f32_e32 v96, v96, v98
	v_mul_f32_e32 v98, 0xbfb8aa3b, v92
	v_exp_f32_e32 v98, v98
	v_mul_f32_e32 v97, v103, v97
	v_mul_f32_e32 v97, v97, v99
	v_cvt_pk_bf16_f32 v107, v96, v97
	v_add_f32_e32 v98, 1.0, v98
	v_rcp_f32_e32 v98, v98
	v_or_b32_e32 v96, 32, v158
	v_mad_i64_i32 v[96:97], s[12:13], v96, s52, v[150:151]
	v_mul_f32_e32 v92, v92, v98
	v_mul_f32_e32 v88, v92, v88
	v_mul_f32_e32 v92, 0xbfb8aa3b, v93
	v_exp_f32_e32 v92, v92
	v_lshl_add_u64 v[96:97], v[96:97], 0, v[152:153]
	global_store_dwordx4 v[112:113], v[104:107], off
	v_add_f32_e32 v92, 1.0, v92
	v_rcp_f32_e32 v92, v92
	s_nop 0
	v_mul_f32_e32 v92, v93, v92
	v_mul_f32_e32 v89, v92, v89
	v_cvt_pk_bf16_f32 v88, v88, v89
	v_mul_f32_e32 v89, 0xbfb8aa3b, v94
	v_exp_f32_e32 v89, v89
	s_nop 0
	v_add_f32_e32 v89, 1.0, v89
	v_rcp_f32_e32 v89, v89
	s_nop 0
	v_mul_f32_e32 v89, v94, v89
	v_mul_f32_e32 v89, v89, v90
	v_mul_f32_e32 v90, 0xbfb8aa3b, v95
	v_exp_f32_e32 v90, v90
	s_nop 0
	v_add_f32_e32 v90, 1.0, v90
	v_rcp_f32_e32 v90, v90
	s_nop 0
	v_mul_f32_e32 v90, v95, v90
	v_mul_f32_e32 v90, v90, v91
	v_cvt_pk_bf16_f32 v89, v89, v90
	v_mul_f32_e32 v90, 0xbfb8aa3b, v84
	v_exp_f32_e32 v90, v90
	s_nop 0
	v_add_f32_e32 v90, 1.0, v90
	v_rcp_f32_e32 v90, v90
	s_nop 0
	v_mul_f32_e32 v84, v84, v90
	v_mul_f32_e32 v80, v84, v80
	v_mul_f32_e32 v84, 0xbfb8aa3b, v85
	v_exp_f32_e32 v84, v84
	s_nop 0
	v_add_f32_e32 v84, 1.0, v84
	v_rcp_f32_e32 v84, v84
	s_nop 0
	v_mul_f32_e32 v84, v85, v84
	v_mul_f32_e32 v81, v84, v81
	v_cvt_pk_bf16_f32 v90, v80, v81
	v_mul_f32_e32 v80, 0xbfb8aa3b, v86
	v_exp_f32_e32 v80, v80
	v_mul_f32_e32 v81, 0xbfb8aa3b, v87
	v_exp_f32_e32 v81, v81
	v_add_f32_e32 v80, 1.0, v80
	v_rcp_f32_e32 v80, v80
	v_add_f32_e32 v81, 1.0, v81
	v_rcp_f32_e32 v81, v81
	v_mul_f32_e32 v80, v86, v80
	v_mul_f32_e32 v80, v80, v82
	v_mul_f32_e32 v82, 0xbfb8aa3b, v76
	v_exp_f32_e32 v82, v82
	v_mul_f32_e32 v81, v87, v81
	v_mul_f32_e32 v81, v81, v83
	v_cvt_pk_bf16_f32 v91, v80, v81
	v_add_f32_e32 v82, 1.0, v82
	v_rcp_f32_e32 v82, v82
	v_or_b32_e32 v80, 48, v158
	v_mad_i64_i32 v[80:81], s[12:13], v80, s52, v[150:151]
	v_mul_f32_e32 v76, v76, v82
	v_mul_f32_e32 v72, v76, v72
	v_mul_f32_e32 v76, 0xbfb8aa3b, v77
	v_exp_f32_e32 v76, v76
	v_lshl_add_u64 v[80:81], v[80:81], 0, v[152:153]
	global_store_dwordx4 v[96:97], v[88:91], off
	v_add_f32_e32 v76, 1.0, v76
	v_rcp_f32_e32 v76, v76
	s_nop 0
	v_mul_f32_e32 v76, v77, v76
	v_mul_f32_e32 v73, v76, v73
	v_cvt_pk_bf16_f32 v72, v72, v73
	v_mul_f32_e32 v73, 0xbfb8aa3b, v78
	v_exp_f32_e32 v73, v73
	s_nop 0
	v_add_f32_e32 v73, 1.0, v73
	v_rcp_f32_e32 v73, v73
	s_nop 0
	v_mul_f32_e32 v73, v78, v73
	v_mul_f32_e32 v73, v73, v74
	v_mul_f32_e32 v74, 0xbfb8aa3b, v79
	v_exp_f32_e32 v74, v74
	s_nop 0
	v_add_f32_e32 v74, 1.0, v74
	v_rcp_f32_e32 v74, v74
	s_nop 0
	v_mul_f32_e32 v74, v79, v74
	v_mul_f32_e32 v74, v74, v75
	v_cvt_pk_bf16_f32 v73, v73, v74
	v_mul_f32_e32 v74, 0xbfb8aa3b, v68
	v_exp_f32_e32 v74, v74
	s_nop 0
	v_add_f32_e32 v74, 1.0, v74
	v_rcp_f32_e32 v74, v74
	s_nop 0
	v_mul_f32_e32 v68, v68, v74
	v_mul_f32_e32 v64, v68, v64
	v_mul_f32_e32 v68, 0xbfb8aa3b, v69
	v_exp_f32_e32 v68, v68
	s_nop 0
	v_add_f32_e32 v68, 1.0, v68
	v_rcp_f32_e32 v68, v68
	s_nop 0
	v_mul_f32_e32 v68, v69, v68
	v_mul_f32_e32 v65, v68, v65
	v_cvt_pk_bf16_f32 v74, v64, v65
	v_mul_f32_e32 v64, 0xbfb8aa3b, v70
	v_exp_f32_e32 v64, v64
	v_mul_f32_e32 v65, 0xbfb8aa3b, v71
	v_exp_f32_e32 v65, v65
	v_add_f32_e32 v64, 1.0, v64
	v_rcp_f32_e32 v64, v64
	v_add_f32_e32 v65, 1.0, v65
	v_rcp_f32_e32 v65, v65
	v_mul_f32_e32 v64, v70, v64
	v_mul_f32_e32 v64, v64, v66
	v_mul_f32_e32 v66, 0xbfb8aa3b, v60
	v_exp_f32_e32 v66, v66
	v_mul_f32_e32 v65, v71, v65
	v_mul_f32_e32 v65, v65, v67
	v_cvt_pk_bf16_f32 v75, v64, v65
	v_add_f32_e32 v66, 1.0, v66
	v_rcp_f32_e32 v66, v66
	v_add_u32_e32 v64, 0x80, v158
	v_mad_i64_i32 v[64:65], s[12:13], v64, s52, v[150:151]
	v_mul_f32_e32 v60, v60, v66
	v_mul_f32_e32 v56, v60, v56
	v_mul_f32_e32 v60, 0xbfb8aa3b, v61
	v_exp_f32_e32 v60, v60
	v_lshl_add_u64 v[64:65], v[64:65], 0, v[152:153]
	global_store_dwordx4 v[80:81], v[72:75], off
	v_add_f32_e32 v60, 1.0, v60
	v_rcp_f32_e32 v60, v60
	s_nop 0
	v_mul_f32_e32 v60, v61, v60
	v_mul_f32_e32 v57, v60, v57
	v_cvt_pk_bf16_f32 v56, v56, v57
	v_mul_f32_e32 v57, 0xbfb8aa3b, v62
	v_exp_f32_e32 v57, v57
	s_nop 0
	v_add_f32_e32 v57, 1.0, v57
	v_rcp_f32_e32 v57, v57
	s_nop 0
	v_mul_f32_e32 v57, v62, v57
	v_mul_f32_e32 v57, v57, v58
	v_mul_f32_e32 v58, 0xbfb8aa3b, v63
	v_exp_f32_e32 v58, v58
	s_nop 0
	v_add_f32_e32 v58, 1.0, v58
	v_rcp_f32_e32 v58, v58
	s_nop 0
	v_mul_f32_e32 v58, v63, v58
	v_mul_f32_e32 v58, v58, v59
	v_cvt_pk_bf16_f32 v57, v57, v58
	v_mul_f32_e32 v58, 0xbfb8aa3b, v52
	v_exp_f32_e32 v58, v58
;   __device__ __forceinline__ bf16* y() const { unsigned o_ = (unsigned)(OFF_y); asm volatile("" : "+s"(o_)); return (bf16*)(ws + o_); }
; __device__ __forceinline__ unsigned pk2(float a, float b) { unsigned r; asm("v_cvt_pk_bf16_f32 %0, %1, %2" : "=v"(r) : "v"(a), "v"(b)); return r; }
; __device__ __forceinline__ float silu(float x) { return x * sigm(x); }
; #define PG8_WAIT_V(n) asm volatile("s_waitcnt vmcnt(" #n ")" ::: "memory")
; #define PG8_BAR __builtin_amdgcn_s_barrier()
; template <class Epi, class Sched>
; __device__ __forceinline__ void gemm_phase(PG8_LAS unsigned char* lds, const Gemm g, const Sched& S, const Epi& E) {
;     ...
;         if (!has_next) break;
; #pragma unroll
;         for (int a = 0; a < 2; ++a)
; #pragma unroll
;             for (int b = 0; b < 2; ++b)
; #pragma unroll
;                 for (int m = 0; m < 4; ++m)
; #pragma unroll
;                     for (int n = 0; n < 2; ++n) acc[a][b][m][n] = (f32x4){0.f, 0.f, 0.f, 0.f};
;         cur = nxt; cA = nA; cB = nB; ++ui;
;     }
;     PG8_WAIT_V(0);
;     if (wr == 0) PG8_BAR;
;     PG8_BAR;
;   __device__ __forceinline__ void operator()(const f32x4 (&acc)[2][2][4][2], const pg8::Unit& u, int wr, int wc, int fr, int fq) const {
;     const int row0 = u.pm * 256 + wr * 64 + fr, col0 = u.pn * 128 + wc * 32 + 8 * fq;
; #pragma unroll
;     for (int ai = 0; ai < 2; ++ai)
; #pragma unroll
;       for (int m = 0; m < 4; ++m) {
;         bf16* rowp = O + (size_t)(row0 + ai * 128 + m * 16) * FF + col0;
;         const f32x4 g0 = acc[ai][0][m][0], g1 = acc[ai][0][m][1], u0 = acc[ai][1][m][0], u1 = acc[ai][1][m][1];
;         uint4 o;
;         o.x = pk2(silu(g0[0]) * u0[0], silu(g0[1]) * u0[1]); o.y = pk2(silu(g0[2]) * u0[2], silu(g0[3]) * u0[3]);
;         o.z = pk2(silu(g1[0]) * u1[0], silu(g1[1]) * u1[1]); o.w = pk2(silu(g1[2]) * u1[2], silu(g1[3]) * u1[3]);
;         *(uint4*)rowp = o;
;       }
	s_nop 0
	v_add_f32_e32 v58, 1.0, v58
	v_rcp_f32_e32 v58, v58
	s_nop 0
	v_mul_f32_e32 v52, v52, v58
	v_mul_f32_e32 v48, v52, v48
	v_mul_f32_e32 v52, 0xbfb8aa3b, v53
	v_exp_f32_e32 v52, v52
	s_nop 0
	v_add_f32_e32 v52, 1.0, v52
	v_rcp_f32_e32 v52, v52
	s_nop 0
	v_mul_f32_e32 v52, v53, v52
	v_mul_f32_e32 v49, v52, v49
	v_cvt_pk_bf16_f32 v58, v48, v49
	v_mul_f32_e32 v48, 0xbfb8aa3b, v54
	v_exp_f32_e32 v48, v48
	v_mul_f32_e32 v49, 0xbfb8aa3b, v55
	v_exp_f32_e32 v49, v49
	v_add_f32_e32 v48, 1.0, v48
	v_rcp_f32_e32 v48, v48
	v_add_f32_e32 v49, 1.0, v49
	v_rcp_f32_e32 v49, v49
	v_mul_f32_e32 v48, v54, v48
	v_mul_f32_e32 v48, v48, v50
	v_mul_f32_e32 v50, 0xbfb8aa3b, v44
	v_exp_f32_e32 v50, v50
	v_mul_f32_e32 v49, v55, v49
	v_mul_f32_e32 v49, v49, v51
	v_cvt_pk_bf16_f32 v59, v48, v49
	v_add_f32_e32 v50, 1.0, v50
	v_rcp_f32_e32 v50, v50
	v_add_u32_e32 v48, 0x90, v158
	v_mad_i64_i32 v[48:49], s[12:13], v48, s52, v[150:151]
	v_mul_f32_e32 v44, v44, v50
	v_mul_f32_e32 v40, v44, v40
	v_mul_f32_e32 v44, 0xbfb8aa3b, v45
	v_exp_f32_e32 v44, v44
	v_lshl_add_u64 v[48:49], v[48:49], 0, v[152:153]
	global_store_dwordx4 v[64:65], v[56:59], off
	v_add_f32_e32 v44, 1.0, v44
	v_rcp_f32_e32 v44, v44
	s_nop 0
	v_mul_f32_e32 v44, v45, v44
	v_mul_f32_e32 v41, v44, v41
	v_cvt_pk_bf16_f32 v40, v40, v41
	v_mul_f32_e32 v41, 0xbfb8aa3b, v46
	v_exp_f32_e32 v41, v41
	s_nop 0
	v_add_f32_e32 v41, 1.0, v41
	v_rcp_f32_e32 v41, v41
	s_nop 0
	v_mul_f32_e32 v41, v46, v41
	v_mul_f32_e32 v41, v41, v42
	v_mul_f32_e32 v42, 0xbfb8aa3b, v47
	v_exp_f32_e32 v42, v42
	s_nop 0
	v_add_f32_e32 v42, 1.0, v42
	v_rcp_f32_e32 v42, v42
	s_nop 0
	v_mul_f32_e32 v42, v47, v42
	v_mul_f32_e32 v42, v42, v43
	v_cvt_pk_bf16_f32 v41, v41, v42
	v_mul_f32_e32 v42, 0xbfb8aa3b, v36
	v_exp_f32_e32 v42, v42
	s_nop 0
	v_add_f32_e32 v42, 1.0, v42
	v_rcp_f32_e32 v42, v42
	s_nop 0
	v_mul_f32_e32 v36, v36, v42
	v_mul_f32_e32 v32, v36, v32
	v_mul_f32_e32 v36, 0xbfb8aa3b, v37
	v_exp_f32_e32 v36, v36
	s_nop 0
	v_add_f32_e32 v36, 1.0, v36
	v_rcp_f32_e32 v36, v36
	s_nop 0
	v_mul_f32_e32 v36, v37, v36
	v_mul_f32_e32 v33, v36, v33
	v_cvt_pk_bf16_f32 v42, v32, v33
	v_mul_f32_e32 v32, 0xbfb8aa3b, v38
	v_exp_f32_e32 v32, v32
	v_mul_f32_e32 v33, 0xbfb8aa3b, v39
	v_exp_f32_e32 v33, v33
	v_add_f32_e32 v32, 1.0, v32
	v_rcp_f32_e32 v32, v32
	v_add_f32_e32 v33, 1.0, v33
	v_rcp_f32_e32 v33, v33
	v_mul_f32_e32 v32, v38, v32
	v_mul_f32_e32 v32, v32, v34
	v_mul_f32_e32 v34, 0xbfb8aa3b, v28
	v_exp_f32_e32 v34, v34
	v_mul_f32_e32 v33, v39, v33
	v_mul_f32_e32 v33, v33, v35
	v_cvt_pk_bf16_f32 v43, v32, v33
	v_add_f32_e32 v34, 1.0, v34
	v_rcp_f32_e32 v34, v34
	v_add_u32_e32 v32, 0xa0, v158
	v_mad_i64_i32 v[32:33], s[12:13], v32, s52, v[150:151]
	v_mul_f32_e32 v28, v28, v34
	v_mul_f32_e32 v24, v28, v24
	v_mul_f32_e32 v28, 0xbfb8aa3b, v29
	v_exp_f32_e32 v28, v28
	v_lshl_add_u64 v[32:33], v[32:33], 0, v[152:153]
	global_store_dwordx4 v[48:49], v[40:43], off
	v_add_f32_e32 v28, 1.0, v28
	v_rcp_f32_e32 v28, v28
	s_nop 0
	v_mul_f32_e32 v28, v29, v28
	v_mul_f32_e32 v25, v28, v25
	v_cvt_pk_bf16_f32 v24, v24, v25
	v_mul_f32_e32 v25, 0xbfb8aa3b, v30
	v_exp_f32_e32 v25, v25
	s_nop 0
	v_add_f32_e32 v25, 1.0, v25
	v_rcp_f32_e32 v25, v25
	s_nop 0
	v_mul_f32_e32 v25, v30, v25
	v_mul_f32_e32 v25, v25, v26
	v_mul_f32_e32 v26, 0xbfb8aa3b, v31
	v_exp_f32_e32 v26, v26
	s_nop 0
	v_add_f32_e32 v26, 1.0, v26
	v_rcp_f32_e32 v26, v26
	s_nop 0
	v_mul_f32_e32 v26, v31, v26
	v_mul_f32_e32 v26, v26, v27
	v_cvt_pk_bf16_f32 v25, v25, v26
	v_mul_f32_e32 v26, 0xbfb8aa3b, v20
	v_exp_f32_e32 v26, v26
	s_nop 0
	v_add_f32_e32 v26, 1.0, v26
	v_rcp_f32_e32 v26, v26
	s_nop 0
	v_mul_f32_e32 v20, v20, v26
	v_mul_f32_e32 v16, v20, v16
	v_mul_f32_e32 v20, 0xbfb8aa3b, v21
	v_exp_f32_e32 v20, v20
	s_nop 0
	v_add_f32_e32 v20, 1.0, v20
	v_rcp_f32_e32 v20, v20
	s_nop 0
	v_mul_f32_e32 v20, v21, v20
	v_mul_f32_e32 v17, v20, v17
	v_cvt_pk_bf16_f32 v26, v16, v17
	v_mul_f32_e32 v16, 0xbfb8aa3b, v22
	v_exp_f32_e32 v16, v16
	v_mul_f32_e32 v17, 0xbfb8aa3b, v23
	v_exp_f32_e32 v17, v17
	v_add_f32_e32 v16, 1.0, v16
	v_rcp_f32_e32 v16, v16
	v_add_f32_e32 v17, 1.0, v17
	v_rcp_f32_e32 v17, v17
	v_mul_f32_e32 v16, v22, v16
	v_mul_f32_e32 v16, v16, v18
	v_mul_f32_e32 v18, 0xbfb8aa3b, v12
	v_exp_f32_e32 v18, v18
	v_mul_f32_e32 v17, v23, v17
	v_mul_f32_e32 v17, v17, v19
	v_cvt_pk_bf16_f32 v27, v16, v17
	v_add_f32_e32 v18, 1.0, v18
	v_rcp_f32_e32 v18, v18
	v_add_u32_e32 v16, 0xb0, v158
	v_mad_i64_i32 v[16:17], s[12:13], v16, s52, v[150:151]
	v_mul_f32_e32 v12, v12, v18
	v_mul_f32_e32 v8, v12, v8
	v_mul_f32_e32 v12, 0xbfb8aa3b, v13
	v_exp_f32_e32 v12, v12
	v_lshl_add_u64 v[16:17], v[16:17], 0, v[152:153]
	global_store_dwordx4 v[32:33], v[24:27], off
	v_add_f32_e32 v12, 1.0, v12
	v_rcp_f32_e32 v12, v12
	s_nop 0
	v_mul_f32_e32 v12, v13, v12
	v_mul_f32_e32 v9, v12, v9
	v_cvt_pk_bf16_f32 v8, v8, v9
	v_mul_f32_e32 v9, 0xbfb8aa3b, v14
	v_exp_f32_e32 v9, v9
	s_nop 0
	v_add_f32_e32 v9, 1.0, v9
	v_rcp_f32_e32 v9, v9
	s_nop 0
	v_mul_f32_e32 v9, v14, v9
	v_mul_f32_e32 v9, v9, v10
	v_mul_f32_e32 v10, 0xbfb8aa3b, v15
	v_exp_f32_e32 v10, v10
	s_nop 0
	v_add_f32_e32 v10, 1.0, v10
	v_rcp_f32_e32 v10, v10
	s_nop 0
	v_mul_f32_e32 v10, v15, v10
	v_mul_f32_e32 v10, v10, v11
	v_cvt_pk_bf16_f32 v9, v9, v10
	v_mul_f32_e32 v10, 0xbfb8aa3b, v4
	v_exp_f32_e32 v10, v10
	s_nop 0
	v_add_f32_e32 v10, 1.0, v10
	v_rcp_f32_e32 v10, v10
	s_nop 0
	v_mul_f32_e32 v4, v4, v10
	v_mul_f32_e32 v0, v4, v0
	v_mul_f32_e32 v4, 0xbfb8aa3b, v5
	v_exp_f32_e32 v4, v4
	s_nop 0
	v_add_f32_e32 v4, 1.0, v4
	v_rcp_f32_e32 v4, v4
	s_nop 0
	v_mul_f32_e32 v4, v5, v4
	v_mul_f32_e32 v1, v4, v1
	v_cvt_pk_bf16_f32 v10, v0, v1
	v_mul_f32_e32 v0, 0xbfb8aa3b, v6
	v_mul_f32_e32 v1, 0xbfb8aa3b, v7
	v_exp_f32_e32 v0, v0
	v_exp_f32_e32 v1, v1
	v_add_f32_e32 v0, 1.0, v0
	v_add_f32_e32 v1, 1.0, v1
	v_rcp_f32_e32 v0, v0
	v_rcp_f32_e32 v1, v1
	v_mul_f32_e32 v0, v6, v0
	v_mul_f32_e32 v1, v7, v1
	v_mul_f32_e32 v0, v0, v2
	v_mul_f32_e32 v1, v1, v3
	v_cvt_pk_bf16_f32 v11, v0, v1
	global_store_dwordx4 v[16:17], v[8:11], off
	s_cbranch_vccz .LBB0_990
	s_waitcnt vmcnt(0)
	s_cmpk_gt_u32 s25, 0xff
	s_cbranch_scc1 .LBB0_1001
	s_barrier

; #define PG8_STAGE(bufoff, gbase, voff) do { _Pragma("unroll") for (int _i = 0; _i < 2; ++_i) \
;         __builtin_amdgcn_global_load_lds((const unsigned*)((const char*)(gbase) + (voff)[_i]), (PG8_LAS unsigned*)(lds + (bufoff) + ldsw + _i * 8192), 16, 0, 0); } while (0)
; #define PG8_LDA(dst, b, h) do { _Pragma("unroll") for (int m = 0; m < 4; ++m) _Pragma("unroll") for (int k = 0; k < 2; ++k) dst[m][k] = *(const PG8_LAS bf16x8*)(lds + PG8_SA(b, h) + aoff + m * 2048 + k * 1024); } while (0)
; #define PG8_LDB(dst, b, h) do { _Pragma("unroll") for (int n = 0; n < 2; ++n) _Pragma("unroll") for (int k = 0; k < 2; ++k) dst[n][k] = *(const PG8_LAS bf16x8*)(lds + PG8_SB(b, h) + boff + n * 2048 + k * 1024); } while (0)
; #define PG8_WAIT_V(n) asm volatile("s_waitcnt vmcnt(" #n ")" ::: "memory")
; #define PG8_BAR __builtin_amdgcn_s_barrier()
; template <class Epi, class Sched>
; __device__ __forceinline__ void gemm_phase(PG8_LAS unsigned char* lds, const Gemm g, const Sched& S, const Epi& E) {
;     ...
;         for (int t = 0; t < nt; t += 2) {
;             const bool last = (t == nt - 2);
;             const char* a1 = cA + (size_t)(t + 1) * kstep;
;             const char* a2 = last ? nA : cA + (size_t)(t + 2) * kstep; const char* b2 = last ? nB : cB + (size_t)(t + 2) * kstep;
;             const char* a3 = a2 + kstep; const char* b3 = b2 + kstep;
;             if (last && has_next) S.a_ready(nxt);
;             PG8_LDB(B0, 0, 0); PG8_SCHED; PG8_LDA(At, 0, 0); PG8_STAGE(PG8_SA(1, 1), a1 + hstep, voffA);
;             PG8_WAIT_L(8); PG8_BAR; PG8_WAIT_L(0); PG8_MMA(0, 0, At, B0); PG8_BAR; PG8_SCHED;
;             PG8_LDB(B1, 0, 1); PG8_STAGE(PG8_SB(0, 0), b2, voffB);
;             PG8_BAR; PG8_WAIT_L(0); PG8_MMA(0, 1, At, B1); PG8_BAR;
;             PG8_LDA(At, 0, 1); PG8_STAGE(PG8_SA(0, 0), a2, voffA);
;             PG8_BAR; PG8_WAIT_L(0); PG8_MMA(1, 0, At, B0); PG8_BAR; PG8_SCHED;
;             PG8_STAGE(PG8_SB(0, 1), b2 + hstep, voffB);
;             PG8_WAIT_V(6); PG8_BAR; PG8_MMA(1, 1, At, B1); PG8_BAR;
;             PG8_LDB(B0, 1, 0); PG8_SCHED; PG8_LDA(At, 1, 0); PG8_STAGE(PG8_SA(0, 1), a2 + hstep, voffA);
;             PG8_WAIT_L(8); PG8_BAR; PG8_WAIT_L(0); PG8_MMA(0, 0, At, B0); PG8_BAR; PG8_SCHED;
;             PG8_LDB(B1, 1, 1); PG8_STAGE(PG8_SB(1, 0), b3, voffB);
;             PG8_BAR; PG8_WAIT_L(0); PG8_MMA(0, 1, At, B1); PG8_BAR;
.LBB0_1074:
	s_add_u32 s12, s8, s20
	s_addc_u32 s13, s9, s21
	s_add_u32 s12, s12, 0x100
	s_addc_u32 s13, s13, 0
	s_add_u32 s22, s68, s20
	s_addc_u32 s23, s82, s21
	s_add_i32 s69, s46, 0x100
	v_add_u32_e32 v159, s69, v155
	ds_read_b128 v[160:163], v159
	ds_read_b128 v[164:167], v159 offset:1024
	ds_read_b128 v[168:171], v159 offset:2048
	ds_read_b128 v[172:175], v159 offset:3072
	s_cmpk_eq_i32 s20, 0x1500
	s_cselect_b32 s25, s19, s13
	s_cselect_b32 s24, s18, s12
	s_cselect_b32 s23, s7, s23
	s_cselect_b32 s22, s6, s22
	v_lshl_add_u64 v[230:231], v[150:151], 0, s[20:21]
	s_add_i32 m0, s58, 0xc000
	ds_read_b128 v[176:179], v158
	ds_read_b128 v[180:183], v158 offset:1024
	ds_read_b128 v[184:187], v158 offset:2048
	ds_read_b128 v[210:213], v158 offset:3072
	ds_read_b128 v[214:217], v158 offset:4096
	ds_read_b128 v[218:221], v158 offset:5120
	ds_read_b128 v[222:225], v158 offset:6144
	ds_read_b128 v[226:229], v158 offset:7168
	global_load_lds_dwordx4 v[230:231], off
	v_lshl_add_u64 v[230:231], v[152:153], 0, s[20:21]
	s_add_i32 m0, s58, 0xe000
	s_nop 0
	global_load_lds_dwordx4 v[230:231], off
	s_waitcnt lgkmcnt(8)
	s_barrier
	s_waitcnt lgkmcnt(0)
	v_mfma_f32_16x16x32_bf16 v[124:127], v[160:163], v[176:179], v[124:127]
	v_mfma_f32_16x16x32_bf16 v[120:123], v[168:171], v[176:179], v[120:123]
	v_mfma_f32_16x16x32_bf16 v[116:119], v[160:163], v[184:187], v[116:119]
	v_mfma_f32_16x16x32_bf16 v[112:115], v[168:171], v[184:187], v[112:115]
	v_mfma_f32_16x16x32_bf16 v[108:111], v[160:163], v[214:217], v[108:111]
	v_mfma_f32_16x16x32_bf16 v[104:107], v[168:171], v[214:217], v[104:107]
	v_mfma_f32_16x16x32_bf16 v[100:103], v[160:163], v[222:225], v[100:103]
	v_mfma_f32_16x16x32_bf16 v[96:99], v[168:171], v[222:225], v[96:99]
	v_mfma_f32_16x16x32_bf16 v[124:127], v[164:167], v[180:183], v[124:127]
	v_mfma_f32_16x16x32_bf16 v[120:123], v[172:175], v[180:183], v[120:123]
	v_mfma_f32_16x16x32_bf16 v[116:119], v[164:167], v[210:213], v[116:119]
	v_mfma_f32_16x16x32_bf16 v[112:115], v[172:175], v[210:213], v[112:115]
	v_mfma_f32_16x16x32_bf16 v[108:111], v[164:167], v[218:221], v[108:111]
	v_mfma_f32_16x16x32_bf16 v[104:107], v[172:175], v[218:221], v[104:107]
	v_mfma_f32_16x16x32_bf16 v[100:103], v[164:167], v[226:229], v[100:103]
	v_mfma_f32_16x16x32_bf16 v[96:99], v[172:175], v[226:229], v[96:99]
	s_barrier
	s_add_i32 s84, s48, 0x100
	s_add_i32 s12, s69, s41
	v_add_u32_e32 v159, s84, v155
	v_lshl_add_u64 v[246:247], s[22:23], 0, v[138:139]
	s_mov_b32 m0, s12
	ds_read_b128 v[230:233], v159
	ds_read_b128 v[234:237], v159 offset:1024
	ds_read_b128 v[238:241], v159 offset:2048
	ds_read_b128 v[242:245], v159 offset:3072
	global_load_lds_dwordx4 v[246:247], off
	v_lshl_add_u64 v[248:249], s[22:23], 0, v[132:133]
	s_add_i32 m0, s12, 0x2000
	s_nop 0
	global_load_lds_dwordx4 v[248:249], off
	s_barrier
	s_waitcnt lgkmcnt(0)
	v_mfma_f32_16x16x32_bf16 v[60:63], v[230:233], v[176:179], v[60:63]
	v_mfma_f32_16x16x32_bf16 v[56:59], v[238:241], v[176:179], v[56:59]
	v_mfma_f32_16x16x32_bf16 v[52:55], v[230:233], v[184:187], v[52:55]
	v_mfma_f32_16x16x32_bf16 v[48:51], v[238:241], v[184:187], v[48:51]
	v_mfma_f32_16x16x32_bf16 v[44:47], v[230:233], v[214:217], v[44:47]
	v_mfma_f32_16x16x32_bf16 v[40:43], v[238:241], v[214:217], v[40:43]
	v_mfma_f32_16x16x32_bf16 v[36:39], v[230:233], v[222:225], v[36:39]
	v_mfma_f32_16x16x32_bf16 v[32:35], v[238:241], v[222:225], v[32:35]
	v_mfma_f32_16x16x32_bf16 v[60:63], v[234:237], v[180:183], v[60:63]
	v_mfma_f32_16x16x32_bf16 v[56:59], v[242:245], v[180:183], v[56:59]
	v_mfma_f32_16x16x32_bf16 v[52:55], v[234:237], v[210:213], v[52:55]
	v_mfma_f32_16x16x32_bf16 v[48:51], v[242:245], v[210:213], v[48:51]
	v_mfma_f32_16x16x32_bf16 v[44:47], v[234:237], v[218:221], v[44:47]
	v_mfma_f32_16x16x32_bf16 v[40:43], v[242:245], v[218:221], v[40:43]
	v_mfma_f32_16x16x32_bf16 v[36:39], v[234:237], v[226:229], v[36:39]
	v_mfma_f32_16x16x32_bf16 v[32:35], v[242:245], v[226:229], v[32:35]
	s_mov_b32 m0, s58
	v_lshl_add_u64 v[250:251], s[24:25], 0, v[128:129]
	s_barrier
	ds_read_b128 v[176:179], v158 offset:16384
	ds_read_b128 v[180:183], v158 offset:17408
	ds_read_b128 v[184:187], v158 offset:18432
	ds_read_b128 v[210:213], v158 offset:19456
	ds_read_b128 v[214:217], v158 offset:20480
	ds_read_b128 v[218:221], v158 offset:21504
	ds_read_b128 v[222:225], v158 offset:22528
	ds_read_b128 v[226:229], v158 offset:23552
	global_load_lds_dwordx4 v[250:251], off
	v_lshl_add_u64 v[252:253], s[24:25], 0, v[130:131]
	s_mov_b32 m0, s59
	s_nop 0
	global_load_lds_dwordx4 v[252:253], off
	s_barrier
	s_waitcnt lgkmcnt(0)
	v_mfma_f32_16x16x32_bf16 v[92:95], v[160:163], v[176:179], v[92:95]
	v_mfma_f32_16x16x32_bf16 v[88:91], v[168:171], v[176:179], v[88:91]
	v_mfma_f32_16x16x32_bf16 v[84:87], v[160:163], v[184:187], v[84:87]
	v_mfma_f32_16x16x32_bf16 v[80:83], v[168:171], v[184:187], v[80:83]
	v_mfma_f32_16x16x32_bf16 v[76:79], v[160:163], v[214:217], v[76:79]
	v_mfma_f32_16x16x32_bf16 v[72:75], v[168:171], v[214:217], v[72:75]
	v_mfma_f32_16x16x32_bf16 v[68:71], v[160:163], v[222:225], v[68:71]
	v_mfma_f32_16x16x32_bf16 v[64:67], v[168:171], v[222:225], v[64:67]
	v_mfma_f32_16x16x32_bf16 v[92:95], v[164:167], v[180:183], v[92:95]
	v_mfma_f32_16x16x32_bf16 v[88:91], v[172:175], v[180:183], v[88:91]
	v_mfma_f32_16x16x32_bf16 v[84:87], v[164:167], v[210:213], v[84:87]
	v_mfma_f32_16x16x32_bf16 v[80:83], v[172:175], v[210:213], v[80:83]
	v_mfma_f32_16x16x32_bf16 v[76:79], v[164:167], v[218:221], v[76:79]
	v_mfma_f32_16x16x32_bf16 v[72:75], v[172:175], v[218:221], v[72:75]
	v_mfma_f32_16x16x32_bf16 v[68:71], v[164:167], v[226:229], v[68:71]
	v_mfma_f32_16x16x32_bf16 v[64:67], v[172:175], v[226:229], v[64:67]
	s_barrier
; #define PG8_STAGE(bufoff, gbase, voff) do { _Pragma("unroll") for (int _i = 0; _i < 2; ++_i) \
;         __builtin_amdgcn_global_load_lds((const unsigned*)((const char*)(gbase) + (voff)[_i]), (PG8_LAS unsigned*)(lds + (bufoff) + ldsw + _i * 8192), 16, 0, 0); } while (0)
; #define PG8_LDA(dst, b, h) do { _Pragma("unroll") for (int m = 0; m < 4; ++m) _Pragma("unroll") for (int k = 0; k < 2; ++k) dst[m][k] = *(const PG8_LAS bf16x8*)(lds + PG8_SA(b, h) + aoff + m * 2048 + k * 1024); } while (0)
; #define PG8_LDB(dst, b, h) do { _Pragma("unroll") for (int n = 0; n < 2; ++n) _Pragma("unroll") for (int k = 0; k < 2; ++k) dst[n][k] = *(const PG8_LAS bf16x8*)(lds + PG8_SB(b, h) + boff + n * 2048 + k * 1024); } while (0)
; #define PG8_MMA(ai, bj, At, Bt) do { __builtin_amdgcn_s_setprio(1); _Pragma("unroll") for (int m = 0; m < 4; ++m) _Pragma("unroll") for (int n = 0; n < 2; ++n) _Pragma("unroll") for (int k = 0; k < 2; ++k) \
;         acc[ai][bj][m][n] = __builtin_amdgcn_mfma_f32_16x16x32_bf16(Bt[n][k], At[m][k], acc[ai][bj][m][n], 0, 0, 0); __builtin_amdgcn_s_setprio(0); } while (0)
; #define PG8_WAIT_V(n) asm volatile("s_waitcnt vmcnt(" #n ")" ::: "memory")
; #define PG8_WAIT_L(n) asm volatile("s_waitcnt lgkmcnt(" #n ")" ::: "memory")
; #define PG8_BAR __builtin_amdgcn_s_barrier()
; #define PG8_SCHED __builtin_amdgcn_sched_barrier(0)
; template <class Epi, class Sched>
; __device__ __forceinline__ void gemm_phase(PG8_LAS unsigned char* lds, const Gemm g, const Sched& S, const Epi& E) {
;     ...
;             PG8_STAGE(PG8_SB(0, 1), b2 + hstep, voffB);
;             PG8_WAIT_V(6); PG8_BAR; PG8_MMA(1, 1, At, B1); PG8_BAR;
;             PG8_LDB(B0, 1, 0); PG8_SCHED; PG8_LDA(At, 1, 0); PG8_STAGE(PG8_SA(0, 1), a2 + hstep, voffA);
;             PG8_WAIT_L(8); PG8_BAR; PG8_WAIT_L(0); PG8_MMA(0, 0, At, B0); PG8_BAR; PG8_SCHED;
;             PG8_LDB(B1, 1, 1); PG8_STAGE(PG8_SB(1, 0), b3, voffB);
;             PG8_BAR; PG8_WAIT_L(0); PG8_MMA(0, 1, At, B1); PG8_BAR;
;             PG8_LDA(At, 1, 1); PG8_STAGE(PG8_SA(1, 0), a3, voffA);
;             PG8_BAR; PG8_WAIT_L(0); PG8_MMA(1, 0, At, B0); PG8_BAR; PG8_SCHED;
	s_add_u32 s12, s22, 0xb0000
	s_addc_u32 s13, s23, 0
	s_add_i32 s69, s84, s41
	v_lshl_add_u64 v[160:161], s[12:13], 0, v[138:139]
	s_mov_b32 m0, s69
	s_nop 0
	global_load_lds_dwordx4 v[160:161], off
	v_lshl_add_u64 v[160:161], s[12:13], 0, v[132:133]
	s_add_i32 m0, s69, 0x2000
	s_nop 0
	global_load_lds_dwordx4 v[160:161], off
	s_waitcnt vmcnt(6)
	s_barrier
	v_mfma_f32_16x16x32_bf16 v[28:31], v[230:233], v[176:179], v[28:31]
	v_mfma_f32_16x16x32_bf16 v[24:27], v[238:241], v[176:179], v[24:27]
	v_mfma_f32_16x16x32_bf16 v[20:23], v[230:233], v[184:187], v[20:23]
	v_mfma_f32_16x16x32_bf16 v[16:19], v[238:241], v[184:187], v[16:19]
	v_mfma_f32_16x16x32_bf16 v[12:15], v[230:233], v[214:217], v[12:15]
	v_mfma_f32_16x16x32_bf16 v[8:11], v[238:241], v[214:217], v[8:11]
	v_mfma_f32_16x16x32_bf16 v[4:7], v[230:233], v[222:225], v[4:7]
	v_mfma_f32_16x16x32_bf16 v[0:3], v[238:241], v[222:225], v[0:3]
	v_mfma_f32_16x16x32_bf16 v[28:31], v[234:237], v[180:183], v[28:31]
	v_mfma_f32_16x16x32_bf16 v[24:27], v[242:245], v[180:183], v[24:27]
	v_mfma_f32_16x16x32_bf16 v[20:23], v[234:237], v[210:213], v[20:23]
	v_mfma_f32_16x16x32_bf16 v[16:19], v[242:245], v[210:213], v[16:19]
	v_mfma_f32_16x16x32_bf16 v[12:15], v[234:237], v[218:221], v[12:15]
	v_mfma_f32_16x16x32_bf16 v[8:11], v[242:245], v[218:221], v[8:11]
	v_mfma_f32_16x16x32_bf16 v[4:7], v[234:237], v[226:229], v[4:7]
	v_mfma_f32_16x16x32_bf16 v[0:3], v[242:245], v[226:229], v[0:3]
	s_add_i32 s69, s51, 0x100
	v_add_u32_e32 v159, s69, v155
	s_barrier
	ds_read_b128 v[160:163], v159
	ds_read_b128 v[164:167], v159 offset:1024
	ds_read_b128 v[168:171], v159 offset:2048
	ds_read_b128 v[172:175], v159 offset:3072
	s_add_u32 s12, s24, 0xb0000
	s_addc_u32 s13, s25, 0
	s_mov_b32 m0, s60
	v_lshl_add_u64 v[230:231], s[12:13], 0, v[128:129]
	ds_read_b128 v[176:179], v158 offset:32768
	ds_read_b128 v[180:183], v158 offset:33792
	ds_read_b128 v[184:187], v158 offset:34816
	ds_read_b128 v[210:213], v158 offset:35840
	ds_read_b128 v[214:217], v158 offset:36864
	ds_read_b128 v[218:221], v158 offset:37888
	ds_read_b128 v[222:225], v158 offset:38912
	ds_read_b128 v[226:229], v158 offset:39936
	global_load_lds_dwordx4 v[230:231], off
	v_lshl_add_u64 v[230:231], s[12:13], 0, v[130:131]
	s_mov_b32 m0, s61
	s_nop 0
	global_load_lds_dwordx4 v[230:231], off
	s_waitcnt lgkmcnt(8)
	s_barrier
	s_waitcnt lgkmcnt(0)
	v_mfma_f32_16x16x32_bf16 v[124:127], v[160:163], v[176:179], v[124:127]
	v_mfma_f32_16x16x32_bf16 v[120:123], v[168:171], v[176:179], v[120:123]
	v_mfma_f32_16x16x32_bf16 v[116:119], v[160:163], v[184:187], v[116:119]
	v_mfma_f32_16x16x32_bf16 v[112:115], v[168:171], v[184:187], v[112:115]
	v_mfma_f32_16x16x32_bf16 v[108:111], v[160:163], v[214:217], v[108:111]
	v_mfma_f32_16x16x32_bf16 v[104:107], v[168:171], v[214:217], v[104:107]
	v_mfma_f32_16x16x32_bf16 v[100:103], v[160:163], v[222:225], v[100:103]
	v_mfma_f32_16x16x32_bf16 v[96:99], v[168:171], v[222:225], v[96:99]
	v_mfma_f32_16x16x32_bf16 v[124:127], v[164:167], v[180:183], v[124:127]
	v_mfma_f32_16x16x32_bf16 v[120:123], v[172:175], v[180:183], v[120:123]
	v_mfma_f32_16x16x32_bf16 v[116:119], v[164:167], v[210:213], v[116:119]
	v_mfma_f32_16x16x32_bf16 v[112:115], v[172:175], v[210:213], v[112:115]
	v_mfma_f32_16x16x32_bf16 v[108:111], v[164:167], v[218:221], v[108:111]
	v_mfma_f32_16x16x32_bf16 v[104:107], v[172:175], v[218:221], v[104:107]
	v_mfma_f32_16x16x32_bf16 v[100:103], v[164:167], v[226:229], v[100:103]
	v_mfma_f32_16x16x32_bf16 v[96:99], v[172:175], v[226:229], v[96:99]
	s_barrier
	s_add_i32 s24, s55, 0x100
	s_add_i32 s12, s69, s41
	v_add_u32_e32 v159, s24, v155
	v_lshl_add_u64 v[246:247], v[246:247], 0, s[94:95]
	s_mov_b32 m0, s12
	ds_read_b128 v[230:233], v159
	ds_read_b128 v[234:237], v159 offset:1024
	ds_read_b128 v[238:241], v159 offset:2048
	ds_read_b128 v[242:245], v159 offset:3072
	global_load_lds_dwordx4 v[246:247], off
	v_lshl_add_u64 v[246:247], v[248:249], 0, s[94:95]
	s_add_i32 m0, s12, 0x2000
	s_nop 0
	global_load_lds_dwordx4 v[246:247], off
	s_barrier
	s_waitcnt lgkmcnt(0)
	v_mfma_f32_16x16x32_bf16 v[60:63], v[230:233], v[176:179], v[60:63]
	v_mfma_f32_16x16x32_bf16 v[56:59], v[238:241], v[176:179], v[56:59]
	v_mfma_f32_16x16x32_bf16 v[52:55], v[230:233], v[184:187], v[52:55]
	v_mfma_f32_16x16x32_bf16 v[48:51], v[238:241], v[184:187], v[48:51]
	v_mfma_f32_16x16x32_bf16 v[44:47], v[230:233], v[214:217], v[44:47]
	v_mfma_f32_16x16x32_bf16 v[40:43], v[238:241], v[214:217], v[40:43]
	v_mfma_f32_16x16x32_bf16 v[36:39], v[230:233], v[222:225], v[36:39]
	v_mfma_f32_16x16x32_bf16 v[32:35], v[238:241], v[222:225], v[32:35]
	v_mfma_f32_16x16x32_bf16 v[60:63], v[234:237], v[180:183], v[60:63]
	v_mfma_f32_16x16x32_bf16 v[56:59], v[242:245], v[180:183], v[56:59]
	v_mfma_f32_16x16x32_bf16 v[52:55], v[234:237], v[210:213], v[52:55]
	v_mfma_f32_16x16x32_bf16 v[48:51], v[242:245], v[210:213], v[48:51]
	v_mfma_f32_16x16x32_bf16 v[44:47], v[234:237], v[218:221], v[44:47]
	v_mfma_f32_16x16x32_bf16 v[40:43], v[242:245], v[218:221], v[40:43]
	v_mfma_f32_16x16x32_bf16 v[36:39], v[234:237], v[226:229], v[36:39]
	v_mfma_f32_16x16x32_bf16 v[32:35], v[242:245], v[226:229], v[32:35]
	s_mov_b32 m0, s62
	v_lshl_add_u64 v[246:247], v[250:251], 0, s[94:95]
	s_barrier
	ds_read_b128 v[176:179], v158 offset:49152
	ds_read_b128 v[180:183], v158 offset:50176
	ds_read_b128 v[184:187], v158 offset:51200
	ds_read_b128 v[210:213], v158 offset:52224
	ds_read_b128 v[214:217], v158 offset:53248
	ds_read_b128 v[218:221], v158 offset:54272
	ds_read_b128 v[222:225], v158 offset:55296
	ds_read_b128 v[226:229], v158 offset:56320
	global_load_lds_dwordx4 v[246:247], off
	v_lshl_add_u64 v[246:247], v[252:253], 0, s[94:95]
	s_mov_b32 m0, s63
	s_nop 0
	global_load_lds_dwordx4 v[246:247], off
	s_barrier
; #define PG8_STAGE(bufoff, gbase, voff) do { _Pragma("unroll") for (int _i = 0; _i < 2; ++_i) \
;         __builtin_amdgcn_global_load_lds((const unsigned*)((const char*)(gbase) + (voff)[_i]), (PG8_LAS unsigned*)(lds + (bufoff) + ldsw + _i * 8192), 16, 0, 0); } while (0)
; #define PG8_LDA(dst, b, h) do { _Pragma("unroll") for (int m = 0; m < 4; ++m) _Pragma("unroll") for (int k = 0; k < 2; ++k) dst[m][k] = *(const PG8_LAS bf16x8*)(lds + PG8_SA(b, h) + aoff + m * 2048 + k * 1024); } while (0)
; #define PG8_MMA(ai, bj, At, Bt) do { __builtin_amdgcn_s_setprio(1); _Pragma("unroll") for (int m = 0; m < 4; ++m) _Pragma("unroll") for (int n = 0; n < 2; ++n) _Pragma("unroll") for (int k = 0; k < 2; ++k) \
;         acc[ai][bj][m][n] = __builtin_amdgcn_mfma_f32_16x16x32_bf16(Bt[n][k], At[m][k], acc[ai][bj][m][n], 0, 0, 0); __builtin_amdgcn_s_setprio(0); } while (0)
; #define PG8_WAIT_V(n) asm volatile("s_waitcnt vmcnt(" #n ")" ::: "memory")
; #define PG8_WAIT_L(n) asm volatile("s_waitcnt lgkmcnt(" #n ")" ::: "memory")
; #define PG8_BAR __builtin_amdgcn_s_barrier()
; #define PG8_SCHED __builtin_amdgcn_sched_barrier(0)
; template <class Epi, class Sched>
; __device__ __forceinline__ void gemm_phase(PG8_LAS unsigned char* lds, const Gemm g, const Sched& S, const Epi& E) {
;     ...
;             PG8_LDA(At, 1, 1); PG8_STAGE(PG8_SA(1, 0), a3, voffA);
;             PG8_BAR; PG8_WAIT_L(0); PG8_MMA(1, 0, At, B0); PG8_BAR; PG8_SCHED;
;             PG8_STAGE(PG8_SB(1, 1), b3 + hstep, voffB);
;             PG8_WAIT_V(6); PG8_BAR; PG8_MMA(1, 1, At, B1); PG8_BAR;
;         }
;         if constexpr (!Epi::AFTER_DRAIN) { E(acc, cur, wr, wc, fr, fq); S.done(cur); }
;         if (!has_next) break;
; #pragma unroll
;         for (int a = 0; a < 2; ++a)
; #pragma unroll
;             for (int b = 0; b < 2; ++b)
; #pragma unroll
;                 for (int m = 0; m < 4; ++m)
; #pragma unroll
;                     for (int n = 0; n < 2; ++n) acc[a][b][m][n] = (f32x4){0.f, 0.f, 0.f, 0.f};
;         cur = nxt; cA = nA; cB = nB; ++ui;
	s_waitcnt lgkmcnt(0)
	v_mfma_f32_16x16x32_bf16 v[92:95], v[160:163], v[176:179], v[92:95]
	v_mfma_f32_16x16x32_bf16 v[88:91], v[168:171], v[176:179], v[88:91]
	v_mfma_f32_16x16x32_bf16 v[84:87], v[160:163], v[184:187], v[84:87]
	v_mfma_f32_16x16x32_bf16 v[80:83], v[168:171], v[184:187], v[80:83]
	v_mfma_f32_16x16x32_bf16 v[76:79], v[160:163], v[214:217], v[76:79]
	v_mfma_f32_16x16x32_bf16 v[72:75], v[168:171], v[214:217], v[72:75]
	v_mfma_f32_16x16x32_bf16 v[68:71], v[160:163], v[222:225], v[68:71]
	v_mfma_f32_16x16x32_bf16 v[64:67], v[168:171], v[222:225], v[64:67]
	v_mfma_f32_16x16x32_bf16 v[92:95], v[164:167], v[180:183], v[92:95]
	v_mfma_f32_16x16x32_bf16 v[88:91], v[172:175], v[180:183], v[88:91]
	v_mfma_f32_16x16x32_bf16 v[84:87], v[164:167], v[210:213], v[84:87]
	v_mfma_f32_16x16x32_bf16 v[80:83], v[172:175], v[210:213], v[80:83]
	v_mfma_f32_16x16x32_bf16 v[76:79], v[164:167], v[218:221], v[76:79]
	v_mfma_f32_16x16x32_bf16 v[72:75], v[172:175], v[218:221], v[72:75]
	v_mfma_f32_16x16x32_bf16 v[68:71], v[164:167], v[226:229], v[68:71]
	v_mfma_f32_16x16x32_bf16 v[64:67], v[172:175], v[226:229], v[64:67]
	s_barrier
	s_add_u32 s12, s22, 0xb0080
	s_addc_u32 s13, s23, 0
	s_add_i32 s22, s24, s41
	v_lshl_add_u64 v[160:161], s[12:13], 0, v[138:139]
	s_mov_b32 m0, s22
	s_nop 0
	global_load_lds_dwordx4 v[160:161], off
	v_lshl_add_u64 v[160:161], s[12:13], 0, v[132:133]
	s_add_i32 m0, s22, 0x2000
	s_nop 0
	global_load_lds_dwordx4 v[160:161], off
	s_waitcnt vmcnt(6)
	s_barrier
	v_mfma_f32_16x16x32_bf16 v[28:31], v[230:233], v[176:179], v[28:31]
	v_mfma_f32_16x16x32_bf16 v[24:27], v[238:241], v[176:179], v[24:27]
	v_mfma_f32_16x16x32_bf16 v[20:23], v[230:233], v[184:187], v[20:23]
	v_mfma_f32_16x16x32_bf16 v[16:19], v[238:241], v[184:187], v[16:19]
	v_mfma_f32_16x16x32_bf16 v[12:15], v[230:233], v[214:217], v[12:15]
	v_mfma_f32_16x16x32_bf16 v[8:11], v[238:241], v[214:217], v[8:11]
	v_mfma_f32_16x16x32_bf16 v[4:7], v[230:233], v[222:225], v[4:7]
	v_mfma_f32_16x16x32_bf16 v[0:3], v[238:241], v[222:225], v[0:3]
	v_mfma_f32_16x16x32_bf16 v[28:31], v[234:237], v[180:183], v[28:31]
	v_mfma_f32_16x16x32_bf16 v[24:27], v[242:245], v[180:183], v[24:27]
	v_mfma_f32_16x16x32_bf16 v[20:23], v[234:237], v[210:213], v[20:23]
	v_mfma_f32_16x16x32_bf16 v[16:19], v[242:245], v[210:213], v[16:19]
	v_mfma_f32_16x16x32_bf16 v[12:15], v[234:237], v[218:221], v[12:15]
	v_mfma_f32_16x16x32_bf16 v[8:11], v[242:245], v[218:221], v[8:11]
	v_mfma_f32_16x16x32_bf16 v[4:7], v[234:237], v[226:229], v[4:7]
	v_mfma_f32_16x16x32_bf16 v[0:3], v[242:245], v[226:229], v[0:3]
	s_add_i32 s83, s83, 2
	s_add_u32 s20, s20, 0x100
	s_addc_u32 s21, s21, 0
	s_cmp_gt_u32 s83, 41
	s_barrier
	s_cbranch_scc0 .LBB0_1074
	s_add_u32 s20, s68, 0xffffff00
	s_addc_u32 s21, s82, -1
	s_and_b64 vcc, exec, s[0:1]
	s_cbranch_vccnz .LBB0_1077
	v_mov_b32_e32 v0, 0
	s_mov_b32 s29, s65
	s_mov_b32 s16, s66
	s_mov_b64 s[8:9], s[18:19]
	s_mov_b32 s64, s67
	v_mov_b32_e32 v1, v0
	v_mov_b32_e32 v2, v0
	v_mov_b32_e32 v3, v0
	v_mov_b32_e32 v4, v0
	v_mov_b32_e32 v5, v0
	v_mov_b32_e32 v6, v0
	v_mov_b32_e32 v7, v0
	v_mov_b32_e32 v8, v0
	v_mov_b32_e32 v9, v0
	v_mov_b32_e32 v10, v0
	v_mov_b32_e32 v11, v0
	v_mov_b32_e32 v12, v0
	v_mov_b32_e32 v13, v0
	v_mov_b32_e32 v14, v0
	v_mov_b32_e32 v15, v0
	v_mov_b32_e32 v16, v0
	v_mov_b32_e32 v17, v0
	v_mov_b32_e32 v18, v0
	v_mov_b32_e32 v19, v0
	v_mov_b32_e32 v20, v0
	v_mov_b32_e32 v21, v0
	v_mov_b32_e32 v22, v0
	v_mov_b32_e32 v23, v0
	v_mov_b32_e32 v24, v0
	v_mov_b32_e32 v25, v0
	v_mov_b32_e32 v26, v0
	v_mov_b32_e32 v27, v0
	v_mov_b32_e32 v28, v0
	v_mov_b32_e32 v29, v0
	v_mov_b32_e32 v30, v0
	v_mov_b32_e32 v31, v0
	v_mov_b32_e32 v64, v0
	v_mov_b32_e32 v65, v0
	v_mov_b32_e32 v66, v0
	v_mov_b32_e32 v67, v0
	v_mov_b32_e32 v68, v0
	v_mov_b32_e32 v69, v0
	v_mov_b32_e32 v70, v0
	v_mov_b32_e32 v71, v0
	v_mov_b32_e32 v72, v0
	v_mov_b32_e32 v73, v0
	v_mov_b32_e32 v74, v0
	v_mov_b32_e32 v75, v0
	v_mov_b32_e32 v76, v0
	v_mov_b32_e32 v77, v0
	v_mov_b32_e32 v78, v0
	v_mov_b32_e32 v79, v0
	v_mov_b32_e32 v80, v0
	v_mov_b32_e32 v81, v0
	v_mov_b32_e32 v82, v0
	v_mov_b32_e32 v83, v0
	v_mov_b32_e32 v84, v0
	v_mov_b32_e32 v85, v0
	v_mov_b32_e32 v86, v0
	v_mov_b32_e32 v87, v0
	v_mov_b32_e32 v88, v0
	v_mov_b32_e32 v89, v0
	v_mov_b32_e32 v90, v0
	v_mov_b32_e32 v91, v0
	v_mov_b32_e32 v92, v0
	v_mov_b32_e32 v93, v0
	v_mov_b32_e32 v94, v0
	v_mov_b32_e32 v95, v0
	v_mov_b32_e32 v32, v0
	v_mov_b32_e32 v33, v0
	v_mov_b32_e32 v34, v0
	v_mov_b32_e32 v35, v0
	v_mov_b32_e32 v36, v0
	v_mov_b32_e32 v37, v0
	v_mov_b32_e32 v38, v0
	v_mov_b32_e32 v39, v0
	v_mov_b32_e32 v40, v0
	v_mov_b32_e32 v41, v0
	v_mov_b32_e32 v42, v0
	v_mov_b32_e32 v43, v0
	v_mov_b32_e32 v44, v0
	v_mov_b32_e32 v45, v0
	v_mov_b32_e32 v46, v0
	v_mov_b32_e32 v47, v0
	v_mov_b32_e32 v48, v0
	v_mov_b32_e32 v49, v0
	v_mov_b32_e32 v50, v0
	v_mov_b32_e32 v51, v0
	v_mov_b32_e32 v52, v0
	v_mov_b32_e32 v53, v0
	v_mov_b32_e32 v54, v0
	v_mov_b32_e32 v55, v0
	v_mov_b32_e32 v56, v0
	v_mov_b32_e32 v57, v0
	v_mov_b32_e32 v58, v0
	v_mov_b32_e32 v59, v0
	v_mov_b32_e32 v60, v0
	v_mov_b32_e32 v61, v0
	v_mov_b32_e32 v62, v0
	v_mov_b32_e32 v63, v0
	v_mov_b32_e32 v96, v0
	v_mov_b32_e32 v97, v0
	v_mov_b32_e32 v98, v0
	v_mov_b32_e32 v99, v0
	v_mov_b32_e32 v100, v0
	v_mov_b32_e32 v101, v0
	v_mov_b32_e32 v102, v0
	v_mov_b32_e32 v103, v0
	v_mov_b32_e32 v104, v0
	v_mov_b32_e32 v105, v0
	v_mov_b32_e32 v106, v0
	v_mov_b32_e32 v107, v0
	v_mov_b32_e32 v108, v0
	v_mov_b32_e32 v109, v0
	v_mov_b32_e32 v110, v0
	v_mov_b32_e32 v111, v0
	v_mov_b32_e32 v112, v0
	v_mov_b32_e32 v113, v0
	v_mov_b32_e32 v114, v0
	v_mov_b32_e32 v115, v0
	v_mov_b32_e32 v116, v0
	v_mov_b32_e32 v117, v0
	v_mov_b32_e32 v118, v0
	v_mov_b32_e32 v119, v0
	v_mov_b32_e32 v120, v0
	v_mov_b32_e32 v121, v0
	v_mov_b32_e32 v122, v0
	v_mov_b32_e32 v123, v0
	v_mov_b32_e32 v124, v0
	v_mov_b32_e32 v125, v0
	v_mov_b32_e32 v126, v0
	v_mov_b32_e32 v127, v0
	s_andn2_b64 vcc, exec, s[4:5]
	s_cbranch_vccnz .LBB0_1078
	s_branch .LBB0_1079

; #define PG8_STAGE(bufoff, gbase, voff) do { _Pragma("unroll") for (int _i = 0; _i < 2; ++_i) \
;         __builtin_amdgcn_global_load_lds((const unsigned*)((const char*)(gbase) + (voff)[_i]), (PG8_LAS unsigned*)(lds + (bufoff) + ldsw + _i * 8192), 16, 0, 0); } while (0)
; #define PG8_LDA(dst, b, h) do { _Pragma("unroll") for (int m = 0; m < 4; ++m) _Pragma("unroll") for (int k = 0; k < 2; ++k) dst[m][k] = *(const PG8_LAS bf16x8*)(lds + PG8_SA(b, h) + aoff + m * 2048 + k * 1024); } while (0)
; #define PG8_LDB(dst, b, h) do { _Pragma("unroll") for (int n = 0; n < 2; ++n) _Pragma("unroll") for (int k = 0; k < 2; ++k) dst[n][k] = *(const PG8_LAS bf16x8*)(lds + PG8_SB(b, h) + boff + n * 2048 + k * 1024); } while (0)
; #define PG8_WAIT_V(n) asm volatile("s_waitcnt vmcnt(" #n ")" ::: "memory")
; #define PG8_BAR __builtin_amdgcn_s_barrier()
; template <class Epi, class Sched>
; __device__ __forceinline__ void gemm_phase(PG8_LAS unsigned char* lds, const Gemm g, const Sched& S, const Epi& E) {
;     ...
;         for (int t = 0; t < nt; t += 2) {
;             const bool last = (t == nt - 2);
;             const char* a1 = cA + (size_t)(t + 1) * kstep;
;             const char* a2 = last ? nA : cA + (size_t)(t + 2) * kstep; const char* b2 = last ? nB : cB + (size_t)(t + 2) * kstep;
;             const char* a3 = a2 + kstep; const char* b3 = b2 + kstep;
;             if (last && has_next) S.a_ready(nxt);
;             PG8_LDB(B0, 0, 0); PG8_SCHED; PG8_LDA(At, 0, 0); PG8_STAGE(PG8_SA(1, 1), a1 + hstep, voffA);
;             PG8_WAIT_L(8); PG8_BAR; PG8_WAIT_L(0); PG8_MMA(0, 0, At, B0); PG8_BAR; PG8_SCHED;
;             PG8_LDB(B1, 0, 1); PG8_STAGE(PG8_SB(0, 0), b2, voffB);
;             PG8_BAR; PG8_WAIT_L(0); PG8_MMA(0, 1, At, B1); PG8_BAR;
;             PG8_LDA(At, 0, 1); PG8_STAGE(PG8_SA(0, 0), a2, voffA);
;             PG8_BAR; PG8_WAIT_L(0); PG8_MMA(1, 0, At, B0); PG8_BAR; PG8_SCHED;
;             PG8_STAGE(PG8_SB(0, 1), b2 + hstep, voffB);
;             PG8_WAIT_V(6); PG8_BAR; PG8_MMA(1, 1, At, B1); PG8_BAR;
;             PG8_LDB(B0, 1, 0); PG8_SCHED; PG8_LDA(At, 1, 0); PG8_STAGE(PG8_SA(0, 1), a2 + hstep, voffA);
;             PG8_WAIT_L(8); PG8_BAR; PG8_WAIT_L(0); PG8_MMA(0, 0, At, B0); PG8_BAR; PG8_SCHED;
;             PG8_LDB(B1, 1, 1); PG8_STAGE(PG8_SB(1, 0), b3, voffB);
;             PG8_BAR; PG8_WAIT_L(0); PG8_MMA(0, 1, At, B1); PG8_BAR;
.LBB0_1165:
	s_add_u32 s12, s16, s20
	s_addc_u32 s13, s17, s21
	s_add_u32 s12, s12, 0x100
	s_addc_u32 s13, s13, 0
	s_add_u32 s22, s65, s20
	s_addc_u32 s23, s66, s21
	s_add_i32 s68, s46, 0x100
	v_add_u32_e32 v159, s68, v156
	ds_read_b128 v[160:163], v159
	ds_read_b128 v[164:167], v159 offset:1024
	ds_read_b128 v[168:171], v159 offset:2048
	ds_read_b128 v[172:175], v159 offset:3072
	s_cmpk_eq_i32 s20, 0x1500
	s_cselect_b32 s25, s19, s13
	s_cselect_b32 s24, s18, s12
	s_cselect_b32 s23, s7, s23
	s_cselect_b32 s22, s6, s22
	v_lshl_add_u64 v[230:231], v[150:151], 0, s[20:21]
	s_add_i32 m0, s39, 0xc000
	ds_read_b128 v[176:179], v157
	ds_read_b128 v[180:183], v157 offset:1024
	ds_read_b128 v[184:187], v157 offset:2048
	ds_read_b128 v[210:213], v157 offset:3072
	ds_read_b128 v[214:217], v157 offset:4096
	ds_read_b128 v[218:221], v157 offset:5120
	ds_read_b128 v[222:225], v157 offset:6144
	ds_read_b128 v[226:229], v157 offset:7168
	global_load_lds_dwordx4 v[230:231], off
	v_lshl_add_u64 v[230:231], v[152:153], 0, s[20:21]
	s_add_i32 m0, s39, 0xe000
	s_nop 0
	global_load_lds_dwordx4 v[230:231], off
	s_waitcnt lgkmcnt(8)
	s_barrier
	s_waitcnt lgkmcnt(0)
	v_mfma_f32_16x16x32_bf16 v[124:127], v[160:163], v[176:179], v[124:127]
	v_mfma_f32_16x16x32_bf16 v[120:123], v[168:171], v[176:179], v[120:123]
	v_mfma_f32_16x16x32_bf16 v[116:119], v[160:163], v[184:187], v[116:119]
	v_mfma_f32_16x16x32_bf16 v[112:115], v[168:171], v[184:187], v[112:115]
	v_mfma_f32_16x16x32_bf16 v[108:111], v[160:163], v[214:217], v[108:111]
	v_mfma_f32_16x16x32_bf16 v[104:107], v[168:171], v[214:217], v[104:107]
	v_mfma_f32_16x16x32_bf16 v[100:103], v[160:163], v[222:225], v[100:103]
	v_mfma_f32_16x16x32_bf16 v[96:99], v[168:171], v[222:225], v[96:99]
	v_mfma_f32_16x16x32_bf16 v[124:127], v[164:167], v[180:183], v[124:127]
	v_mfma_f32_16x16x32_bf16 v[120:123], v[172:175], v[180:183], v[120:123]
	v_mfma_f32_16x16x32_bf16 v[116:119], v[164:167], v[210:213], v[116:119]
	v_mfma_f32_16x16x32_bf16 v[112:115], v[172:175], v[210:213], v[112:115]
	v_mfma_f32_16x16x32_bf16 v[108:111], v[164:167], v[218:221], v[108:111]
	v_mfma_f32_16x16x32_bf16 v[104:107], v[172:175], v[218:221], v[104:107]
	v_mfma_f32_16x16x32_bf16 v[100:103], v[164:167], v[226:229], v[100:103]
	v_mfma_f32_16x16x32_bf16 v[96:99], v[172:175], v[226:229], v[96:99]
	s_barrier
	s_add_i32 s69, s48, 0x100
	s_add_i32 s12, s68, s38
	v_add_u32_e32 v159, s69, v156
	v_lshl_add_u64 v[246:247], s[22:23], 0, v[138:139]
	s_mov_b32 m0, s12
	ds_read_b128 v[230:233], v159
	ds_read_b128 v[234:237], v159 offset:1024
	ds_read_b128 v[238:241], v159 offset:2048
	ds_read_b128 v[242:245], v159 offset:3072
	global_load_lds_dwordx4 v[246:247], off
	v_lshl_add_u64 v[248:249], s[22:23], 0, v[132:133]
	s_add_i32 m0, s12, 0x2000
	s_nop 0
	global_load_lds_dwordx4 v[248:249], off
	s_barrier
	s_waitcnt lgkmcnt(0)
	v_mfma_f32_16x16x32_bf16 v[60:63], v[230:233], v[176:179], v[60:63]
	v_mfma_f32_16x16x32_bf16 v[56:59], v[238:241], v[176:179], v[56:59]
	v_mfma_f32_16x16x32_bf16 v[52:55], v[230:233], v[184:187], v[52:55]
	v_mfma_f32_16x16x32_bf16 v[48:51], v[238:241], v[184:187], v[48:51]
	v_mfma_f32_16x16x32_bf16 v[44:47], v[230:233], v[214:217], v[44:47]
	v_mfma_f32_16x16x32_bf16 v[40:43], v[238:241], v[214:217], v[40:43]
	v_mfma_f32_16x16x32_bf16 v[36:39], v[230:233], v[222:225], v[36:39]
	v_mfma_f32_16x16x32_bf16 v[32:35], v[238:241], v[222:225], v[32:35]
	v_mfma_f32_16x16x32_bf16 v[60:63], v[234:237], v[180:183], v[60:63]
	v_mfma_f32_16x16x32_bf16 v[56:59], v[242:245], v[180:183], v[56:59]
	v_mfma_f32_16x16x32_bf16 v[52:55], v[234:237], v[210:213], v[52:55]
	v_mfma_f32_16x16x32_bf16 v[48:51], v[242:245], v[210:213], v[48:51]
	v_mfma_f32_16x16x32_bf16 v[44:47], v[234:237], v[218:221], v[44:47]
	v_mfma_f32_16x16x32_bf16 v[40:43], v[242:245], v[218:221], v[40:43]
	v_mfma_f32_16x16x32_bf16 v[36:39], v[234:237], v[226:229], v[36:39]
	v_mfma_f32_16x16x32_bf16 v[32:35], v[242:245], v[226:229], v[32:35]
	s_mov_b32 m0, s39
	v_lshl_add_u64 v[250:251], s[24:25], 0, v[128:129]
	s_barrier
	ds_read_b128 v[176:179], v157 offset:16384
	ds_read_b128 v[180:183], v157 offset:17408
	ds_read_b128 v[184:187], v157 offset:18432
	ds_read_b128 v[210:213], v157 offset:19456
	ds_read_b128 v[214:217], v157 offset:20480
	ds_read_b128 v[218:221], v157 offset:21504
	ds_read_b128 v[222:225], v157 offset:22528
	ds_read_b128 v[226:229], v157 offset:23552
	global_load_lds_dwordx4 v[250:251], off
	v_lshl_add_u64 v[252:253], s[24:25], 0, v[130:131]
	s_mov_b32 m0, s40
	s_nop 0
	global_load_lds_dwordx4 v[252:253], off
	s_barrier
	s_waitcnt lgkmcnt(0)
	v_mfma_f32_16x16x32_bf16 v[92:95], v[160:163], v[176:179], v[92:95]
	v_mfma_f32_16x16x32_bf16 v[88:91], v[168:171], v[176:179], v[88:91]
	v_mfma_f32_16x16x32_bf16 v[84:87], v[160:163], v[184:187], v[84:87]
	v_mfma_f32_16x16x32_bf16 v[80:83], v[168:171], v[184:187], v[80:83]
	v_mfma_f32_16x16x32_bf16 v[76:79], v[160:163], v[214:217], v[76:79]
	v_mfma_f32_16x16x32_bf16 v[72:75], v[168:171], v[214:217], v[72:75]
	v_mfma_f32_16x16x32_bf16 v[68:71], v[160:163], v[222:225], v[68:71]
	v_mfma_f32_16x16x32_bf16 v[64:67], v[168:171], v[222:225], v[64:67]
	v_mfma_f32_16x16x32_bf16 v[92:95], v[164:167], v[180:183], v[92:95]
	v_mfma_f32_16x16x32_bf16 v[88:91], v[172:175], v[180:183], v[88:91]
	v_mfma_f32_16x16x32_bf16 v[84:87], v[164:167], v[210:213], v[84:87]
	v_mfma_f32_16x16x32_bf16 v[80:83], v[172:175], v[210:213], v[80:83]
	v_mfma_f32_16x16x32_bf16 v[76:79], v[164:167], v[218:221], v[76:79]
	v_mfma_f32_16x16x32_bf16 v[72:75], v[172:175], v[218:221], v[72:75]
	v_mfma_f32_16x16x32_bf16 v[68:71], v[164:167], v[226:229], v[68:71]
	v_mfma_f32_16x16x32_bf16 v[64:67], v[172:175], v[226:229], v[64:67]
	s_barrier
; #define PG8_STAGE(bufoff, gbase, voff) do { _Pragma("unroll") for (int _i = 0; _i < 2; ++_i) \
;         __builtin_amdgcn_global_load_lds((const unsigned*)((const char*)(gbase) + (voff)[_i]), (PG8_LAS unsigned*)(lds + (bufoff) + ldsw + _i * 8192), 16, 0, 0); } while (0)
; #define PG8_LDA(dst, b, h) do { _Pragma("unroll") for (int m = 0; m < 4; ++m) _Pragma("unroll") for (int k = 0; k < 2; ++k) dst[m][k] = *(const PG8_LAS bf16x8*)(lds + PG8_SA(b, h) + aoff + m * 2048 + k * 1024); } while (0)
; #define PG8_LDB(dst, b, h) do { _Pragma("unroll") for (int n = 0; n < 2; ++n) _Pragma("unroll") for (int k = 0; k < 2; ++k) dst[n][k] = *(const PG8_LAS bf16x8*)(lds + PG8_SB(b, h) + boff + n * 2048 + k * 1024); } while (0)
; #define PG8_MMA(ai, bj, At, Bt) do { __builtin_amdgcn_s_setprio(1); _Pragma("unroll") for (int m = 0; m < 4; ++m) _Pragma("unroll") for (int n = 0; n < 2; ++n) _Pragma("unroll") for (int k = 0; k < 2; ++k) \
;         acc[ai][bj][m][n] = __builtin_amdgcn_mfma_f32_16x16x32_bf16(Bt[n][k], At[m][k], acc[ai][bj][m][n], 0, 0, 0); __builtin_amdgcn_s_setprio(0); } while (0)
; #define PG8_WAIT_V(n) asm volatile("s_waitcnt vmcnt(" #n ")" ::: "memory")
; #define PG8_WAIT_L(n) asm volatile("s_waitcnt lgkmcnt(" #n ")" ::: "memory")
; #define PG8_BAR __builtin_amdgcn_s_barrier()
; #define PG8_SCHED __builtin_amdgcn_sched_barrier(0)
; template <class Epi, class Sched>
; __device__ __forceinline__ void gemm_phase(PG8_LAS unsigned char* lds, const Gemm g, const Sched& S, const Epi& E) {
;     ...
;             PG8_STAGE(PG8_SB(0, 1), b2 + hstep, voffB);
;             PG8_WAIT_V(6); PG8_BAR; PG8_MMA(1, 1, At, B1); PG8_BAR;
;             PG8_LDB(B0, 1, 0); PG8_SCHED; PG8_LDA(At, 1, 0); PG8_STAGE(PG8_SA(0, 1), a2 + hstep, voffA);
;             PG8_WAIT_L(8); PG8_BAR; PG8_WAIT_L(0); PG8_MMA(0, 0, At, B0); PG8_BAR; PG8_SCHED;
;             PG8_LDB(B1, 1, 1); PG8_STAGE(PG8_SB(1, 0), b3, voffB);
;             PG8_BAR; PG8_WAIT_L(0); PG8_MMA(0, 1, At, B1); PG8_BAR;
;             PG8_LDA(At, 1, 1); PG8_STAGE(PG8_SA(1, 0), a3, voffA);
;             PG8_BAR; PG8_WAIT_L(0); PG8_MMA(1, 0, At, B0); PG8_BAR; PG8_SCHED;
	s_add_u32 s12, s22, 0xb0000
	s_addc_u32 s13, s23, 0
	s_add_i32 s68, s69, s38
	v_lshl_add_u64 v[160:161], s[12:13], 0, v[138:139]
	s_mov_b32 m0, s68
	s_nop 0
	global_load_lds_dwordx4 v[160:161], off
	v_lshl_add_u64 v[160:161], s[12:13], 0, v[132:133]
	s_add_i32 m0, s68, 0x2000
	s_nop 0
	global_load_lds_dwordx4 v[160:161], off
	s_waitcnt vmcnt(6)
	s_barrier
	v_mfma_f32_16x16x32_bf16 v[28:31], v[230:233], v[176:179], v[28:31]
	v_mfma_f32_16x16x32_bf16 v[24:27], v[238:241], v[176:179], v[24:27]
	v_mfma_f32_16x16x32_bf16 v[20:23], v[230:233], v[184:187], v[20:23]
	v_mfma_f32_16x16x32_bf16 v[16:19], v[238:241], v[184:187], v[16:19]
	v_mfma_f32_16x16x32_bf16 v[12:15], v[230:233], v[214:217], v[12:15]
	v_mfma_f32_16x16x32_bf16 v[8:11], v[238:241], v[214:217], v[8:11]
	v_mfma_f32_16x16x32_bf16 v[4:7], v[230:233], v[222:225], v[4:7]
	v_mfma_f32_16x16x32_bf16 v[0:3], v[238:241], v[222:225], v[0:3]
	v_mfma_f32_16x16x32_bf16 v[28:31], v[234:237], v[180:183], v[28:31]
	v_mfma_f32_16x16x32_bf16 v[24:27], v[242:245], v[180:183], v[24:27]
	v_mfma_f32_16x16x32_bf16 v[20:23], v[234:237], v[210:213], v[20:23]
	v_mfma_f32_16x16x32_bf16 v[16:19], v[242:245], v[210:213], v[16:19]
	v_mfma_f32_16x16x32_bf16 v[12:15], v[234:237], v[218:221], v[12:15]
	v_mfma_f32_16x16x32_bf16 v[8:11], v[242:245], v[218:221], v[8:11]
	v_mfma_f32_16x16x32_bf16 v[4:7], v[234:237], v[226:229], v[4:7]
	v_mfma_f32_16x16x32_bf16 v[0:3], v[242:245], v[226:229], v[0:3]
	s_add_i32 s68, s51, 0x100
	v_add_u32_e32 v159, s68, v156
	s_barrier
	ds_read_b128 v[160:163], v159
	ds_read_b128 v[164:167], v159 offset:1024
	ds_read_b128 v[168:171], v159 offset:2048
	ds_read_b128 v[172:175], v159 offset:3072
	s_add_u32 s12, s24, 0xb0000
	s_addc_u32 s13, s25, 0
	s_mov_b32 m0, s41
	v_lshl_add_u64 v[230:231], s[12:13], 0, v[128:129]
	ds_read_b128 v[176:179], v157 offset:32768
	ds_read_b128 v[180:183], v157 offset:33792
	ds_read_b128 v[184:187], v157 offset:34816
	ds_read_b128 v[210:213], v157 offset:35840
	ds_read_b128 v[214:217], v157 offset:36864
	ds_read_b128 v[218:221], v157 offset:37888
	ds_read_b128 v[222:225], v157 offset:38912
	ds_read_b128 v[226:229], v157 offset:39936
	global_load_lds_dwordx4 v[230:231], off
	v_lshl_add_u64 v[230:231], s[12:13], 0, v[130:131]
	s_mov_b32 m0, s58
	s_nop 0
	global_load_lds_dwordx4 v[230:231], off
	s_waitcnt lgkmcnt(8)
	s_barrier
	s_waitcnt lgkmcnt(0)
	v_mfma_f32_16x16x32_bf16 v[124:127], v[160:163], v[176:179], v[124:127]
	v_mfma_f32_16x16x32_bf16 v[120:123], v[168:171], v[176:179], v[120:123]
	v_mfma_f32_16x16x32_bf16 v[116:119], v[160:163], v[184:187], v[116:119]
	v_mfma_f32_16x16x32_bf16 v[112:115], v[168:171], v[184:187], v[112:115]
	v_mfma_f32_16x16x32_bf16 v[108:111], v[160:163], v[214:217], v[108:111]
	v_mfma_f32_16x16x32_bf16 v[104:107], v[168:171], v[214:217], v[104:107]
	v_mfma_f32_16x16x32_bf16 v[100:103], v[160:163], v[222:225], v[100:103]
	v_mfma_f32_16x16x32_bf16 v[96:99], v[168:171], v[222:225], v[96:99]
	v_mfma_f32_16x16x32_bf16 v[124:127], v[164:167], v[180:183], v[124:127]
	v_mfma_f32_16x16x32_bf16 v[120:123], v[172:175], v[180:183], v[120:123]
	v_mfma_f32_16x16x32_bf16 v[116:119], v[164:167], v[210:213], v[116:119]
	v_mfma_f32_16x16x32_bf16 v[112:115], v[172:175], v[210:213], v[112:115]
	v_mfma_f32_16x16x32_bf16 v[108:111], v[164:167], v[218:221], v[108:111]
	v_mfma_f32_16x16x32_bf16 v[104:107], v[172:175], v[218:221], v[104:107]
	v_mfma_f32_16x16x32_bf16 v[100:103], v[164:167], v[226:229], v[100:103]
	v_mfma_f32_16x16x32_bf16 v[96:99], v[172:175], v[226:229], v[96:99]
	s_barrier
	s_add_i32 s24, s55, 0x100
	s_add_i32 s12, s68, s38
	v_add_u32_e32 v159, s24, v156
	v_lshl_add_u64 v[246:247], v[246:247], 0, s[94:95]
	s_mov_b32 m0, s12
	ds_read_b128 v[230:233], v159
	ds_read_b128 v[234:237], v159 offset:1024
	ds_read_b128 v[238:241], v159 offset:2048
	ds_read_b128 v[242:245], v159 offset:3072
	global_load_lds_dwordx4 v[246:247], off
	v_lshl_add_u64 v[246:247], v[248:249], 0, s[94:95]
	s_add_i32 m0, s12, 0x2000
	s_nop 0
	global_load_lds_dwordx4 v[246:247], off
	s_barrier
	s_waitcnt lgkmcnt(0)
	v_mfma_f32_16x16x32_bf16 v[60:63], v[230:233], v[176:179], v[60:63]
	v_mfma_f32_16x16x32_bf16 v[56:59], v[238:241], v[176:179], v[56:59]
	v_mfma_f32_16x16x32_bf16 v[52:55], v[230:233], v[184:187], v[52:55]
	v_mfma_f32_16x16x32_bf16 v[48:51], v[238:241], v[184:187], v[48:51]
	v_mfma_f32_16x16x32_bf16 v[44:47], v[230:233], v[214:217], v[44:47]
	v_mfma_f32_16x16x32_bf16 v[40:43], v[238:241], v[214:217], v[40:43]
	v_mfma_f32_16x16x32_bf16 v[36:39], v[230:233], v[222:225], v[36:39]
	v_mfma_f32_16x16x32_bf16 v[32:35], v[238:241], v[222:225], v[32:35]
	v_mfma_f32_16x16x32_bf16 v[60:63], v[234:237], v[180:183], v[60:63]
	v_mfma_f32_16x16x32_bf16 v[56:59], v[242:245], v[180:183], v[56:59]
	v_mfma_f32_16x16x32_bf16 v[52:55], v[234:237], v[210:213], v[52:55]
	v_mfma_f32_16x16x32_bf16 v[48:51], v[242:245], v[210:213], v[48:51]
	v_mfma_f32_16x16x32_bf16 v[44:47], v[234:237], v[218:221], v[44:47]
	v_mfma_f32_16x16x32_bf16 v[40:43], v[242:245], v[218:221], v[40:43]
	v_mfma_f32_16x16x32_bf16 v[36:39], v[234:237], v[226:229], v[36:39]
	v_mfma_f32_16x16x32_bf16 v[32:35], v[242:245], v[226:229], v[32:35]
	s_mov_b32 m0, s59
	v_lshl_add_u64 v[246:247], v[250:251], 0, s[94:95]
	s_barrier
	ds_read_b128 v[176:179], v157 offset:49152
	ds_read_b128 v[180:183], v157 offset:50176
	ds_read_b128 v[184:187], v157 offset:51200
	ds_read_b128 v[210:213], v157 offset:52224
	ds_read_b128 v[214:217], v157 offset:53248
	ds_read_b128 v[218:221], v157 offset:54272
	ds_read_b128 v[222:225], v157 offset:55296
	ds_read_b128 v[226:229], v157 offset:56320
	global_load_lds_dwordx4 v[246:247], off
	v_lshl_add_u64 v[246:247], v[252:253], 0, s[94:95]
	s_mov_b32 m0, s60
	s_nop 0
	global_load_lds_dwordx4 v[246:247], off
	s_barrier
; #define PG8_STAGE(bufoff, gbase, voff) do { _Pragma("unroll") for (int _i = 0; _i < 2; ++_i) \
;         __builtin_amdgcn_global_load_lds((const unsigned*)((const char*)(gbase) + (voff)[_i]), (PG8_LAS unsigned*)(lds + (bufoff) + ldsw + _i * 8192), 16, 0, 0); } while (0)
; #define PG8_LDA(dst, b, h) do { _Pragma("unroll") for (int m = 0; m < 4; ++m) _Pragma("unroll") for (int k = 0; k < 2; ++k) dst[m][k] = *(const PG8_LAS bf16x8*)(lds + PG8_SA(b, h) + aoff + m * 2048 + k * 1024); } while (0)
; #define PG8_MMA(ai, bj, At, Bt) do { __builtin_amdgcn_s_setprio(1); _Pragma("unroll") for (int m = 0; m < 4; ++m) _Pragma("unroll") for (int n = 0; n < 2; ++n) _Pragma("unroll") for (int k = 0; k < 2; ++k) \
;         acc[ai][bj][m][n] = __builtin_amdgcn_mfma_f32_16x16x32_bf16(Bt[n][k], At[m][k], acc[ai][bj][m][n], 0, 0, 0); __builtin_amdgcn_s_setprio(0); } while (0)
; #define PG8_WAIT_V(n) asm volatile("s_waitcnt vmcnt(" #n ")" ::: "memory")
; #define PG8_WAIT_L(n) asm volatile("s_waitcnt lgkmcnt(" #n ")" ::: "memory")
; #define PG8_BAR __builtin_amdgcn_s_barrier()
; #define PG8_SCHED __builtin_amdgcn_sched_barrier(0)
; template <class Epi, class Sched>
; __device__ __forceinline__ void gemm_phase(PG8_LAS unsigned char* lds, const Gemm g, const Sched& S, const Epi& E) {
;     ...
;             PG8_LDA(At, 1, 1); PG8_STAGE(PG8_SA(1, 0), a3, voffA);
;             PG8_BAR; PG8_WAIT_L(0); PG8_MMA(1, 0, At, B0); PG8_BAR; PG8_SCHED;
;             PG8_STAGE(PG8_SB(1, 1), b3 + hstep, voffB);
;             PG8_WAIT_V(6); PG8_BAR; PG8_MMA(1, 1, At, B1); PG8_BAR;
;         }
;         if constexpr (!Epi::AFTER_DRAIN) { E(acc, cur, wr, wc, fr, fq); S.done(cur); }
;         if (!has_next) break;
; #pragma unroll
;         for (int a = 0; a < 2; ++a)
; #pragma unroll
;             for (int b = 0; b < 2; ++b)
; #pragma unroll
;                 for (int m = 0; m < 4; ++m)
; #pragma unroll
;                     for (int n = 0; n < 2; ++n) acc[a][b][m][n] = (f32x4){0.f, 0.f, 0.f, 0.f};
;         cur = nxt; cA = nA; cB = nB; ++ui;
	s_waitcnt lgkmcnt(0)
	v_mfma_f32_16x16x32_bf16 v[92:95], v[160:163], v[176:179], v[92:95]
	v_mfma_f32_16x16x32_bf16 v[88:91], v[168:171], v[176:179], v[88:91]
	v_mfma_f32_16x16x32_bf16 v[84:87], v[160:163], v[184:187], v[84:87]
	v_mfma_f32_16x16x32_bf16 v[80:83], v[168:171], v[184:187], v[80:83]
	v_mfma_f32_16x16x32_bf16 v[76:79], v[160:163], v[214:217], v[76:79]
	v_mfma_f32_16x16x32_bf16 v[72:75], v[168:171], v[214:217], v[72:75]
	v_mfma_f32_16x16x32_bf16 v[68:71], v[160:163], v[222:225], v[68:71]
	v_mfma_f32_16x16x32_bf16 v[64:67], v[168:171], v[222:225], v[64:67]
	v_mfma_f32_16x16x32_bf16 v[92:95], v[164:167], v[180:183], v[92:95]
	v_mfma_f32_16x16x32_bf16 v[88:91], v[172:175], v[180:183], v[88:91]
	v_mfma_f32_16x16x32_bf16 v[84:87], v[164:167], v[210:213], v[84:87]
	v_mfma_f32_16x16x32_bf16 v[80:83], v[172:175], v[210:213], v[80:83]
	v_mfma_f32_16x16x32_bf16 v[76:79], v[164:167], v[218:221], v[76:79]
	v_mfma_f32_16x16x32_bf16 v[72:75], v[172:175], v[218:221], v[72:75]
	v_mfma_f32_16x16x32_bf16 v[68:71], v[164:167], v[226:229], v[68:71]
	v_mfma_f32_16x16x32_bf16 v[64:67], v[172:175], v[226:229], v[64:67]
	s_barrier
	s_add_u32 s12, s22, 0xb0080
	s_addc_u32 s13, s23, 0
	s_add_i32 s22, s24, s38
	v_lshl_add_u64 v[160:161], s[12:13], 0, v[138:139]
	s_mov_b32 m0, s22
	s_nop 0
	global_load_lds_dwordx4 v[160:161], off
	v_lshl_add_u64 v[160:161], s[12:13], 0, v[132:133]
	s_add_i32 m0, s22, 0x2000
	s_nop 0
	global_load_lds_dwordx4 v[160:161], off
	s_waitcnt vmcnt(6)
	s_barrier
	v_mfma_f32_16x16x32_bf16 v[28:31], v[230:233], v[176:179], v[28:31]
	v_mfma_f32_16x16x32_bf16 v[24:27], v[238:241], v[176:179], v[24:27]
	v_mfma_f32_16x16x32_bf16 v[20:23], v[230:233], v[184:187], v[20:23]
	v_mfma_f32_16x16x32_bf16 v[16:19], v[238:241], v[184:187], v[16:19]
	v_mfma_f32_16x16x32_bf16 v[12:15], v[230:233], v[214:217], v[12:15]
	v_mfma_f32_16x16x32_bf16 v[8:11], v[238:241], v[214:217], v[8:11]
	v_mfma_f32_16x16x32_bf16 v[4:7], v[230:233], v[222:225], v[4:7]
	v_mfma_f32_16x16x32_bf16 v[0:3], v[238:241], v[222:225], v[0:3]
	v_mfma_f32_16x16x32_bf16 v[28:31], v[234:237], v[180:183], v[28:31]
	v_mfma_f32_16x16x32_bf16 v[24:27], v[242:245], v[180:183], v[24:27]
	v_mfma_f32_16x16x32_bf16 v[20:23], v[234:237], v[210:213], v[20:23]
	v_mfma_f32_16x16x32_bf16 v[16:19], v[242:245], v[210:213], v[16:19]
	v_mfma_f32_16x16x32_bf16 v[12:15], v[234:237], v[218:221], v[12:15]
	v_mfma_f32_16x16x32_bf16 v[8:11], v[242:245], v[218:221], v[8:11]
	v_mfma_f32_16x16x32_bf16 v[4:7], v[234:237], v[226:229], v[4:7]
	v_mfma_f32_16x16x32_bf16 v[0:3], v[242:245], v[226:229], v[0:3]
	s_add_i32 s67, s67, 2
	s_add_u32 s20, s20, 0x100
	s_addc_u32 s21, s21, 0
	s_cmp_gt_u32 s67, 41
	s_barrier
	s_cbranch_scc0 .LBB0_1165
	s_add_u32 s20, s65, 0xffffff00
	s_addc_u32 s21, s66, -1
	s_and_b64 vcc, exec, s[0:1]
	s_cbranch_vccnz .LBB0_1168
	v_mov_b32_e32 v0, 0
	s_mov_b32 s27, s62
	s_mov_b32 s8, s63
	s_mov_b64 s[16:17], s[18:19]
	s_mov_b32 s61, s64
	v_mov_b32_e32 v1, v0
	v_mov_b32_e32 v2, v0
	v_mov_b32_e32 v3, v0
	v_mov_b32_e32 v4, v0
	v_mov_b32_e32 v5, v0
	v_mov_b32_e32 v6, v0
	v_mov_b32_e32 v7, v0
	v_mov_b32_e32 v8, v0
	v_mov_b32_e32 v9, v0
	v_mov_b32_e32 v10, v0
	v_mov_b32_e32 v11, v0
	v_mov_b32_e32 v12, v0
	v_mov_b32_e32 v13, v0
	v_mov_b32_e32 v14, v0
	v_mov_b32_e32 v15, v0
	v_mov_b32_e32 v16, v0
	v_mov_b32_e32 v17, v0
	v_mov_b32_e32 v18, v0
	v_mov_b32_e32 v19, v0
	v_mov_b32_e32 v20, v0
	v_mov_b32_e32 v21, v0
	v_mov_b32_e32 v22, v0
	v_mov_b32_e32 v23, v0
	v_mov_b32_e32 v24, v0
	v_mov_b32_e32 v25, v0
	v_mov_b32_e32 v26, v0
	v_mov_b32_e32 v27, v0
	v_mov_b32_e32 v28, v0
	v_mov_b32_e32 v29, v0
	v_mov_b32_e32 v30, v0
	v_mov_b32_e32 v31, v0
	v_mov_b32_e32 v64, v0
	v_mov_b32_e32 v65, v0
	v_mov_b32_e32 v66, v0
	v_mov_b32_e32 v67, v0
	v_mov_b32_e32 v68, v0
	v_mov_b32_e32 v69, v0
	v_mov_b32_e32 v70, v0
	v_mov_b32_e32 v71, v0
	v_mov_b32_e32 v72, v0
	v_mov_b32_e32 v73, v0
	v_mov_b32_e32 v74, v0
	v_mov_b32_e32 v75, v0
	v_mov_b32_e32 v76, v0
	v_mov_b32_e32 v77, v0
	v_mov_b32_e32 v78, v0
	v_mov_b32_e32 v79, v0
	v_mov_b32_e32 v80, v0
	v_mov_b32_e32 v81, v0
	v_mov_b32_e32 v82, v0
	v_mov_b32_e32 v83, v0
	v_mov_b32_e32 v84, v0
	v_mov_b32_e32 v85, v0
	v_mov_b32_e32 v86, v0
	v_mov_b32_e32 v87, v0
	v_mov_b32_e32 v88, v0
	v_mov_b32_e32 v89, v0
	v_mov_b32_e32 v90, v0
	v_mov_b32_e32 v91, v0
	v_mov_b32_e32 v92, v0
	v_mov_b32_e32 v93, v0
	v_mov_b32_e32 v94, v0
	v_mov_b32_e32 v95, v0
	v_mov_b32_e32 v32, v0
	v_mov_b32_e32 v33, v0
	v_mov_b32_e32 v34, v0
	v_mov_b32_e32 v35, v0
	v_mov_b32_e32 v36, v0
	v_mov_b32_e32 v37, v0
	v_mov_b32_e32 v38, v0
	v_mov_b32_e32 v39, v0
	v_mov_b32_e32 v40, v0
	v_mov_b32_e32 v41, v0
	v_mov_b32_e32 v42, v0
	v_mov_b32_e32 v43, v0
	v_mov_b32_e32 v44, v0
	v_mov_b32_e32 v45, v0
	v_mov_b32_e32 v46, v0
	v_mov_b32_e32 v47, v0
	v_mov_b32_e32 v48, v0
	v_mov_b32_e32 v49, v0
	v_mov_b32_e32 v50, v0
	v_mov_b32_e32 v51, v0
	v_mov_b32_e32 v52, v0
	v_mov_b32_e32 v53, v0
	v_mov_b32_e32 v54, v0
	v_mov_b32_e32 v55, v0
	v_mov_b32_e32 v56, v0
	v_mov_b32_e32 v57, v0
	v_mov_b32_e32 v58, v0
	v_mov_b32_e32 v59, v0
	v_mov_b32_e32 v60, v0
	v_mov_b32_e32 v61, v0
	v_mov_b32_e32 v62, v0
	v_mov_b32_e32 v63, v0
	v_mov_b32_e32 v96, v0
	v_mov_b32_e32 v97, v0
	v_mov_b32_e32 v98, v0
	v_mov_b32_e32 v99, v0
	v_mov_b32_e32 v100, v0
	v_mov_b32_e32 v101, v0
	v_mov_b32_e32 v102, v0
	v_mov_b32_e32 v103, v0
	v_mov_b32_e32 v104, v0
	v_mov_b32_e32 v105, v0
	v_mov_b32_e32 v106, v0
	v_mov_b32_e32 v107, v0
	v_mov_b32_e32 v108, v0
	v_mov_b32_e32 v109, v0
	v_mov_b32_e32 v110, v0
	v_mov_b32_e32 v111, v0
	v_mov_b32_e32 v112, v0
	v_mov_b32_e32 v113, v0
	v_mov_b32_e32 v114, v0
	v_mov_b32_e32 v115, v0
	v_mov_b32_e32 v116, v0
	v_mov_b32_e32 v117, v0
	v_mov_b32_e32 v118, v0
	v_mov_b32_e32 v119, v0
	v_mov_b32_e32 v120, v0
	v_mov_b32_e32 v121, v0
	v_mov_b32_e32 v122, v0
	v_mov_b32_e32 v123, v0
	v_mov_b32_e32 v124, v0
	v_mov_b32_e32 v125, v0
	v_mov_b32_e32 v126, v0
	v_mov_b32_e32 v127, v0
	s_andn2_b64 vcc, exec, s[4:5]
	s_cbranch_vccnz .LBB0_1169
	s_branch .LBB0_1170
